# weight conversion code: v_mov pairs feeding v_pk_mul_f32 gain multiplies folded into two scalar v_mul_f32 reading the loaded registers directly (377 sites, 739 moves removed), bit-identical
# baseline (speedup 1.0000x reference)
.LBB0_15:
	s_waitcnt vmcnt(14)
	s_waitcnt vmcnt(12)
	v_mul_f32_e32 v40, v92, v42
	v_mul_f32_e32 v41, v93, v46
	v_lshlrev_b32_e32 v84, 11, v86
	v_bfe_u32 v42, v40, 16, 1
	v_add3_u32 v42, v40, v42, s50
	v_bfe_u32 v40, v41, 16, 1
	v_add3_u32 v46, v41, v40, s50
	s_waitcnt vmcnt(10)
	s_waitcnt vmcnt(8)
	v_mul_f32_e32 v40, v80, v50
	v_mul_f32_e32 v41, v81, v58
	s_lshl_b32 s8, s8, 1
	v_bfe_u32 v50, v40, 16, 1
	v_add3_u32 v50, v40, v50, s50
	v_bfe_u32 v40, v41, 16, 1
	v_add3_u32 v58, v41, v40, s50
	v_mul_f32_e32 v40, v74, v54
	v_mul_f32_e32 v41, v75, v62
	v_mov_b32_e32 v94, 1.0
	v_bfe_u32 v54, v41, 16, 1
	v_add3_u32 v54, v41, v54, s50
	v_bfe_u32 v41, v40, 16, 1
	v_add3_u32 v62, v40, v41, s50
	v_mul_f32_e32 v40, v78, v66
	v_mul_f32_e32 v41, v79, v70
	v_lshrrev_b32_e32 v54, 16, v54
	v_bfe_u32 v66, v41, 16, 1
	v_add3_u32 v41, v41, v66, s50
	v_bfe_u32 v66, v40, 16, 1
	v_add3_u32 v40, v40, v66, s50
	v_lshrrev_b32_e32 v41, 16, v41
	v_and_or_b32 v103, v46, s51, v41
	v_lshrrev_b32_e32 v40, 16, v40
	v_mov_b32_e32 v46, v43
	v_and_or_b32 v102, v42, s51, v40
	v_pk_mul_f32 v[42:43], v[46:47], v[92:93]
	v_and_or_b32 v105, v58, s51, v54
	v_bfe_u32 v46, v42, 16, 1
	v_add3_u32 v46, v42, v46, s50
	v_bfe_u32 v42, v43, 16, 1
	v_mov_b32_e32 v58, v51
	v_lshrrev_b32_e32 v62, 16, v62
	v_add3_u32 v47, v43, v42, s50
	v_pk_mul_f32 v[42:43], v[58:59], v[80:81]
	v_and_or_b32 v104, v50, s51, v62
	v_bfe_u32 v50, v42, 16, 1
	v_add3_u32 v50, v42, v50, s50
	v_bfe_u32 v42, v43, 16, 1
	v_mov_b32_e32 v62, v55
	s_waitcnt lgkmcnt(0)
	v_lshl_add_u64 v[40:41], s[24:25], 0, v[84:85]
	v_add3_u32 v51, v43, v42, s50
	v_pk_mul_f32 v[42:43], v[62:63], v[74:75]
	v_lshl_add_u64 v[40:41], v[40:41], 0, s[8:9]
	v_lshlrev_b32_e32 v84, 1, v82
	v_bfe_u32 v54, v43, 16, 1
	v_lshl_add_u64 v[86:87], v[40:41], 0, v[84:85]
	v_add3_u32 v54, v43, v54, s50
	v_bfe_u32 v43, v42, 16, 1
	v_add_co_u32_e32 v40, vcc, s52, v86
	v_add3_u32 v55, v42, v43, s50
	s_nop 0
	v_addc_co_u32_e32 v41, vcc, 0, v87, vcc
	v_lshrrev_b32_e32 v55, 16, v55
	v_lshrrev_b32_e32 v54, 16, v54
	global_store_dwordx4 v[40:41], v[102:105], off offset:-4096
	v_mov_b32_e32 v70, v67
	v_pk_mul_f32 v[42:43], v[70:71], v[78:79]
	v_and_or_b32 v105, v51, s51, v54
	v_and_or_b32 v104, v50, s51, v55
	v_mul_f32_e32 v50, v92, v44
	v_mul_f32_e32 v51, v93, v48
	v_bfe_u32 v58, v43, 16, 1
	v_bfe_u32 v44, v50, 16, 1
	v_bfe_u32 v48, v51, 16, 1
	v_add3_u32 v44, v50, v44, s50
	v_add3_u32 v48, v51, v48, s50
	v_mul_f32_e32 v50, v80, v52
	v_mul_f32_e32 v51, v81, v60
	v_add3_u32 v43, v43, v58, s50
	v_bfe_u32 v52, v50, 16, 1
	v_bfe_u32 v58, v42, 16, 1
	v_add3_u32 v52, v50, v52, s50
	v_bfe_u32 v50, v51, 16, 1
	v_add3_u32 v42, v42, v58, s50
	v_add3_u32 v54, v51, v50, s50
	v_lshrrev_b32_e32 v43, 16, v43
	v_lshrrev_b32_e32 v42, 16, v42
	v_mul_f32_e32 v50, v74, v56
	v_mul_f32_e32 v51, v75, v64
	v_and_or_b32 v103, v47, s51, v43
	v_and_or_b32 v102, v46, s51, v42
	v_bfe_u32 v55, v51, 16, 1
	v_mul_f32_e32 v42, v78, v68
	v_mul_f32_e32 v43, v79, v72
	v_add3_u32 v51, v51, v55, s50
	v_bfe_u32 v55, v50, 16, 1
	v_add3_u32 v50, v50, v55, s50
	v_bfe_u32 v55, v43, 16, 1
	v_add3_u32 v43, v43, v55, s50
	v_bfe_u32 v55, v42, 16, 1
	v_add3_u32 v42, v42, v55, s50
	v_lshrrev_b32_e32 v43, 16, v43
	v_and_or_b32 v67, v48, s51, v43
	v_lshrrev_b32_e32 v42, 16, v42
	v_mov_b32_e32 v48, v45
	v_mov_b32_e32 v60, v53
	v_mov_b32_e32 v72, v69
	v_lshrrev_b32_e32 v50, 16, v50
	v_lshrrev_b32_e32 v51, 16, v51
	v_and_or_b32 v66, v44, s51, v42
	v_pk_mul_f32 v[42:43], v[48:49], v[92:93]
	v_mov_b32_e32 v64, v57
	v_pk_mul_f32 v[48:49], v[60:61], v[80:81]
	v_pk_mul_f32 v[46:47], v[72:73], v[78:79]
	v_and_or_b32 v69, v54, s51, v51
	v_and_or_b32 v68, v52, s51, v50
	v_pk_mul_f32 v[44:45], v[64:65], v[74:75]
	v_cvt_pk_bf16_f32 v45, v45, v49
	v_cvt_pk_bf16_f32 v44, v44, v48
	v_cvt_pk_bf16_f32 v43, v47, v43
	v_cvt_pk_bf16_f32 v42, v46, v42
	global_store_dwordx4 v[40:41], v[42:45], off offset:2048
	s_waitcnt vmcnt(5)
	s_waitcnt vmcnt(3)
	v_mul_f32_e32 v42, v2, v10
	v_mul_f32_e32 v43, v3, v18
	v_mul_f32_e32 v46, v38, v26
	v_mul_f32_e32 v47, v39, v34
	s_waitcnt vmcnt(2)
	v_mul_f32_e32 v44, v76, v6
	v_mul_f32_e32 v45, v77, v14
	v_mul_f32_e32 v48, v4, v22
	v_mul_f32_e32 v49, v5, v30
	v_bfe_u32 v22, v42, 16, 1
	v_bfe_u32 v18, v44, 16, 1
	v_add3_u32 v22, v42, v22, s50
	v_add3_u32 v18, v44, v18, s50
	v_lshrrev_b32_e32 v22, 16, v22
	v_cvt_pk_bf16_f32 v44, v46, v48
	v_cvt_pk_bf16_f32 v43, v43, v45
	v_and_or_b32 v42, v18, s51, v22
	v_mov_b32_e32 v18, v11
	v_mov_b32_e32 v14, v7
	v_mov_b32_e32 v30, v23
	v_cvt_pk_bf16_f32 v45, v47, v49
	v_pk_mul_f32 v[10:11], v[18:19], v[2:3]
	v_pk_mul_f32 v[6:7], v[14:15], v[76:77]
	v_mov_b32_e32 v34, v27
	v_pk_mul_f32 v[18:19], v[30:31], v[4:5]
	v_pk_mul_f32 v[14:15], v[34:35], v[38:39]
	v_lshl_add_u64 v[86:87], v[86:87], 0, s[6:7]
	global_store_dwordx4 v[86:87], v[42:45], off offset:32
	global_store_dwordx4 v[86:87], v[102:105], off offset:2048
	global_store_dwordx4 v[40:41], v[66:69], off
	v_cvt_pk_bf16_f32 v45, v15, v19
	v_cvt_pk_bf16_f32 v44, v14, v18
	v_cvt_pk_bf16_f32 v43, v11, v7
	v_cvt_pk_bf16_f32 v42, v10, v6
	v_mul_f32_e32 v10, v76, v8
	v_mul_f32_e32 v11, v77, v16
	v_mul_f32_e32 v18, v4, v24
	v_mul_f32_e32 v19, v5, v32
	v_mul_f32_e32 v6, v2, v12
	v_mul_f32_e32 v7, v3, v20
	v_bfe_u32 v12, v18, 16, 1
	v_bfe_u32 v16, v11, 16, 1
	v_mul_f32_e32 v14, v38, v28
	v_mul_f32_e32 v15, v39, v36
	v_bfe_u32 v8, v19, 16, 1
	v_bfe_u32 v20, v10, 16, 1
	v_add3_u32 v11, v11, v16, s50
	v_add3_u32 v12, v18, v12, s50
	v_bfe_u32 v16, v6, 16, 1
	v_bfe_u32 v18, v7, 16, 1
	v_add3_u32 v10, v10, v20, s50
	v_add3_u32 v8, v19, v8, s50
	v_bfe_u32 v19, v14, 16, 1
	v_bfe_u32 v20, v15, 16, 1
	v_add3_u32 v7, v7, v18, s50
	v_add3_u32 v6, v6, v16, s50
	v_add3_u32 v15, v15, v20, s50
	v_add3_u32 v14, v14, v19, s50
	v_lshrrev_b32_e32 v6, 16, v6
	v_lshrrev_b32_e32 v7, 16, v7
	v_mov_b32_e32 v16, v9
	v_mov_b32_e32 v32, v25
	global_store_dwordx4 v[86:87], v[42:45], off offset:2080
	v_lshrrev_b32_e32 v14, 16, v14
	v_lshrrev_b32_e32 v15, 16, v15
	v_and_or_b32 v43, v11, s51, v7
	v_and_or_b32 v42, v10, s51, v6
	v_mov_b32_e32 v20, v13
	v_pk_mul_f32 v[6:7], v[16:17], v[76:77]
	v_mov_b32_e32 v36, v29
	v_pk_mul_f32 v[4:5], v[32:33], v[4:5]
	v_and_or_b32 v45, v8, s51, v15
	v_and_or_b32 v44, v12, s51, v14
	v_pk_mul_f32 v[2:3], v[20:21], v[2:3]
	v_pk_mul_f32 v[8:9], v[36:37], v[38:39]
	v_cvt_pk_bf16_f32 v5, v9, v5
	v_cvt_pk_bf16_f32 v4, v8, v4
	v_cvt_pk_bf16_f32 v3, v3, v7
	v_cvt_pk_bf16_f32 v2, v2, v6
	global_store_dwordx4 v[40:41], v[2:5], off offset:2080
	global_store_dwordx4 v[40:41], v[42:45], off offset:32
	v_mov_b32_e32 v74, 1.0
	v_or_b32_e32 v2, 32, v97
	v_add_co_u32_e32 v4, vcc, s53, v88
	v_mad_u64_u32 v[2:3], s[24:25], v2, s44, v[90:91]
	s_nop 0
	v_addc_co_u32_e32 v5, vcc, 0, v89, vcc
	global_load_dwordx4 v[46:49], v[2:3], off nt
	global_load_dwordx4 v[42:45], v[4:5], off nt
	v_add_co_u32_e32 v2, vcc, s54, v88
	v_mov_b32_e32 v75, 1.0
	s_nop 0
	v_addc_co_u32_e32 v3, vcc, 0, v89, vcc
	v_add_co_u32_e32 v4, vcc, s55, v88
	v_mov_b32_e32 v95, 1.0
	s_nop 0
	v_addc_co_u32_e32 v5, vcc, 0, v89, vcc
	global_load_dwordx4 v[54:57], v[2:3], off nt
	global_load_dwordx4 v[50:53], v[4:5], off nt
	v_add_co_u32_e32 v2, vcc, s56, v88
	v_mov_b32_e32 v78, 1.0
	s_nop 0
	v_addc_co_u32_e32 v3, vcc, 0, v89, vcc
	v_add_co_u32_e32 v4, vcc, 0x6f000, v88
	v_mov_b32_e32 v92, 1.0
	s_nop 0
	v_addc_co_u32_e32 v5, vcc, 0, v89, vcc
	global_load_dwordx4 v[62:65], v[2:3], off nt
	global_load_dwordx4 v[58:61], v[4:5], off nt
	v_add_co_u32_e32 v2, vcc, 0x72000, v88
	v_mov_b32_e32 v79, 1.0
	s_nop 0
	v_addc_co_u32_e32 v3, vcc, 0, v89, vcc
	v_add_co_u32_e32 v4, vcc, 0x75000, v88
	v_mov_b32_e32 v93, 1.0
	s_nop 0
	v_addc_co_u32_e32 v5, vcc, 0, v89, vcc
	global_load_dwordx4 v[70:73], v[2:3], off nt
	global_load_dwordx4 v[66:69], v[4:5], off nt
	v_mov_b32_e32 v2, 1.0
	s_and_b64 vcc, exec, s[4:5]
	s_cbranch_vccnz .LBB0_17
	global_load_dwordx4 v[74:77], v96, s[10:11] offset:128
	global_load_dwordx4 v[78:81], v96, s[10:11] offset:144
	s_waitcnt vmcnt(1)
	v_mov_b32_e32 v94, v75
	v_mov_b32_e32 v75, v76
	v_mov_b32_e32 v95, v77
	s_waitcnt vmcnt(0)
	v_mov_b32_e32 v92, v79
	v_mov_b32_e32 v79, v80
	v_mov_b32_e32 v93, v81

.LBB0_19:
	s_waitcnt vmcnt(14)
	s_waitcnt vmcnt(12)
	v_mul_f32_e32 v40, v94, v42
	v_mul_f32_e32 v41, v95, v50
	s_mov_b64 s[4:5], 0
	v_bfe_u32 v42, v40, 16, 1
	v_add3_u32 v42, v40, v42, s50
	v_bfe_u32 v40, v41, 16, 1
	v_add3_u32 v50, v41, v40, s50
	s_waitcnt vmcnt(10)
	s_waitcnt vmcnt(8)
	v_mul_f32_e32 v40, v92, v58
	v_mul_f32_e32 v41, v93, v66
	s_nop 0
	v_bfe_u32 v58, v40, 16, 1
	v_add3_u32 v58, v40, v58, s50
	v_bfe_u32 v40, v41, 16, 1
	v_add3_u32 v66, v41, v40, s50
	v_mul_f32_e32 v40, v78, v62
	v_mul_f32_e32 v41, v79, v70
	s_nop 0
	v_bfe_u32 v62, v41, 16, 1
	v_add3_u32 v62, v41, v62, s50
	v_bfe_u32 v41, v40, 16, 1
	v_add3_u32 v70, v40, v41, s50
	v_mul_f32_e32 v40, v74, v46
	v_mul_f32_e32 v41, v75, v54
	v_lshrrev_b32_e32 v54, 16, v62
	v_bfe_u32 v46, v41, 16, 1
	v_add3_u32 v41, v41, v46, s50
	v_bfe_u32 v46, v40, 16, 1
	v_add3_u32 v40, v40, v46, s50
	v_lshrrev_b32_e32 v41, 16, v41
	v_and_or_b32 v89, v50, s51, v41
	v_lshrrev_b32_e32 v40, 16, v40
	v_mov_b32_e32 v50, v43
	v_and_or_b32 v88, v42, s51, v40
	v_pk_mul_f32 v[40:41], v[50:51], v[94:95]
	v_lshrrev_b32_e32 v46, 16, v70
	v_bfe_u32 v42, v40, 16, 1
	v_and_or_b32 v91, v66, s51, v54
	v_and_or_b32 v90, v58, s51, v46
	v_add3_u32 v46, v40, v42, s50
	v_bfe_u32 v40, v41, 16, 1
	v_mov_b32_e32 v66, v59
	v_add3_u32 v50, v41, v40, s50
	v_pk_mul_f32 v[40:41], v[66:67], v[92:93]
	v_mov_b32_e32 v70, v63
	v_bfe_u32 v42, v40, 16, 1
	v_add3_u32 v42, v40, v42, s50
	v_bfe_u32 v40, v41, 16, 1
	v_add3_u32 v43, v41, v40, s50
	v_pk_mul_f32 v[40:41], v[70:71], v[78:79]
	v_mov_b32_e32 v54, v47
	v_bfe_u32 v51, v41, 16, 1
	v_add3_u32 v51, v41, v51, s50
	v_bfe_u32 v41, v40, 16, 1
	v_add3_u32 v58, v40, v41, s50
	v_pk_mul_f32 v[40:41], v[54:55], v[74:75]
	v_lshrrev_b32_e32 v51, 16, v51
	v_bfe_u32 v47, v41, 16, 1
	v_add3_u32 v41, v41, v47, s50
	v_bfe_u32 v47, v40, 16, 1
	v_add3_u32 v40, v40, v47, s50
	v_lshrrev_b32_e32 v47, 16, v58
	v_lshrrev_b32_e32 v41, 16, v41
	v_lshrrev_b32_e32 v40, 16, v40
	v_and_or_b32 v43, v43, s51, v51
	v_and_or_b32 v42, v42, s51, v47
	v_and_or_b32 v41, v50, s51, v41
	v_and_or_b32 v40, v46, s51, v40
	global_store_dwordx4 v[86:87], v[40:43], off offset:2112
	global_store_dwordx4 v[86:87], v[88:91], off offset:64
	s_nop 0
	v_mul_f32_e32 v40, v94, v44
	v_mul_f32_e32 v41, v95, v52
	v_mov_b32_e32 v52, v45
	v_bfe_u32 v42, v40, 16, 1
	v_add3_u32 v44, v40, v42, s50
	v_bfe_u32 v40, v41, 16, 1
	v_add3_u32 v46, v41, v40, s50
	v_mul_f32_e32 v40, v92, v60
	v_mul_f32_e32 v41, v93, v68
	v_mov_b32_e32 v68, v61
	v_bfe_u32 v42, v40, 16, 1
	v_add3_u32 v42, v40, v42, s50
	v_bfe_u32 v40, v41, 16, 1
	v_add3_u32 v43, v41, v40, s50
	v_mul_f32_e32 v40, v78, v64
	v_mul_f32_e32 v41, v79, v72
	v_mov_b32_e32 v72, v65
	v_bfe_u32 v47, v41, 16, 1
	v_add3_u32 v47, v41, v47, s50
	v_bfe_u32 v41, v40, 16, 1
	v_add3_u32 v50, v40, v41, s50
	v_mul_f32_e32 v40, v74, v48
	v_mul_f32_e32 v41, v75, v56
	v_lshrrev_b32_e32 v47, 16, v47
	v_bfe_u32 v48, v41, 16, 1
	v_add3_u32 v41, v41, v48, s50
	v_bfe_u32 v48, v40, 16, 1
	v_add3_u32 v40, v40, v48, s50
	v_lshrrev_b32_e32 v41, 16, v41
	v_lshrrev_b32_e32 v48, 16, v50
	v_and_or_b32 v41, v46, s51, v41
	v_lshrrev_b32_e32 v40, 16, v40
	v_add_co_u32_e32 v46, vcc, s57, v86
	v_and_or_b32 v43, v43, s51, v47
	v_and_or_b32 v42, v42, s51, v48
	v_and_or_b32 v40, v44, s51, v40
	v_addc_co_u32_e32 v47, vcc, 0, v87, vcc
	global_store_dwordx4 v[46:47], v[40:43], off offset:64
	v_mov_b32_e32 v56, v49
	v_pk_mul_f32 v[48:49], v[68:69], v[92:93]
	v_pk_mul_f32 v[42:43], v[52:53], v[94:95]
	v_pk_mul_f32 v[40:41], v[56:57], v[74:75]
	v_pk_mul_f32 v[44:45], v[72:73], v[78:79]
	v_bfe_u32 v50, v49, 16, 1
	v_bfe_u32 v51, v48, 16, 1
	v_bfe_u32 v52, v43, 16, 1
	v_bfe_u32 v53, v42, 16, 1
	v_add3_u32 v53, v42, v53, s50
	v_add3_u32 v52, v43, v52, s50
	v_add3_u32 v42, v48, v51, s50
	v_add3_u32 v43, v49, v50, s50
	v_bfe_u32 v48, v40, 16, 1
	v_bfe_u32 v49, v41, 16, 1
	v_bfe_u32 v50, v44, 16, 1
	v_bfe_u32 v51, v45, 16, 1
	v_add3_u32 v45, v45, v51, s50
	v_add3_u32 v44, v44, v50, s50
	v_add3_u32 v41, v41, v49, s50
	v_add3_u32 v40, v40, v48, s50
	v_lshrrev_b32_e32 v40, 16, v40
	v_lshrrev_b32_e32 v41, 16, v41
	v_lshrrev_b32_e32 v44, 16, v44
	v_lshrrev_b32_e32 v45, 16, v45
	v_and_or_b32 v43, v43, s51, v45
	v_and_or_b32 v42, v42, s51, v44
	v_and_or_b32 v41, v52, s51, v41
	v_and_or_b32 v40, v53, s51, v40
	global_store_dwordx4 v[46:47], v[40:43], off offset:2112
	s_waitcnt vmcnt(7)
	s_waitcnt vmcnt(5)
	v_mul_f32_e32 v40, v2, v10
	v_mul_f32_e32 v41, v3, v18
	v_mul_f32_e32 v44, v38, v26
	v_mul_f32_e32 v45, v39, v34
	s_waitcnt vmcnt(4)
	v_mul_f32_e32 v42, v76, v6
	v_mul_f32_e32 v43, v77, v14
	v_mul_f32_e32 v48, v4, v22
	v_mul_f32_e32 v49, v5, v30
	v_bfe_u32 v22, v40, 16, 1
	v_bfe_u32 v18, v42, 16, 1
	v_add3_u32 v22, v40, v22, s50
	v_add3_u32 v18, v42, v18, s50
	v_lshrrev_b32_e32 v22, 16, v22
	v_cvt_pk_bf16_f32 v42, v44, v48
	v_cvt_pk_bf16_f32 v41, v41, v43
	v_and_or_b32 v40, v18, s51, v22
	v_mov_b32_e32 v18, v11
	v_mov_b32_e32 v14, v7
	v_mov_b32_e32 v30, v23
	v_cvt_pk_bf16_f32 v43, v45, v49
	v_pk_mul_f32 v[10:11], v[18:19], v[2:3]
	v_pk_mul_f32 v[6:7], v[14:15], v[76:77]
	v_mov_b32_e32 v34, v27
	v_pk_mul_f32 v[18:19], v[30:31], v[4:5]
	v_pk_mul_f32 v[14:15], v[34:35], v[38:39]
	global_store_dwordx4 v[86:87], v[40:43], off offset:96
	s_nop 1
	v_cvt_pk_bf16_f32 v43, v15, v19
	v_cvt_pk_bf16_f32 v42, v14, v18
	v_cvt_pk_bf16_f32 v41, v11, v7
	v_cvt_pk_bf16_f32 v40, v10, v6
	v_mul_f32_e32 v10, v76, v8
	v_mul_f32_e32 v11, v77, v16
	v_mul_f32_e32 v18, v4, v24
	v_mul_f32_e32 v19, v5, v32
	v_mul_f32_e32 v6, v2, v12
	v_mul_f32_e32 v7, v3, v20
	v_bfe_u32 v12, v18, 16, 1
	v_bfe_u32 v16, v11, 16, 1
	v_mul_f32_e32 v14, v38, v28
	v_mul_f32_e32 v15, v39, v36
	v_bfe_u32 v8, v19, 16, 1
	v_bfe_u32 v20, v10, 16, 1
	v_add3_u32 v11, v11, v16, s50
	v_add3_u32 v12, v18, v12, s50
	v_bfe_u32 v16, v6, 16, 1
	v_bfe_u32 v18, v7, 16, 1
	v_add3_u32 v10, v10, v20, s50
	v_add3_u32 v8, v19, v8, s50
	v_bfe_u32 v19, v14, 16, 1
	v_bfe_u32 v20, v15, 16, 1
	v_add3_u32 v7, v7, v18, s50
	v_add3_u32 v6, v6, v16, s50
	v_add3_u32 v15, v15, v20, s50
	v_add3_u32 v14, v14, v19, s50
	v_lshrrev_b32_e32 v6, 16, v6
	v_lshrrev_b32_e32 v7, 16, v7
	v_mov_b32_e32 v16, v9
	v_mov_b32_e32 v32, v25
	global_store_dwordx4 v[86:87], v[40:43], off offset:2144
	v_lshrrev_b32_e32 v14, 16, v14
	v_lshrrev_b32_e32 v15, 16, v15
	v_and_or_b32 v41, v11, s51, v7
	v_and_or_b32 v40, v10, s51, v6
	v_mov_b32_e32 v20, v13
	v_pk_mul_f32 v[6:7], v[16:17], v[76:77]
	v_mov_b32_e32 v36, v29
	v_pk_mul_f32 v[4:5], v[32:33], v[4:5]
	v_and_or_b32 v43, v8, s51, v15
	v_and_or_b32 v42, v12, s51, v14
	v_pk_mul_f32 v[2:3], v[20:21], v[2:3]
	v_pk_mul_f32 v[8:9], v[36:37], v[38:39]
	v_cvt_pk_bf16_f32 v5, v9, v5
	v_cvt_pk_bf16_f32 v4, v8, v4
	v_cvt_pk_bf16_f32 v3, v3, v7
	v_cvt_pk_bf16_f32 v2, v2, v6
	global_store_dwordx4 v[46:47], v[40:43], off offset:96
	global_store_dwordx4 v[46:47], v[2:5], off offset:2144

.LBB0_37:
	s_waitcnt vmcnt(14)
	s_waitcnt vmcnt(12)
	v_mul_f32_e32 v40, v98, v42
	v_mul_f32_e32 v41, v99, v50
	v_add_co_u32_e32 v88, vcc, s57, v86
	v_bfe_u32 v42, v40, 16, 1
	v_add3_u32 v42, v40, v42, s50
	v_bfe_u32 v40, v41, 16, 1
	v_add3_u32 v50, v41, v40, s50
	s_waitcnt vmcnt(10)
	s_waitcnt vmcnt(8)
	v_mul_f32_e32 v40, v96, v54
	v_mul_f32_e32 v41, v97, v66
	v_addc_co_u32_e32 v89, vcc, 0, v87, vcc
	v_bfe_u32 v54, v40, 16, 1
	v_add3_u32 v54, v40, v54, s50
	v_bfe_u32 v40, v41, 16, 1
	v_add3_u32 v66, v41, v40, s50
	v_mul_f32_e32 v40, v78, v62
	v_mul_f32_e32 v41, v79, v70
	s_and_b64 vcc, exec, s[4:5]
	v_bfe_u32 v62, v41, 16, 1
	v_add3_u32 v62, v41, v62, s50
	v_bfe_u32 v41, v40, 16, 1
	v_add3_u32 v70, v40, v41, s50
	v_mul_f32_e32 v40, v74, v46
	v_mul_f32_e32 v41, v75, v58
	v_lshrrev_b32_e32 v58, 16, v62
	v_bfe_u32 v46, v41, 16, 1
	v_add3_u32 v41, v41, v46, s50
	v_bfe_u32 v46, v40, 16, 1
	v_add3_u32 v40, v40, v46, s50
	v_lshrrev_b32_e32 v41, 16, v41
	v_and_or_b32 v103, v50, s51, v41
	v_lshrrev_b32_e32 v40, 16, v40
	v_mov_b32_e32 v50, v43
	v_and_or_b32 v102, v42, s51, v40
	v_pk_mul_f32 v[40:41], v[50:51], v[98:99]
	v_lshrrev_b32_e32 v46, 16, v70
	v_bfe_u32 v42, v40, 16, 1
	v_and_or_b32 v105, v66, s51, v58
	v_and_or_b32 v104, v54, s51, v46
	v_add3_u32 v46, v40, v42, s50
	v_bfe_u32 v40, v41, 16, 1
	v_mov_b32_e32 v66, v55
	v_add3_u32 v50, v41, v40, s50
	v_pk_mul_f32 v[40:41], v[66:67], v[96:97]
	v_mov_b32_e32 v70, v63
	v_bfe_u32 v42, v40, 16, 1
	v_add3_u32 v42, v40, v42, s50
	v_bfe_u32 v40, v41, 16, 1
	v_add3_u32 v43, v41, v40, s50
	v_pk_mul_f32 v[40:41], v[70:71], v[78:79]
	v_mov_b32_e32 v58, v47
	v_bfe_u32 v51, v41, 16, 1
	v_add3_u32 v51, v41, v51, s50
	v_bfe_u32 v41, v40, 16, 1
	v_add3_u32 v54, v40, v41, s50
	v_pk_mul_f32 v[40:41], v[58:59], v[74:75]
	v_lshrrev_b32_e32 v51, 16, v51
	v_bfe_u32 v47, v41, 16, 1
	v_add3_u32 v41, v41, v47, s50
	v_bfe_u32 v47, v40, 16, 1
	v_add3_u32 v40, v40, v47, s50
	v_lshrrev_b32_e32 v47, 16, v54
	v_lshrrev_b32_e32 v41, 16, v41
	v_lshrrev_b32_e32 v40, 16, v40
	v_and_or_b32 v43, v43, s51, v51
	v_and_or_b32 v42, v42, s51, v47
	v_and_or_b32 v41, v50, s51, v41
	v_and_or_b32 v40, v46, s51, v40
	global_store_dwordx4 v[86:87], v[40:43], off offset:2048
	global_store_dwordx4 v[86:87], v[102:105], off
	s_nop 0
	v_mul_f32_e32 v40, v98, v44
	v_mul_f32_e32 v41, v99, v52
	v_mov_b32_e32 v52, v45
	v_bfe_u32 v42, v40, 16, 1
	v_add3_u32 v44, v40, v42, s50
	v_bfe_u32 v40, v41, 16, 1
	v_add3_u32 v46, v41, v40, s50
	v_mul_f32_e32 v40, v96, v56
	v_mul_f32_e32 v41, v97, v68
	v_mov_b32_e32 v68, v57
	v_bfe_u32 v42, v40, 16, 1
	v_add3_u32 v42, v40, v42, s50
	v_bfe_u32 v40, v41, 16, 1
	v_add3_u32 v43, v41, v40, s50
	v_mul_f32_e32 v40, v78, v64
	v_mul_f32_e32 v41, v79, v72
	v_mov_b32_e32 v72, v65
	v_bfe_u32 v47, v41, 16, 1
	v_add3_u32 v47, v41, v47, s50
	v_bfe_u32 v41, v40, 16, 1
	v_add3_u32 v50, v40, v41, s50
	v_mul_f32_e32 v40, v74, v48
	v_mul_f32_e32 v41, v75, v60
	v_lshrrev_b32_e32 v47, 16, v47
	v_bfe_u32 v48, v41, 16, 1
	v_add3_u32 v41, v41, v48, s50
	v_bfe_u32 v48, v40, 16, 1
	v_add3_u32 v40, v40, v48, s50
	v_lshrrev_b32_e32 v48, 16, v50
	v_lshrrev_b32_e32 v41, 16, v41
	v_lshrrev_b32_e32 v40, 16, v40
	v_and_or_b32 v43, v43, s51, v47
	v_and_or_b32 v42, v42, s51, v48
	v_and_or_b32 v41, v46, s51, v41
	v_and_or_b32 v40, v44, s51, v40
	global_store_dwordx4 v[88:89], v[40:43], off
	v_mov_b32_e32 v60, v49
	v_pk_mul_f32 v[46:47], v[68:69], v[96:97]
	v_pk_mul_f32 v[42:43], v[52:53], v[98:99]
	v_pk_mul_f32 v[40:41], v[60:61], v[74:75]
	v_pk_mul_f32 v[44:45], v[72:73], v[78:79]
	v_bfe_u32 v48, v47, 16, 1
	v_bfe_u32 v49, v46, 16, 1
	v_bfe_u32 v50, v43, 16, 1
	v_bfe_u32 v51, v42, 16, 1
	v_add3_u32 v51, v42, v51, s50
	v_add3_u32 v50, v43, v50, s50
	v_add3_u32 v42, v46, v49, s50
	v_add3_u32 v43, v47, v48, s50
	v_bfe_u32 v46, v40, 16, 1
	v_bfe_u32 v47, v41, 16, 1
	v_bfe_u32 v48, v44, 16, 1
	v_bfe_u32 v49, v45, 16, 1
	v_add3_u32 v45, v45, v49, s50
	v_add3_u32 v44, v44, v48, s50
	v_add3_u32 v41, v41, v47, s50
	v_add3_u32 v40, v40, v46, s50
	v_lshrrev_b32_e32 v40, 16, v40
	v_lshrrev_b32_e32 v41, 16, v41
	v_lshrrev_b32_e32 v44, 16, v44
	v_lshrrev_b32_e32 v45, 16, v45
	v_and_or_b32 v43, v43, s51, v45
	v_and_or_b32 v42, v42, s51, v44
	v_and_or_b32 v41, v50, s51, v41
	v_and_or_b32 v40, v51, s51, v40
	global_store_dwordx4 v[88:89], v[40:43], off offset:2048
	s_waitcnt vmcnt(7)
	s_waitcnt vmcnt(5)
	v_mul_f32_e32 v40, v2, v10
	v_mul_f32_e32 v41, v3, v22
	v_mul_f32_e32 v44, v38, v26
	v_mul_f32_e32 v45, v39, v34
	s_waitcnt vmcnt(4)
	v_mul_f32_e32 v42, v76, v6
	v_mul_f32_e32 v43, v77, v14
	v_mul_f32_e32 v46, v4, v18
	v_mul_f32_e32 v47, v5, v30
	v_bfe_u32 v22, v40, 16, 1
	v_bfe_u32 v18, v42, 16, 1
	v_add3_u32 v22, v40, v22, s50
	v_add3_u32 v18, v42, v18, s50
	v_lshrrev_b32_e32 v22, 16, v22
	v_cvt_pk_bf16_f32 v42, v44, v46
	v_cvt_pk_bf16_f32 v41, v41, v43
	v_mov_b32_e32 v14, v7
	v_mov_b32_e32 v30, v19
	v_cvt_pk_bf16_f32 v43, v45, v47
	v_and_or_b32 v40, v18, s51, v22
	v_mov_b32_e32 v22, v11
	v_pk_mul_f32 v[6:7], v[14:15], v[76:77]
	v_mov_b32_e32 v34, v27
	v_pk_mul_f32 v[18:19], v[30:31], v[4:5]
	v_pk_mul_f32 v[10:11], v[22:23], v[2:3]
	v_pk_mul_f32 v[14:15], v[34:35], v[38:39]
	global_store_dwordx4 v[86:87], v[40:43], off offset:32
	v_mov_b32_e32 v74, 1.0
	v_mov_b32_e32 v98, 1.0
	v_cvt_pk_bf16_f32 v43, v15, v19
	v_cvt_pk_bf16_f32 v42, v14, v18
	v_cvt_pk_bf16_f32 v41, v11, v7
	v_cvt_pk_bf16_f32 v40, v10, v6
	v_mul_f32_e32 v10, v76, v8
	v_mul_f32_e32 v11, v77, v16
	v_mul_f32_e32 v18, v4, v20
	v_mul_f32_e32 v19, v5, v32
	v_mul_f32_e32 v6, v2, v12
	v_mul_f32_e32 v7, v3, v24
	v_bfe_u32 v12, v18, 16, 1
	v_bfe_u32 v16, v11, 16, 1
	v_mul_f32_e32 v14, v38, v28
	v_mul_f32_e32 v15, v39, v36
	v_bfe_u32 v8, v19, 16, 1
	v_bfe_u32 v20, v10, 16, 1
	v_add3_u32 v11, v11, v16, s50
	v_add3_u32 v12, v18, v12, s50
	v_bfe_u32 v16, v6, 16, 1
	v_bfe_u32 v18, v7, 16, 1
	v_add3_u32 v10, v10, v20, s50
	v_add3_u32 v8, v19, v8, s50
	v_bfe_u32 v19, v14, 16, 1
	v_bfe_u32 v20, v15, 16, 1
	v_add3_u32 v7, v7, v18, s50
	v_add3_u32 v6, v6, v16, s50
	v_add3_u32 v15, v15, v20, s50
	v_add3_u32 v14, v14, v19, s50
	v_lshrrev_b32_e32 v6, 16, v6
	v_lshrrev_b32_e32 v7, 16, v7
	v_mov_b32_e32 v16, v9
	v_mov_b32_e32 v32, v21
	global_store_dwordx4 v[86:87], v[40:43], off offset:2080
	v_lshrrev_b32_e32 v14, 16, v14
	v_lshrrev_b32_e32 v15, 16, v15
	v_and_or_b32 v41, v11, s51, v7
	v_and_or_b32 v40, v10, s51, v6
	v_mov_b32_e32 v24, v13
	v_pk_mul_f32 v[6:7], v[16:17], v[76:77]
	v_mov_b32_e32 v36, v29
	v_pk_mul_f32 v[4:5], v[32:33], v[4:5]
	v_and_or_b32 v43, v8, s51, v15
	v_and_or_b32 v42, v12, s51, v14
	v_pk_mul_f32 v[2:3], v[24:25], v[2:3]
	v_pk_mul_f32 v[8:9], v[36:37], v[38:39]
	v_cvt_pk_bf16_f32 v5, v9, v5
	v_cvt_pk_bf16_f32 v4, v8, v4
	v_cvt_pk_bf16_f32 v3, v3, v7
	v_cvt_pk_bf16_f32 v2, v2, v6
	global_store_dwordx4 v[88:89], v[2:5], off offset:2080
	global_store_dwordx4 v[88:89], v[40:43], off offset:32
	v_mov_b32_e32 v75, 1.0
	v_or_b32_e32 v2, 32, v90
	v_mad_i64_i32 v[2:3], s[10:11], v2, s75, v[92:93]
	v_or_b32_e32 v4, 33, v90
	v_mad_i64_i32 v[4:5], s[10:11], v4, s75, v[92:93]
	global_load_dwordx4 v[46:49], v[2:3], off nt
	global_load_dwordx4 v[42:45], v[4:5], off nt
	v_or_b32_e32 v2, 34, v90
	v_mad_i64_i32 v[2:3], s[10:11], v2, s75, v[92:93]
	v_or_b32_e32 v4, 35, v90
	v_mad_i64_i32 v[4:5], s[10:11], v4, s75, v[92:93]
	global_load_dwordx4 v[58:61], v[2:3], off nt
	global_load_dwordx4 v[50:53], v[4:5], off nt
	v_or_b32_e32 v2, 36, v90
	v_mad_i64_i32 v[2:3], s[10:11], v2, s75, v[92:93]
	v_or_b32_e32 v4, 37, v90
	v_mad_i64_i32 v[4:5], s[10:11], v4, s75, v[92:93]
	global_load_dwordx4 v[62:65], v[2:3], off nt
	global_load_dwordx4 v[54:57], v[4:5], off nt
	v_or_b32_e32 v2, 38, v90
	v_mad_i64_i32 v[2:3], s[10:11], v2, s75, v[92:93]
	v_or_b32_e32 v4, 39, v90
	v_mad_i64_i32 v[4:5], s[10:11], v4, s75, v[92:93]
	global_load_dwordx4 v[70:73], v[2:3], off nt
	global_load_dwordx4 v[66:69], v[4:5], off nt
	v_mov_b32_e32 v2, 1.0
	v_mov_b32_e32 v99, 1.0
	v_mov_b32_e32 v78, 1.0
	v_mov_b32_e32 v96, 1.0
	v_mov_b32_e32 v79, 1.0
	v_mov_b32_e32 v97, 1.0
	s_cbranch_vccnz .LBB0_39
	global_load_dwordx4 v[74:77], v[94:95], off offset:128
	global_load_dwordx4 v[78:81], v[94:95], off offset:144
	s_waitcnt vmcnt(1)
	v_mov_b32_e32 v98, v75
	v_mov_b32_e32 v75, v76
	v_mov_b32_e32 v99, v77
	s_waitcnt vmcnt(0)
	v_mov_b32_e32 v96, v79
	v_mov_b32_e32 v79, v80
	v_mov_b32_e32 v97, v81

.LBB0_41:
	s_waitcnt vmcnt(14)
	s_waitcnt vmcnt(12)
	v_mul_f32_e32 v4, v98, v42
	v_mul_f32_e32 v5, v99, v50
	s_mov_b64 s[26:27], 0
	v_bfe_u32 v32, v4, 16, 1
	v_add3_u32 v32, v4, v32, s50
	v_bfe_u32 v4, v5, 16, 1
	v_add3_u32 v33, v5, v4, s50
	s_waitcnt vmcnt(10)
	s_waitcnt vmcnt(8)
	v_mul_f32_e32 v4, v96, v54
	v_mul_f32_e32 v5, v97, v66
	v_mov_b32_e32 v66, v55
	v_bfe_u32 v42, v4, 16, 1
	v_add3_u32 v42, v4, v42, s50
	v_bfe_u32 v4, v5, 16, 1
	v_add3_u32 v50, v5, v4, s50
	v_mul_f32_e32 v4, v78, v62
	v_mul_f32_e32 v5, v79, v70
	v_mov_b32_e32 v70, v63
	v_bfe_u32 v54, v5, 16, 1
	v_add3_u32 v54, v5, v54, s50
	v_bfe_u32 v5, v4, 16, 1
	v_add3_u32 v62, v4, v5, s50
	v_mul_f32_e32 v4, v74, v46
	v_mul_f32_e32 v5, v75, v58
	v_lshrrev_b32_e32 v54, 16, v54
	v_bfe_u32 v46, v5, 16, 1
	v_add3_u32 v5, v5, v46, s50
	v_bfe_u32 v46, v4, 16, 1
	v_add3_u32 v4, v4, v46, s50
	v_and_or_b32 v93, v50, s51, v54
	v_lshrrev_b32_e32 v5, 16, v5
	v_lshrrev_b32_e32 v4, 16, v4
	v_mov_b32_e32 v50, v43
	v_and_or_b32 v91, v33, s51, v5
	v_and_or_b32 v90, v32, s51, v4
	v_pk_mul_f32 v[4:5], v[50:51], v[98:99]
	v_lshrrev_b32_e32 v46, 16, v62
	v_bfe_u32 v32, v4, 16, 1
	v_add3_u32 v32, v4, v32, s50
	v_bfe_u32 v4, v5, 16, 1
	v_add3_u32 v33, v5, v4, s50
	v_pk_mul_f32 v[4:5], v[66:67], v[96:97]
	v_and_or_b32 v92, v42, s51, v46
	v_bfe_u32 v42, v4, 16, 1
	v_add3_u32 v42, v4, v42, s50
	v_bfe_u32 v4, v5, 16, 1
	v_add3_u32 v43, v5, v4, s50
	v_pk_mul_f32 v[4:5], v[70:71], v[78:79]
	v_mov_b32_e32 v58, v47
	v_bfe_u32 v46, v5, 16, 1
	v_add3_u32 v46, v5, v46, s50
	v_bfe_u32 v5, v4, 16, 1
	v_add3_u32 v50, v4, v5, s50
	v_pk_mul_f32 v[4:5], v[58:59], v[74:75]
	global_store_dwordx4 v[86:87], v[90:93], off offset:64
	v_bfe_u32 v47, v5, 16, 1
	v_add3_u32 v5, v5, v47, s50
	v_bfe_u32 v47, v4, 16, 1
	v_add3_u32 v4, v4, v47, s50
	v_lshrrev_b32_e32 v5, 16, v5
	v_lshrrev_b32_e32 v4, 16, v4
	v_and_or_b32 v91, v33, s51, v5
	v_and_or_b32 v90, v32, s51, v4
	v_mul_f32_e32 v4, v98, v44
	v_mul_f32_e32 v5, v99, v52
	v_lshrrev_b32_e32 v47, 16, v50
	v_bfe_u32 v32, v4, 16, 1
	v_add3_u32 v32, v4, v32, s50
	v_bfe_u32 v4, v5, 16, 1
	v_add3_u32 v33, v5, v4, s50
	v_mul_f32_e32 v4, v96, v56
	v_mul_f32_e32 v5, v97, v68
	v_and_or_b32 v92, v42, s51, v47
	v_bfe_u32 v42, v4, 16, 1
	v_lshrrev_b32_e32 v46, 16, v46
	v_add3_u32 v42, v4, v42, s50
	v_bfe_u32 v4, v5, 16, 1
	v_and_or_b32 v93, v43, s51, v46
	v_add3_u32 v43, v5, v4, s50
	v_mul_f32_e32 v4, v78, v64
	v_mul_f32_e32 v5, v79, v72
	v_mov_b32_e32 v52, v45
	v_bfe_u32 v44, v5, 16, 1
	v_add3_u32 v44, v5, v44, s50
	v_bfe_u32 v5, v4, 16, 1
	v_add3_u32 v46, v4, v5, s50
	v_mul_f32_e32 v4, v74, v48
	v_mul_f32_e32 v5, v75, v60
	v_lshrrev_b32_e32 v44, 16, v44
	v_bfe_u32 v47, v5, 16, 1
	v_add3_u32 v5, v5, v47, s50
	v_bfe_u32 v47, v4, 16, 1
	v_add3_u32 v4, v4, v47, s50
	v_lshrrev_b32_e32 v5, 16, v5
	v_lshrrev_b32_e32 v4, 16, v4
	v_mov_b32_e32 v68, v57
	global_store_dwordx4 v[86:87], v[90:93], off offset:2112
	v_lshrrev_b32_e32 v46, 16, v46
	v_mov_b32_e32 v60, v49
	v_and_or_b32 v93, v43, s51, v44
	v_and_or_b32 v91, v33, s51, v5
	v_and_or_b32 v90, v32, s51, v4
	v_pk_mul_f32 v[32:33], v[52:53], v[98:99]
	v_mov_b32_e32 v72, v65
	v_pk_mul_f32 v[44:45], v[68:69], v[96:97]
	v_and_or_b32 v92, v42, s51, v46
	v_pk_mul_f32 v[4:5], v[60:61], v[74:75]
	v_pk_mul_f32 v[42:43], v[72:73], v[78:79]
	v_cvt_pk_bf16_f32 v45, v43, v45
	v_cvt_pk_bf16_f32 v44, v42, v44
	v_cvt_pk_bf16_f32 v43, v5, v33
	v_cvt_pk_bf16_f32 v42, v4, v32
	s_waitcnt vmcnt(8)
	s_waitcnt vmcnt(6)
	global_store_dwordx4 v[88:89], v[42:45], off offset:2112
	v_mul_f32_e32 v32, v80, v22
	v_mul_f32_e32 v33, v81, v34
	s_waitcnt vmcnt(6)
	s_waitcnt vmcnt(4)
	v_mul_f32_e32 v42, v30, v18
	v_mul_f32_e32 v43, v31, v10
	s_waitcnt vmcnt(3)
	v_mul_f32_e32 v4, v2, v26
	v_mul_f32_e32 v5, v3, v38
	v_mul_f32_e32 v44, v76, v14
	v_mul_f32_e32 v45, v77, v6
	v_bfe_u32 v18, v32, 16, 1
	v_add3_u32 v18, v32, v18, s50
	v_bfe_u32 v22, v4, 16, 1
	v_add3_u32 v4, v4, v22, s50
	v_cvt_pk_bf16_f32 v45, v43, v45
	v_mov_b32_e32 v34, v23
	v_lshrrev_b32_e32 v4, 16, v4
	v_cvt_pk_bf16_f32 v44, v42, v44
	v_mov_b32_e32 v38, v27
	v_pk_mul_f32 v[22:23], v[34:35], v[80:81]
	v_mul_f32_e32 v6, v76, v15
	v_mul_f32_e32 v7, v77, v7
	v_cvt_pk_bf16_f32 v43, v5, v33
	v_and_or_b32 v42, v18, s51, v4
	v_pk_mul_f32 v[4:5], v[38:39], v[2:3]
	v_mul_f32_e32 v10, v30, v19
	v_mul_f32_e32 v11, v31, v11
	v_cvt_pk_bf16_f32 v7, v11, v7
	v_cvt_pk_bf16_f32 v6, v10, v6
	v_cvt_pk_bf16_f32 v5, v5, v23
	v_cvt_pk_bf16_f32 v4, v4, v22
	global_store_dwordx4 v[86:87], v[4:7], off offset:2144
	s_nop 1
	v_mul_f32_e32 v6, v80, v24
	s_nop 1
	v_mul_f32_e32 v7, v81, v36
	v_mul_f32_e32 v14, v76, v16
	v_mul_f32_e32 v15, v77, v8
	v_mul_f32_e32 v4, v2, v28
	v_mul_f32_e32 v5, v3, v40
	v_mul_f32_e32 v10, v30, v20
	v_mul_f32_e32 v11, v31, v12
	v_bfe_u32 v8, v15, 16, 1
	v_bfe_u32 v12, v14, 16, 1
	v_bfe_u32 v16, v7, 16, 1
	v_bfe_u32 v18, v6, 16, 1
	v_add3_u32 v18, v6, v18, s50
	v_add3_u32 v16, v7, v16, s50
	v_add3_u32 v6, v14, v12, s50
	v_add3_u32 v7, v15, v8, s50
	v_bfe_u32 v8, v4, 16, 1
	v_bfe_u32 v12, v5, 16, 1
	v_bfe_u32 v14, v10, 16, 1
	v_bfe_u32 v15, v11, 16, 1
	v_add3_u32 v11, v11, v15, s50
	v_add3_u32 v10, v10, v14, s50
	v_add3_u32 v5, v5, v12, s50
	v_add3_u32 v4, v4, v8, s50
	v_lshrrev_b32_e32 v4, 16, v4
	v_lshrrev_b32_e32 v5, 16, v5
	v_lshrrev_b32_e32 v8, 16, v10
	v_lshrrev_b32_e32 v10, 16, v11
	v_mov_b32_e32 v40, v29
	v_and_or_b32 v7, v7, s51, v10
	v_and_or_b32 v6, v6, s51, v8
	v_and_or_b32 v5, v16, s51, v5
	v_and_or_b32 v4, v18, s51, v4
	v_pk_mul_f32 v[2:3], v[40:41], v[2:3]
	v_mov_b32_e32 v36, v25
	global_store_dwordx4 v[88:89], v[4:7], off offset:96
	v_mov_b32_e32 v16, v21
	v_mov_b32_e32 v8, v13
	v_pk_mul_f32 v[4:5], v[36:37], v[80:81]
	v_and_b32_sdwa v6, v3, v100 dst_sel:DWORD dst_unused:UNUSED_PAD src0_sel:WORD_1 src1_sel:DWORD
	v_and_b32_sdwa v7, v2, v100 dst_sel:DWORD dst_unused:UNUSED_PAD src0_sel:WORD_1 src1_sel:DWORD
	v_add3_u32 v2, v2, v7, s50
	v_add3_u32 v3, v3, v6, s50
	v_and_b32_sdwa v6, v5, v100 dst_sel:DWORD dst_unused:UNUSED_PAD src0_sel:WORD_1 src1_sel:DWORD
	v_and_b32_sdwa v7, v4, v100 dst_sel:DWORD dst_unused:UNUSED_PAD src0_sel:WORD_1 src1_sel:DWORD
	v_add3_u32 v5, v5, v6, s50
	v_add3_u32 v4, v4, v7, s50
	v_and_b32_e32 v5, 0xffff0000, v5
	v_and_b32_e32 v4, 0xffff0000, v4
	v_or_b32_sdwa v3, v5, v3 dst_sel:DWORD dst_unused:UNUSED_PAD src0_sel:DWORD src1_sel:WORD_1
	v_or_b32_sdwa v2, v4, v2 dst_sel:DWORD dst_unused:UNUSED_PAD src0_sel:DWORD src1_sel:WORD_1
	v_mov_b32_e32 v4, v30
	v_mov_b32_e32 v5, v76
	v_pk_mul_f32 v[4:5], v[16:17], v[4:5]
	v_mov_b32_e32 v76, v31
	v_and_b32_sdwa v6, v5, v100 dst_sel:DWORD dst_unused:UNUSED_PAD src0_sel:WORD_1 src1_sel:DWORD
	v_and_b32_sdwa v7, v4, v100 dst_sel:DWORD dst_unused:UNUSED_PAD src0_sel:WORD_1 src1_sel:DWORD
	v_add3_u32 v5, v5, v6, s50
	v_add3_u32 v4, v4, v7, s50
	v_pk_mul_f32 v[6:7], v[8:9], v[76:77]
	v_lshrrev_b32_e32 v4, 16, v4
	v_and_b32_sdwa v8, v6, v100 dst_sel:DWORD dst_unused:UNUSED_PAD src0_sel:WORD_1 src1_sel:DWORD
	v_and_or_b32 v4, v5, s51, v4
	v_and_b32_sdwa v5, v7, v100 dst_sel:DWORD dst_unused:UNUSED_PAD src0_sel:WORD_1 src1_sel:DWORD
	v_add3_u32 v6, v6, v8, s50
	v_add3_u32 v5, v7, v5, s50
	v_lshrrev_b32_e32 v6, 16, v6
	v_and_or_b32 v5, v5, s51, v6
	global_store_dwordx4 v[88:89], v[90:93], off offset:64
	global_store_dwordx4 v[86:87], v[42:45], off offset:96

.LBB0_482:
	v_or_b32_e32 v2, s24, v155
	v_mul_u32_u24_e32 v2, 0x300, v2
	v_lshlrev_b32_e32 v2, 1, v2
	v_lshl_add_u64 v[42:43], s[60:61], 0, v[2:3]
	s_lshl_b32 s24, s64, 1
	v_lshl_add_u64 v[42:43], v[42:43], 0, s[24:25]
	v_lshlrev_b32_e32 v2, 1, v116
	v_lshl_add_u64 v[100:101], v[42:43], 0, v[2:3]
	s_waitcnt vmcnt(15)
	s_waitcnt vmcnt(13)
	v_mul_f32_e32 v42, v76, v48
	v_mul_f32_e32 v43, v77, v56
	s_waitcnt vmcnt(12)
	s_waitcnt vmcnt(11)
	s_waitcnt vmcnt(9)
	v_mul_f32_e32 v96, v92, v44
	v_mul_f32_e32 v97, v93, v52
	v_mul_f32_e32 v98, v80, v64
	v_mul_f32_e32 v99, v81, v72
	s_waitcnt vmcnt(8)
	v_bfe_u32 v56, v42, 16, 1
	v_mul_f32_e32 v102, v90, v60
	v_mul_f32_e32 v103, v91, v68
	v_bfe_u32 v52, v96, 16, 1
	v_bfe_u32 v68, v99, 16, 1
	v_add3_u32 v42, v42, v56, s76
	v_bfe_u32 v2, v103, 16, 1
	v_add3_u32 v52, v96, v52, s76
	v_add3_u32 v68, v99, v68, s76
	v_lshrrev_b32_e32 v42, 16, v42
	s_mov_b32 s24, 0x5180000
	v_add3_u32 v2, v103, v2, s76
	v_lshrrev_b32_e32 v60, 16, v68
	v_and_or_b32 v96, v52, s77, v42
	v_add_co_u32_e32 v42, vcc, s24, v100
	v_mov_b32_e32 v52, v45
	v_mov_b32_e32 v68, v61
	v_and_or_b32 v99, v2, s77, v60
	v_cvt_pk_bf16_f32 v98, v98, v102
	v_cvt_pk_bf16_f32 v97, v43, v97
	v_addc_co_u32_e32 v43, vcc, 0, v101, vcc
	v_mov_b32_e32 v56, v49
	v_pk_mul_f32 v[44:45], v[52:53], v[92:93]
	v_mov_b32_e32 v72, v65
	v_pk_mul_f32 v[52:53], v[68:69], v[90:91]
	global_store_dwordx4 v[42:43], v[96:99], off
	v_pk_mul_f32 v[42:43], v[56:57], v[76:77]
	v_pk_mul_f32 v[48:49], v[72:73], v[80:81]
	v_bfe_u32 v2, v53, 16, 1
	v_bfe_u32 v56, v52, 16, 1
	v_bfe_u32 v57, v45, 16, 1
	v_bfe_u32 v60, v44, 16, 1
	v_add3_u32 v60, v44, v60, s76
	v_add3_u32 v57, v45, v57, s76
	v_add3_u32 v44, v52, v56, s76
	v_add3_u32 v2, v53, v2, s76
	v_bfe_u32 v45, v42, 16, 1
	v_bfe_u32 v52, v43, 16, 1
	v_bfe_u32 v53, v48, 16, 1
	v_bfe_u32 v56, v49, 16, 1
	v_add3_u32 v49, v49, v56, s76
	v_add3_u32 v48, v48, v53, s76
	v_add3_u32 v43, v43, v52, s76
	v_add3_u32 v42, v42, v45, s76
	s_mov_b64 s[60:61], 0x5180000
	v_lshrrev_b32_e32 v42, 16, v42
	v_lshrrev_b32_e32 v43, 16, v43
	v_lshrrev_b32_e32 v48, 16, v48
	v_lshrrev_b32_e32 v45, 16, v49
	v_lshl_add_u64 v[84:85], v[100:101], 0, s[60:61]
	v_and_or_b32 v45, v2, s77, v45
	v_and_or_b32 v44, v44, s77, v48
	v_and_or_b32 v43, v57, s77, v43
	v_and_or_b32 v42, v60, s77, v42
	global_store_dwordx4 v[84:85], v[42:45], off offset:1536
	s_nop 1
	v_mul_f32_e32 v44, v92, v46
	s_nop 1
	v_mul_f32_e32 v45, v93, v54
	v_mul_f32_e32 v52, v90, v62
	v_mul_f32_e32 v53, v91, v70
	v_mul_f32_e32 v42, v76, v50
	v_mul_f32_e32 v43, v77, v58
	v_mul_f32_e32 v48, v80, v66
	v_mul_f32_e32 v49, v81, v74
	v_bfe_u32 v50, v45, 16, 1
	v_bfe_u32 v54, v44, 16, 1
	v_add3_u32 v54, v44, v54, s76
	v_add3_u32 v50, v45, v50, s76
	v_bfe_u32 v45, v42, 16, 1
	v_bfe_u32 v46, v43, 16, 1
	v_add3_u32 v43, v43, v46, s76
	v_add3_u32 v42, v42, v45, s76
	v_lshrrev_b32_e32 v42, 16, v42
	v_lshrrev_b32_e32 v43, 16, v43
	v_mov_b32_e32 v70, v63
	v_cvt_pk_bf16_f32 v45, v49, v53
	v_cvt_pk_bf16_f32 v44, v48, v52
	v_and_or_b32 v43, v50, s77, v43
	v_and_or_b32 v42, v54, s77, v42
	v_mov_b32_e32 v54, v47
	v_mov_b32_e32 v74, v67
	v_pk_mul_f32 v[48:49], v[70:71], v[90:91]
	global_store_dwordx4 v[84:85], v[42:45], off offset:3072
	v_mov_b32_e32 v58, v51
	v_pk_mul_f32 v[46:47], v[74:75], v[80:81]
	v_pk_mul_f32 v[44:45], v[54:55], v[92:93]
	v_bfe_u32 v2, v49, 16, 1
	v_pk_mul_f32 v[42:43], v[58:59], v[76:77]
	v_bfe_u32 v50, v48, 16, 1
	v_bfe_u32 v51, v45, 16, 1
	v_bfe_u32 v52, v44, 16, 1
	v_add3_u32 v2, v49, v2, s76
	v_bfe_u32 v49, v46, 16, 1
	v_add3_u32 v52, v44, v52, s76
	v_add3_u32 v51, v45, v51, s76
	v_add3_u32 v44, v48, v50, s76
	v_bfe_u32 v45, v42, 16, 1
	v_bfe_u32 v48, v43, 16, 1
	v_bfe_u32 v50, v47, 16, 1
	v_add3_u32 v46, v46, v49, s76
	v_add3_u32 v47, v47, v50, s76
	v_add3_u32 v43, v43, v48, s76
	v_add3_u32 v42, v42, v45, s76
	v_lshrrev_b32_e32 v46, 16, v46
	s_mov_b32 s24, 0x5181000
	v_lshrrev_b32_e32 v42, 16, v42
	v_lshrrev_b32_e32 v43, 16, v43
	v_lshrrev_b32_e32 v45, 16, v47
	v_and_or_b32 v44, v44, s77, v46
	v_add_co_u32_e32 v46, vcc, s24, v100
	v_and_or_b32 v45, v2, s77, v45
	v_and_or_b32 v43, v51, s77, v43
	v_and_or_b32 v42, v52, s77, v42
	v_addc_co_u32_e32 v47, vcc, 0, v101, vcc
	global_store_dwordx4 v[46:47], v[42:45], off offset:512
	s_waitcnt vmcnt(7)
	s_waitcnt vmcnt(5)
	v_mul_f32_e32 v42, v4, v12
	v_mul_f32_e32 v43, v5, v20
	v_mul_f32_e32 v48, v40, v28
	v_mul_f32_e32 v49, v41, v36
	s_waitcnt vmcnt(4)
	v_mul_f32_e32 v44, v82, v8
	v_mul_f32_e32 v45, v83, v16
	v_mul_f32_e32 v50, v78, v24
	v_mul_f32_e32 v51, v79, v32
	v_bfe_u32 v24, v43, 16, 1
	v_bfe_u32 v12, v45, 16, 1
	v_add3_u32 v24, v43, v24, s76
	v_add3_u32 v12, v45, v12, s76
	v_lshrrev_b32_e32 v24, 16, v24
	v_cvt_pk_bf16_f32 v45, v49, v51
	v_cvt_pk_bf16_f32 v42, v42, v44
	v_mov_b32_e32 v20, v13
	v_mov_b32_e32 v32, v25
	v_and_or_b32 v43, v12, s77, v24
	v_pk_mul_f32 v[12:13], v[20:21], v[4:5]
	v_mov_b32_e32 v16, v9
	v_pk_mul_f32 v[20:21], v[32:33], v[78:79]
	v_cvt_pk_bf16_f32 v44, v48, v50
	v_pk_mul_f32 v[8:9], v[16:17], v[82:83]
	v_mov_b32_e32 v36, v29
	v_bfe_u32 v2, v21, 16, 1
	v_pk_mul_f32 v[16:17], v[36:37], v[40:41]
	v_add3_u32 v2, v21, v2, s76
	v_bfe_u32 v28, v17, 16, 1
	global_store_dwordx4 v[84:85], v[42:45], off offset:32
	v_add3_u32 v17, v17, v28, s76
	s_nop 1
	v_cvt_pk_bf16_f32 v43, v13, v9
	v_cvt_pk_bf16_f32 v42, v12, v8
	v_lshrrev_b32_e32 v17, 16, v17
	v_cvt_pk_bf16_f32 v44, v16, v20
	v_mul_f32_e32 v12, v82, v10
	v_mul_f32_e32 v13, v83, v18
	v_and_or_b32 v45, v2, s77, v17
	v_mul_f32_e32 v8, v4, v14
	v_mul_f32_e32 v9, v5, v22
	v_mul_f32_e32 v20, v78, v26
	v_mul_f32_e32 v21, v79, v34
	v_bfe_u32 v14, v13, 16, 1
	v_bfe_u32 v18, v12, 16, 1
	v_mul_f32_e32 v16, v40, v30
	v_mul_f32_e32 v17, v41, v38
	v_add3_u32 v12, v12, v18, s76
	v_add3_u32 v13, v13, v14, s76
	v_bfe_u32 v14, v8, 16, 1
	v_bfe_u32 v18, v9, 16, 1
	v_add3_u32 v9, v9, v18, s76
	v_add3_u32 v8, v8, v14, s76
	v_lshrrev_b32_e32 v8, 16, v8
	v_lshrrev_b32_e32 v9, 16, v9
	v_mov_b32_e32 v34, v27
	global_store_dwordx4 v[84:85], v[42:45], off offset:1568
	s_nop 1
	v_and_or_b32 v43, v13, s77, v9
	s_nop 1
	v_and_or_b32 v42, v12, s77, v8
	v_mov_b32_e32 v22, v15
	v_pk_mul_f32 v[12:13], v[34:35], v[78:79]
	v_cvt_pk_bf16_f32 v45, v17, v21
	v_pk_mul_f32 v[4:5], v[22:23], v[4:5]
	v_mov_b32_e32 v18, v11
	v_cvt_pk_bf16_f32 v44, v16, v20
	v_pk_mul_f32 v[8:9], v[18:19], v[82:83]
	v_mov_b32_e32 v38, v31
	s_mov_b64 s[62:63], 0x18000
	v_pk_mul_f32 v[10:11], v[38:39], v[40:41]
	v_lshl_add_u64 v[6:7], v[86:87], 0, s[62:63]
	s_mov_b32 s24, 0x18000
	v_cvt_pk_bf16_f32 v8, v4, v8
	v_add_co_u32_e32 v4, vcc, s24, v6
	v_cvt_pk_bf16_f32 v9, v5, v9
	v_addc_co_u32_e32 v5, vcc, 0, v7, vcc
	v_cvt_pk_bf16_f32 v11, v11, v13
	v_cvt_pk_bf16_f32 v10, v10, v12
	v_add_co_u32_e32 v6, vcc, s78, v86
	global_store_dwordx4 v[84:85], v[42:45], off offset:3104
	global_store_dwordx4 v[46:47], v[8:11], off offset:544
	v_addc_co_u32_e32 v7, vcc, 0, v87, vcc
	global_load_dwordx4 v[48:51], v[4:5], off nt
	global_load_dwordx4 v[44:47], v[6:7], off offset:2048 nt
	v_add_co_u32_e32 v4, vcc, s79, v86
	s_mov_b32 s24, 0x34000
	s_nop 0
	v_addc_co_u32_e32 v5, vcc, 0, v87, vcc
	v_add_co_u32_e32 v6, vcc, s24, v86
	s_mov_b32 s24, 0x36000
	s_nop 0
	v_addc_co_u32_e32 v7, vcc, 0, v87, vcc
	global_load_dwordx4 v[56:59], v[4:5], off nt
	global_load_dwordx4 v[52:55], v[6:7], off offset:2048 nt
	v_add_co_u32_e32 v4, vcc, s24, v86
	v_mov_b32_e32 v76, 1.0
	s_nop 0
	v_addc_co_u32_e32 v5, vcc, 0, v87, vcc
	v_add_co_u32_e32 v6, vcc, 0x37000, v86
	v_mov_b32_e32 v92, 1.0
	s_nop 0
	v_addc_co_u32_e32 v7, vcc, 0, v87, vcc
	global_load_dwordx4 v[64:67], v[4:5], off nt
	global_load_dwordx4 v[60:63], v[6:7], off offset:2048 nt
	v_add_co_u32_e32 v4, vcc, 0x39000, v86
	v_mov_b32_e32 v77, 1.0
	s_nop 0
	v_addc_co_u32_e32 v5, vcc, 0, v87, vcc
	v_add_co_u32_e32 v6, vcc, 0x3a000, v86
	v_mov_b32_e32 v93, 1.0
	s_nop 0
	v_addc_co_u32_e32 v7, vcc, 0, v87, vcc
	global_load_dwordx4 v[72:75], v[4:5], off nt
	global_load_dwordx4 v[68:71], v[6:7], off offset:2048 nt
	v_mov_b32_e32 v4, 1.0
	s_and_b64 vcc, exec, s[16:17]
	v_mov_b32_e32 v80, 1.0
	v_mov_b32_e32 v90, 1.0
	v_mov_b32_e32 v81, 1.0
	v_mov_b32_e32 v91, 1.0
	s_cbranch_vccnz .LBB0_484
	global_load_dwordx4 v[76:79], v94, s[26:27] offset:128
	global_load_dwordx4 v[80:83], v94, s[26:27] offset:144
	s_waitcnt vmcnt(1)
	v_mov_b32_e32 v92, v77
	v_mov_b32_e32 v77, v78
	v_mov_b32_e32 v93, v79
	s_waitcnt vmcnt(0)
	v_mov_b32_e32 v90, v81
	v_mov_b32_e32 v81, v82
	v_mov_b32_e32 v91, v83

.LBB0_486:
	s_waitcnt vmcnt(15)
	s_waitcnt vmcnt(13)
	v_mul_f32_e32 v42, v76, v48
	v_mul_f32_e32 v43, v77, v56
	s_waitcnt vmcnt(12)
	s_waitcnt vmcnt(11)
	s_waitcnt vmcnt(9)
	v_mul_f32_e32 v82, v92, v44
	v_mul_f32_e32 v83, v93, v52
	v_mul_f32_e32 v86, v80, v64
	v_mul_f32_e32 v87, v81, v72
	s_waitcnt vmcnt(8)
	v_bfe_u32 v56, v42, 16, 1
	v_mul_f32_e32 v88, v90, v60
	v_mul_f32_e32 v89, v91, v68
	v_bfe_u32 v52, v82, 16, 1
	v_bfe_u32 v64, v86, 16, 1
	v_add3_u32 v42, v42, v56, s76
	v_bfe_u32 v44, v88, 16, 1
	v_add3_u32 v52, v82, v52, s76
	v_add3_u32 v64, v86, v64, s76
	v_lshrrev_b32_e32 v42, 16, v42
	v_add3_u32 v44, v88, v44, s76
	v_lshrrev_b32_e32 v56, 16, v64
	v_and_or_b32 v86, v52, s77, v42
	v_mov_b32_e32 v52, v45
	v_mov_b32_e32 v68, v61
	v_and_or_b32 v88, v44, s77, v56
	v_mov_b32_e32 v56, v49
	v_pk_mul_f32 v[44:45], v[52:53], v[92:93]
	v_mov_b32_e32 v72, v65
	v_pk_mul_f32 v[52:53], v[68:69], v[90:91]
	v_cvt_pk_bf16_f32 v89, v87, v89
	v_cvt_pk_bf16_f32 v87, v43, v83
	v_pk_mul_f32 v[42:43], v[56:57], v[76:77]
	v_pk_mul_f32 v[48:49], v[72:73], v[80:81]
	v_bfe_u32 v2, v53, 16, 1
	v_bfe_u32 v56, v52, 16, 1
	v_bfe_u32 v57, v45, 16, 1
	v_bfe_u32 v60, v44, 16, 1
	v_add3_u32 v60, v44, v60, s76
	v_add3_u32 v57, v45, v57, s76
	v_add3_u32 v44, v52, v56, s76
	v_add3_u32 v2, v53, v2, s76
	v_bfe_u32 v45, v42, 16, 1
	v_bfe_u32 v52, v43, 16, 1
	v_bfe_u32 v53, v48, 16, 1
	v_bfe_u32 v56, v49, 16, 1
	v_add3_u32 v49, v49, v56, s76
	v_add3_u32 v48, v48, v53, s76
	v_add3_u32 v43, v43, v52, s76
	v_add3_u32 v42, v42, v45, s76
	v_lshrrev_b32_e32 v42, 16, v42
	v_lshrrev_b32_e32 v43, 16, v43
	v_lshrrev_b32_e32 v48, 16, v48
	v_lshrrev_b32_e32 v45, 16, v49
	v_and_or_b32 v45, v2, s77, v45
	v_and_or_b32 v44, v44, s77, v48
	v_and_or_b32 v43, v57, s77, v43
	v_and_or_b32 v42, v60, s77, v42
	global_store_dwordx4 v[84:85], v[42:45], off offset:1600
	s_nop 1
	v_mul_f32_e32 v44, v92, v46
	s_nop 1
	v_mul_f32_e32 v45, v93, v54
	v_mul_f32_e32 v52, v90, v62
	v_mul_f32_e32 v53, v91, v70
	v_mul_f32_e32 v42, v76, v50
	v_mul_f32_e32 v43, v77, v58
	v_mul_f32_e32 v48, v80, v66
	v_mul_f32_e32 v49, v81, v74
	v_bfe_u32 v50, v45, 16, 1
	v_bfe_u32 v54, v44, 16, 1
	v_add3_u32 v54, v44, v54, s76
	v_add3_u32 v50, v45, v50, s76
	v_bfe_u32 v45, v42, 16, 1
	v_bfe_u32 v46, v43, 16, 1
	v_add3_u32 v43, v43, v46, s76
	v_add3_u32 v42, v42, v45, s76
	v_lshrrev_b32_e32 v42, 16, v42
	v_lshrrev_b32_e32 v43, 16, v43
	v_mov_b32_e32 v70, v63
	v_cvt_pk_bf16_f32 v45, v49, v53
	v_cvt_pk_bf16_f32 v44, v48, v52
	v_and_or_b32 v43, v50, s77, v43
	v_and_or_b32 v42, v54, s77, v42
	v_mov_b32_e32 v54, v47
	v_mov_b32_e32 v74, v67
	v_pk_mul_f32 v[48:49], v[70:71], v[90:91]
	global_store_dwordx4 v[84:85], v[42:45], off offset:3136
	v_mov_b32_e32 v58, v51
	v_pk_mul_f32 v[46:47], v[74:75], v[80:81]
	v_pk_mul_f32 v[44:45], v[54:55], v[92:93]
	v_bfe_u32 v2, v49, 16, 1
	v_pk_mul_f32 v[42:43], v[58:59], v[76:77]
	v_bfe_u32 v50, v48, 16, 1
	v_bfe_u32 v51, v45, 16, 1
	v_bfe_u32 v52, v44, 16, 1
	v_add3_u32 v2, v49, v2, s76
	v_bfe_u32 v49, v46, 16, 1
	v_add3_u32 v52, v44, v52, s76
	v_add3_u32 v51, v45, v51, s76
	v_add3_u32 v44, v48, v50, s76
	v_bfe_u32 v45, v42, 16, 1
	v_bfe_u32 v48, v43, 16, 1
	v_bfe_u32 v50, v47, 16, 1
	v_add3_u32 v46, v46, v49, s76
	v_add3_u32 v47, v47, v50, s76
	v_add3_u32 v43, v43, v48, s76
	v_add3_u32 v42, v42, v45, s76
	v_lshrrev_b32_e32 v46, 16, v46
	v_lshrrev_b32_e32 v42, 16, v42
	v_lshrrev_b32_e32 v43, 16, v43
	v_lshrrev_b32_e32 v45, 16, v47
	v_and_or_b32 v44, v44, s77, v46
	v_add_co_u32_e32 v46, vcc, s69, v84
	v_and_or_b32 v45, v2, s77, v45
	v_and_or_b32 v43, v51, s77, v43
	v_and_or_b32 v42, v52, s77, v42
	v_addc_co_u32_e32 v47, vcc, 0, v85, vcc
	global_store_dwordx4 v[46:47], v[42:45], off offset:576
	s_waitcnt vmcnt(6)
	s_waitcnt vmcnt(4)
	v_mul_f32_e32 v42, v4, v12
	v_mul_f32_e32 v43, v5, v20
	v_mul_f32_e32 v48, v40, v28
	v_mul_f32_e32 v49, v41, v36
	s_waitcnt vmcnt(3)
	v_mul_f32_e32 v44, v78, v8
	v_mul_f32_e32 v45, v79, v16
	v_mul_f32_e32 v50, v6, v24
	v_mul_f32_e32 v51, v7, v32
	v_bfe_u32 v24, v43, 16, 1
	v_bfe_u32 v12, v45, 16, 1
	v_add3_u32 v24, v43, v24, s76
	v_add3_u32 v12, v45, v12, s76
	v_lshrrev_b32_e32 v24, 16, v24
	v_cvt_pk_bf16_f32 v45, v49, v51
	v_cvt_pk_bf16_f32 v42, v42, v44
	v_mov_b32_e32 v20, v13
	v_mov_b32_e32 v32, v25
	v_and_or_b32 v43, v12, s77, v24
	v_pk_mul_f32 v[12:13], v[20:21], v[4:5]
	v_mov_b32_e32 v16, v9
	v_pk_mul_f32 v[20:21], v[32:33], v[6:7]
	v_cvt_pk_bf16_f32 v44, v48, v50
	v_pk_mul_f32 v[8:9], v[16:17], v[78:79]
	v_mov_b32_e32 v36, v29
	v_bfe_u32 v2, v21, 16, 1
	v_pk_mul_f32 v[16:17], v[36:37], v[40:41]
	v_add3_u32 v2, v21, v2, s76
	v_bfe_u32 v28, v17, 16, 1
	global_store_dwordx4 v[84:85], v[42:45], off offset:96
	v_add3_u32 v17, v17, v28, s76
	s_nop 1
	v_cvt_pk_bf16_f32 v43, v13, v9
	v_cvt_pk_bf16_f32 v42, v12, v8
	v_lshrrev_b32_e32 v17, 16, v17
	v_cvt_pk_bf16_f32 v44, v16, v20
	v_mul_f32_e32 v12, v78, v10
	v_mul_f32_e32 v13, v79, v18
	v_and_or_b32 v45, v2, s77, v17
	v_mul_f32_e32 v8, v4, v14
	v_mul_f32_e32 v9, v5, v22
	v_mul_f32_e32 v20, v6, v26
	v_mul_f32_e32 v21, v7, v34
	v_bfe_u32 v14, v13, 16, 1
	v_bfe_u32 v18, v12, 16, 1
	v_mul_f32_e32 v16, v40, v30
	v_mul_f32_e32 v17, v41, v38
	v_add3_u32 v12, v12, v18, s76
	v_add3_u32 v13, v13, v14, s76
	v_bfe_u32 v14, v8, 16, 1
	v_bfe_u32 v18, v9, 16, 1
	v_add3_u32 v9, v9, v18, s76
	v_add3_u32 v8, v8, v14, s76
	v_lshrrev_b32_e32 v8, 16, v8
	v_lshrrev_b32_e32 v9, 16, v9
	v_mov_b32_e32 v18, v11
	v_mov_b32_e32 v34, v27
	global_store_dwordx4 v[84:85], v[42:45], off offset:1632
	s_nop 1
	v_and_or_b32 v43, v13, s77, v9
	s_nop 1
	v_and_or_b32 v42, v12, s77, v8
	v_mov_b32_e32 v22, v15
	v_pk_mul_f32 v[8:9], v[18:19], v[78:79]
	v_mov_b32_e32 v38, v31
	v_pk_mul_f32 v[6:7], v[34:35], v[6:7]
	v_cvt_pk_bf16_f32 v45, v17, v21
	v_cvt_pk_bf16_f32 v44, v16, v20
	v_pk_mul_f32 v[4:5], v[22:23], v[4:5]
	v_pk_mul_f32 v[10:11], v[38:39], v[40:41]
	v_bfe_u32 v2, v7, 16, 1
	v_bfe_u32 v14, v8, 16, 1
	v_add3_u32 v8, v8, v14, s76
	v_add3_u32 v2, v7, v2, s76
	v_bfe_u32 v7, v4, 16, 1
	v_bfe_u32 v14, v11, 16, 1
	v_add3_u32 v11, v11, v14, s76
	v_add3_u32 v4, v4, v7, s76
	v_lshrrev_b32_e32 v4, 16, v4
	v_lshrrev_b32_e32 v7, 16, v11
	v_and_or_b32 v7, v2, s77, v7
	v_cvt_pk_bf16_f32 v6, v10, v6
	v_cvt_pk_bf16_f32 v5, v5, v9
	v_and_or_b32 v4, v8, s77, v4
	global_store_dwordx4 v[84:85], v[86:89], off offset:64
	global_store_dwordx4 v[84:85], v[42:45], off offset:3168
	global_store_dwordx4 v[46:47], v[4:7], off offset:608
	s_mov_b64 s[16:17], 0
.LBB0_487:
	s_and_b64 vcc, exec, s[16:17]
	s_cbranch_vccz .LBB0_489
	s_mov_b64 s[16:17], s[0:1]
	s_load_dwordx2 s[26:27], s[16:17], 0x78
	s_mov_b64 s[16:17], s[0:1]
	s_load_dwordx2 s[60:61], s[16:17], 0xa8
	s_mov_b64 s[16:17], s[0:1]
	s_load_dwordx2 s[16:17], s[16:17], 0x20
	s_waitcnt lgkmcnt(0)
	s_add_u32 s16, s16, 0x1000
	s_addc_u32 s17, s17, 0
	s_add_i32 s24, s23, 32
	s_and_b32 s62, s24, 0xff
	s_mulk_i32 s62, 0xab
	s_lshr_b32 s62, s62, 10
	s_mul_i32 s63, s62, 6
	s_sub_i32 s24, s24, s63
	s_and_b32 s24, s24, 0xff
	v_lshl_or_b32 v6, s24, 7, v155
	v_lshlrev_b32_e32 v2, 11, v6
	v_lshl_add_u64 v[4:5], s[60:61], 0, v[2:3]
	s_lshl_b32 s24, s62, 7
	v_lshl_add_u64 v[4:5], v[4:5], 0, s[24:25]
	v_lshlrev_b32_e32 v2, 1, v116
	s_waitcnt vmcnt(4)
	v_lshl_add_u64 v[96:97], v[4:5], 0, v[2:3]
	v_lshl_or_b32 v78, s62, 6, v116
	v_lshlrev_b32_e32 v2, 2, v6
	v_lshl_add_u64 v[76:77], s[26:27], 0, v[2:3]
	v_mul_u32_u24_e32 v2, 0x300, v78
	v_lshlrev_b32_e32 v2, 2, v2
	v_mad_u64_u32 v[4:5], s[26:27], v78, s68, v[76:77]
	v_lshl_add_u64 v[74:75], v[76:77], 0, v[2:3]
	global_load_dwordx4 v[48:51], v[4:5], off nt
	global_load_dwordx4 v[44:47], v[74:75], off offset:3072 nt
	v_add_co_u32_e32 v4, vcc, s69, v74
	s_movk_i32 s24, 0x3000
	s_nop 0
	v_addc_co_u32_e32 v5, vcc, 0, v75, vcc
	v_add_co_u32_e32 v6, vcc, s81, v74
	v_lshlrev_b32_e32 v2, 2, v78
	s_nop 0
	v_addc_co_u32_e32 v7, vcc, 0, v75, vcc
	global_load_dwordx4 v[56:59], v[4:5], off offset:2048 nt
	global_load_dwordx4 v[52:55], v[6:7], off offset:1024 nt
	v_add_co_u32_e32 v4, vcc, s24, v74
	global_load_dwordx4 v[60:63], v2, s[16:17] offset:16
	global_load_dwordx4 v[68:71], v2, s[16:17]
	v_addc_co_u32_e32 v5, vcc, 0, v75, vcc
	global_load_dwordx4 v[80:83], v[4:5], off nt
	global_load_dwordx4 v[64:67], v[4:5], off offset:3072 nt
	v_add_co_u32_e32 v4, vcc, s70, v74
	s_mov_b32 s24, 0xc000
	s_nop 0
	v_addc_co_u32_e32 v5, vcc, 0, v75, vcc
	global_load_dwordx4 v[84:87], v[4:5], off offset:2048 nt
	v_add_co_u32_e32 v4, vcc, s82, v74
	v_or_b32_e32 v2, 16, v78
	s_nop 0
	v_addc_co_u32_e32 v5, vcc, 0, v75, vcc
	global_load_dwordx4 v[88:91], v[4:5], off offset:1024 nt
	v_add_co_u32_e32 v14, vcc, s24, v74
	s_mov_b32 s24, 0xd000
	s_nop 0
	v_addc_co_u32_e32 v15, vcc, 0, v75, vcc
	v_add_co_u32_e32 v16, vcc, s24, v74
	s_mov_b32 s24, 0xe000
	s_nop 0
	v_addc_co_u32_e32 v17, vcc, 0, v75, vcc
	v_add_co_u32_e32 v18, vcc, s24, v74
	s_mov_b32 s24, 0xf000
	s_nop 0
	v_addc_co_u32_e32 v19, vcc, 0, v75, vcc
	v_add_co_u32_e32 v28, vcc, s24, v74
	s_mov_b32 s24, 0x10000
	s_nop 0
	v_addc_co_u32_e32 v29, vcc, 0, v75, vcc
	v_add_co_u32_e32 v30, vcc, s24, v74
	v_lshlrev_b32_e32 v8, 2, v2
	s_mov_b64 s[26:27], 0x5000000
	v_addc_co_u32_e32 v31, vcc, 0, v75, vcc
	global_load_dwordx4 v[4:7], v8, s[16:17] offset:16
	s_nop 0
	global_load_dwordx4 v[8:11], v8, s[16:17]
	v_lshl_add_u64 v[72:73], v[96:97], 0, s[26:27]
	v_mad_u64_u32 v[12:13], s[26:27], v2, s68, v[76:77]
	v_add_co_u32_e32 v92, vcc, s83, v74
	s_mov_b32 s24, 0x5001000
	s_nop 0
	v_addc_co_u32_e32 v93, vcc, 0, v75, vcc
	global_load_dwordx4 v[20:23], v[12:13], off nt
	global_load_dwordx4 v[32:35], v[14:15], off offset:3072 nt
	global_load_dwordx4 v[40:43], v[16:17], off offset:2048 nt
	global_load_dwordx4 v[36:39], v[18:19], off offset:1024 nt
	global_load_dwordx4 v[24:27], v[28:29], off nt
	s_nop 0
	global_load_dwordx4 v[12:15], v[28:29], off offset:3072 nt
	s_nop 0
	global_load_dwordx4 v[28:31], v[30:31], off offset:2048 nt
	s_nop 0
	global_load_dwordx4 v[16:19], v[92:93], off offset:1024 nt
	s_waitcnt vmcnt(19)
	s_waitcnt vmcnt(18)
	v_mov_b32_e32 v94, v44
	s_waitcnt vmcnt(17)
	s_waitcnt vmcnt(16)
	v_mov_b32_e32 v95, v52
	s_waitcnt vmcnt(15)
	v_mov_b32_e32 v101, v62
	v_mov_b32_e32 v62, v61
	s_waitcnt vmcnt(14)
	v_mov_b32_e32 v98, v68
	v_mov_b32_e32 v99, v70
	s_waitcnt vmcnt(12)
	v_mov_b32_e32 v102, v64
	v_mov_b32_e32 v70, v69
	v_mov_b32_e32 v100, v60
	v_mul_f32_e32 v92, v98, v48
	v_mul_f32_e32 v93, v99, v56
	v_pk_mul_f32 v[68:69], v[94:95], v[70:71]
	s_waitcnt vmcnt(11)
	v_mul_f32_e32 v94, v100, v80
	v_mul_f32_e32 v95, v101, v84
	v_bfe_u32 v56, v94, 16, 1
	s_waitcnt vmcnt(10)
	v_mov_b32_e32 v103, v88
	v_pk_mul_f32 v[60:61], v[102:103], v[62:63]
	v_add3_u32 v56, v94, v56, s76
	v_bfe_u32 v44, v60, 16, 1
	v_add3_u32 v44, v60, v44, s76
	v_lshrrev_b32_e32 v56, 16, v56
	v_cvt_pk_bf16_f32 v92, v92, v68
	v_mov_b32_e32 v52, v45
	v_and_or_b32 v94, v44, s77, v56
	v_mov_b32_e32 v56, v49
	v_pk_mul_f32 v[44:45], v[52:53], v[70:71]
	v_mov_b32_e32 v88, v65
	v_cvt_pk_bf16_f32 v93, v93, v69
	v_pk_mul_f32 v[48:49], v[56:57], v[98:99]
	v_mov_b32_e32 v84, v81
	v_pk_mul_f32 v[56:57], v[88:89], v[62:63]
	v_cvt_pk_bf16_f32 v95, v95, v61
	v_pk_mul_f32 v[52:53], v[84:85], v[100:101]
	v_bfe_u32 v2, v57, 16, 1
	v_add_co_u32_e32 v60, vcc, s24, v96
	v_add3_u32 v2, v57, v2, s76
	v_bfe_u32 v64, v53, 16, 1
	v_addc_co_u32_e32 v61, vcc, 0, v97, vcc
	v_add3_u32 v53, v53, v64, s76
	global_store_dwordx4 v[60:61], v[92:95], off offset:-4096
	v_lshrrev_b32_e32 v53, 16, v53
	s_nop 1
	v_cvt_pk_bf16_f32 v93, v49, v45
	v_cvt_pk_bf16_f32 v92, v48, v44
	v_and_or_b32 v95, v2, s77, v53
	v_cvt_pk_bf16_f32 v94, v52, v56
	v_mul_f32_e32 v48, v70, v46
	v_mul_f32_e32 v49, v71, v54
	v_mov_b32_e32 v44, v50
	v_mul_f32_e32 v52, v100, v82
	v_mul_f32_e32 v53, v101, v86
	v_mul_f32_e32 v56, v62, v66
	v_mul_f32_e32 v57, v63, v90
	v_bfe_u32 v50, v49, 16, 1
	v_mul_f32_e32 v44, v98, v44
	v_mul_f32_e32 v45, v99, v58
	v_bfe_u32 v2, v57, 16, 1
	v_bfe_u32 v46, v56, 16, 1
	v_add3_u32 v49, v49, v50, s76
	v_bfe_u32 v50, v52, 16, 1
	v_add3_u32 v46, v56, v46, s76
	v_add3_u32 v2, v57, v2, s76
	v_bfe_u32 v54, v53, 16, 1
	v_bfe_u32 v57, v45, 16, 1
	v_add3_u32 v50, v52, v50, s76
	v_add3_u32 v53, v53, v54, s76
	v_add3_u32 v45, v45, v57, s76
	v_lshrrev_b32_e32 v50, 16, v50
	v_mov_b32_e32 v54, v47
	v_mov_b32_e32 v90, v67
	global_store_dwordx4 v[72:73], v[92:95], off offset:2048
	v_lshrrev_b32_e32 v52, 16, v53
	v_lshrrev_b32_e32 v45, 16, v45
	v_and_or_b32 v94, v46, s77, v50
	v_mov_b32_e32 v58, v51
	v_pk_mul_f32 v[46:47], v[54:55], v[70:71]
	v_mov_b32_e32 v86, v83
	v_pk_mul_f32 v[50:51], v[90:91], v[62:63]
	v_and_or_b32 v95, v2, s77, v52
	v_and_or_b32 v93, v49, s77, v45
	v_cvt_pk_bf16_f32 v92, v44, v48
	v_pk_mul_f32 v[44:45], v[58:59], v[98:99]
	v_pk_mul_f32 v[48:49], v[86:87], v[100:101]
	v_bfe_u32 v2, v51, 16, 1
	v_bfe_u32 v52, v50, 16, 1
	v_bfe_u32 v53, v47, 16, 1
	v_bfe_u32 v54, v46, 16, 1
	v_add3_u32 v50, v50, v52, s76
	v_add3_u32 v2, v51, v2, s76
	v_add3_u32 v51, v46, v54, s76
	v_add3_u32 v52, v47, v53, s76
	v_bfe_u32 v46, v48, 16, 1
	v_bfe_u32 v47, v49, 16, 1
	v_bfe_u32 v53, v44, 16, 1
	v_bfe_u32 v54, v45, 16, 1
	v_add3_u32 v47, v49, v47, s76
	v_add3_u32 v46, v48, v46, s76
	v_add3_u32 v45, v45, v54, s76
	v_add3_u32 v44, v44, v53, s76
	v_lshrrev_b32_e32 v46, 16, v46
	v_lshrrev_b32_e32 v47, 16, v47
	v_lshrrev_b32_e32 v44, 16, v44
	v_lshrrev_b32_e32 v45, 16, v45
	v_and_or_b32 v47, v2, s77, v47
	v_and_or_b32 v46, v50, s77, v46
	v_and_or_b32 v45, v52, s77, v45
	v_and_or_b32 v44, v51, s77, v44
	global_store_dwordx4 v[60:61], v[44:47], off offset:2048
	s_waitcnt vmcnt(11)
	v_mov_b32_e32 v49, v10
	v_mov_b32_e32 v10, v9
	s_waitcnt vmcnt(9)
	v_mov_b32_e32 v46, v32
	s_waitcnt vmcnt(7)
	v_mov_b32_e32 v47, v36
	v_mov_b32_e32 v48, v8
	v_pk_mul_f32 v[8:9], v[46:47], v[10:11]
	v_mov_b32_e32 v51, v6
	s_waitcnt vmcnt(5)
	v_mov_b32_e32 v52, v12
	s_waitcnt vmcnt(3)
	v_mov_b32_e32 v53, v16
	v_mov_b32_e32 v6, v5
	v_mul_f32_e32 v44, v48, v20
	v_mul_f32_e32 v45, v49, v40
	v_mov_b32_e32 v50, v4
	v_pk_mul_f32 v[4:5], v[52:53], v[6:7]
	v_bfe_u32 v16, v9, 16, 1
	v_mul_f32_e32 v46, v50, v24
	v_mul_f32_e32 v47, v51, v28
	v_bfe_u32 v2, v5, 16, 1
	v_add3_u32 v9, v9, v16, s76
	v_bfe_u32 v20, v45, 16, 1
	v_add3_u32 v2, v5, v2, s76
	v_bfe_u32 v12, v47, 16, 1
	v_add3_u32 v20, v45, v20, s76
	v_add3_u32 v12, v47, v12, s76
	v_lshrrev_b32_e32 v20, 16, v20
	v_mov_b32_e32 v36, v33
	v_lshrrev_b32_e32 v12, 16, v12
	v_and_or_b32 v45, v9, s77, v20
	v_cvt_pk_bf16_f32 v44, v44, v8
	v_mov_b32_e32 v40, v21
	v_pk_mul_f32 v[8:9], v[36:37], v[10:11]
	v_mov_b32_e32 v16, v13
	v_and_or_b32 v47, v2, s77, v12
	v_cvt_pk_bf16_f32 v46, v46, v4
	v_pk_mul_f32 v[4:5], v[40:41], v[48:49]
	v_mov_b32_e32 v28, v25
	v_pk_mul_f32 v[12:13], v[16:17], v[6:7]
	v_pk_mul_f32 v[20:21], v[28:29], v[50:51]
	v_bfe_u32 v16, v12, 16, 1
	v_bfe_u32 v2, v13, 16, 1
	v_add3_u32 v12, v12, v16, s76
	v_bfe_u32 v16, v21, 16, 1
	v_add3_u32 v2, v13, v2, s76
	v_bfe_u32 v13, v20, 16, 1
	v_add3_u32 v16, v21, v16, s76
	global_store_dwordx4 v[72:73], v[44:47], off offset:32
	v_add3_u32 v13, v20, v13, s76
	v_lshrrev_b32_e32 v16, 16, v16
	v_cvt_pk_bf16_f32 v45, v5, v9
	v_cvt_pk_bf16_f32 v44, v4, v8
	v_lshrrev_b32_e32 v13, 16, v13
	v_and_or_b32 v47, v2, s77, v16
	v_mul_f32_e32 v8, v10, v34
	v_mul_f32_e32 v9, v11, v38
	v_and_or_b32 v46, v12, s77, v13
	v_mul_f32_e32 v4, v48, v22
	v_mul_f32_e32 v5, v49, v42
	v_mul_f32_e32 v16, v6, v14
	v_mul_f32_e32 v17, v7, v18
	v_bfe_u32 v18, v9, 16, 1
	v_bfe_u32 v20, v8, 16, 1
	v_mul_f32_e32 v12, v50, v26
	v_mul_f32_e32 v13, v51, v30
	v_add3_u32 v8, v8, v20, s76
	v_add3_u32 v9, v9, v18, s76
	v_bfe_u32 v18, v4, 16, 1
	v_bfe_u32 v20, v5, 16, 1
	v_add3_u32 v5, v5, v20, s76
	v_add3_u32 v4, v4, v18, s76
	v_lshrrev_b32_e32 v4, 16, v4
	v_lshrrev_b32_e32 v5, 16, v5
	v_mov_b32_e32 v38, v35
	v_mov_b32_e32 v18, v15
	global_store_dwordx4 v[72:73], v[44:47], off offset:2080
	s_nop 1
	v_and_or_b32 v45, v9, s77, v5
	s_nop 1
	v_and_or_b32 v44, v8, s77, v4
	v_mov_b32_e32 v42, v23
	v_pk_mul_f32 v[8:9], v[38:39], v[10:11]
	v_mov_b32_e32 v30, v27
	v_pk_mul_f32 v[6:7], v[18:19], v[6:7]
	v_cvt_pk_bf16_f32 v47, v13, v17
	v_cvt_pk_bf16_f32 v46, v12, v16
	v_pk_mul_f32 v[4:5], v[42:43], v[48:49]
	v_pk_mul_f32 v[10:11], v[30:31], v[50:51]
	v_bfe_u32 v2, v7, 16, 1
	v_bfe_u32 v12, v6, 16, 1
	v_add3_u32 v6, v6, v12, s76
	v_add3_u32 v2, v7, v2, s76
	v_bfe_u32 v7, v10, 16, 1
	v_bfe_u32 v12, v11, 16, 1
	v_add3_u32 v11, v11, v12, s76
	v_add3_u32 v7, v10, v7, s76
	v_lshrrev_b32_e32 v10, 16, v7
	v_lshrrev_b32_e32 v7, 16, v11
	v_and_or_b32 v7, v2, s77, v7
	v_and_or_b32 v6, v6, s77, v10
	v_cvt_pk_bf16_f32 v5, v5, v9
	v_cvt_pk_bf16_f32 v4, v4, v8
	s_mov_b32 s24, 0x18000
	global_store_dwordx4 v[60:61], v[4:7], off offset:2080
	v_or_b32_e32 v2, 32, v78
	global_store_dwordx4 v[60:61], v[92:95], off
	v_add_co_u32_e32 v6, vcc, s24, v74
	global_store_dwordx4 v[60:61], v[44:47], off offset:32
	v_mad_u64_u32 v[4:5], s[26:27], v2, s68, v[76:77]
	v_addc_co_u32_e32 v7, vcc, 0, v75, vcc
	s_mov_b32 s24, 0x19000
	global_load_dwordx4 v[44:47], v[4:5], off nt
	global_load_dwordx4 v[48:51], v[6:7], off offset:3072 nt
	v_add_co_u32_e32 v4, vcc, s24, v74
	s_mov_b32 s24, 0x1a000
	s_nop 0
	v_addc_co_u32_e32 v5, vcc, 0, v75, vcc
	v_add_co_u32_e32 v6, vcc, s24, v74
	s_mov_b32 s24, 0x1b000
	s_nop 0
	v_addc_co_u32_e32 v7, vcc, 0, v75, vcc
	global_load_dwordx4 v[52:55], v[4:5], off offset:2048 nt
	global_load_dwordx4 v[56:59], v[6:7], off offset:1024 nt
	v_add_co_u32_e32 v4, vcc, s24, v74
	v_lshlrev_b32_e32 v2, 2, v2
	s_nop 0
	v_addc_co_u32_e32 v5, vcc, 0, v75, vcc
	s_mov_b32 s24, 0x1c000
	global_load_dwordx4 v[62:65], v2, s[16:17] offset:16
	global_load_dwordx4 v[66:69], v2, s[16:17]
	global_load_dwordx4 v[80:83], v[4:5], off nt
	global_load_dwordx4 v[84:87], v[4:5], off offset:3072 nt
	v_add_co_u32_e32 v4, vcc, s24, v74
	s_mov_b32 s24, 0x1d000
	s_nop 0
	v_addc_co_u32_e32 v5, vcc, 0, v75, vcc
	global_load_dwordx4 v[88:91], v[4:5], off offset:2048 nt
	v_add_co_u32_e32 v4, vcc, s24, v74
	s_mov_b32 s24, 0x24000
	s_nop 0
	v_addc_co_u32_e32 v5, vcc, 0, v75, vcc
	global_load_dwordx4 v[92:95], v[4:5], off offset:1024 nt
	v_add_co_u32_e32 v6, vcc, s24, v74
	s_mov_b32 s24, 0x26000
	s_nop 0
	v_addc_co_u32_e32 v7, vcc, 0, v75, vcc
	v_add_co_u32_e32 v12, vcc, s84, v74
	v_or_b32_e32 v2, 48, v78
	s_nop 0
	v_addc_co_u32_e32 v13, vcc, 0, v75, vcc
	v_add_co_u32_e32 v14, vcc, s24, v74
	s_mov_b32 s24, 0x28000
	s_nop 0
	v_addc_co_u32_e32 v15, vcc, 0, v75, vcc
	v_add_co_u32_e32 v16, vcc, s85, v74
	v_mad_u64_u32 v[4:5], s[26:27], v2, s68, v[76:77]
	s_nop 0
	v_addc_co_u32_e32 v17, vcc, 0, v75, vcc
	v_add_co_u32_e32 v28, vcc, s24, v74
	s_mov_b32 s24, 0x29000
	s_nop 0
	v_addc_co_u32_e32 v29, vcc, 0, v75, vcc
	v_add_co_u32_e32 v30, vcc, s24, v74
	v_lshlrev_b32_e32 v2, 2, v2
	s_nop 0
	v_addc_co_u32_e32 v31, vcc, 0, v75, vcc
	global_load_dwordx4 v[8:11], v[4:5], off nt
	s_nop 0
	global_load_dwordx4 v[4:7], v[6:7], off offset:3072 nt
	s_nop 0
	global_load_dwordx4 v[20:23], v[12:13], off offset:2048 nt
	s_nop 0
	global_load_dwordx4 v[12:15], v[14:15], off offset:1024 nt
	s_nop 0
	global_load_dwordx4 v[24:27], v[16:17], off nt
	s_nop 0
	global_load_dwordx4 v[16:19], v[16:17], off offset:3072 nt
	s_nop 0
	global_load_dwordx4 v[32:35], v[28:29], off offset:2048 nt
	s_nop 0
	global_load_dwordx4 v[28:31], v[30:31], off offset:1024 nt
	s_nop 0
	global_load_dwordx4 v[36:39], v2, s[16:17] offset:16
	global_load_dwordx4 v[40:43], v2, s[16:17]
	s_waitcnt vmcnt(19)
	s_waitcnt vmcnt(18)
	v_mov_b32_e32 v74, v48
	s_waitcnt vmcnt(17)
	s_waitcnt vmcnt(16)
	v_mov_b32_e32 v75, v56
	s_waitcnt vmcnt(15)
	v_mov_b32_e32 v96, v62
	s_waitcnt vmcnt(14)
	v_mov_b32_e32 v79, v68
	v_mov_b32_e32 v68, v67
	v_mov_b32_e32 v78, v66
	v_pk_mul_f32 v[66:67], v[74:75], v[68:69]
	s_waitcnt vmcnt(13)
	v_mov_b32_e32 v97, v64
	s_waitcnt vmcnt(12)
	v_mov_b32_e32 v76, v84
	s_waitcnt vmcnt(11)
	v_mov_b32_e32 v64, v63
	v_mul_f32_e32 v74, v96, v80
	v_mul_f32_e32 v75, v97, v88
	v_mul_f32_e32 v70, v78, v44
	v_mul_f32_e32 v71, v79, v52
	v_bfe_u32 v56, v74, 16, 1
	s_waitcnt vmcnt(10)
	v_mov_b32_e32 v77, v92
	v_pk_mul_f32 v[62:63], v[76:77], v[64:65]
	v_bfe_u32 v2, v63, 16, 1
	v_bfe_u32 v44, v62, 16, 1
	v_add3_u32 v2, v63, v2, s76
	v_add3_u32 v56, v74, v56, s76
	v_add3_u32 v44, v62, v44, s76
	v_lshrrev_b32_e32 v56, 16, v56
	v_bfe_u32 v62, v75, 16, 1
	v_and_or_b32 v76, v44, s77, v56
	v_mov_b32_e32 v56, v49
	v_add3_u32 v62, v75, v62, s76
	v_cvt_pk_bf16_f32 v75, v71, v67
	v_cvt_pk_bf16_f32 v74, v70, v66
	v_mov_b32_e32 v52, v45
	v_pk_mul_f32 v[48:49], v[56:57], v[68:69]
	v_mov_b32_e32 v92, v85
	v_lshrrev_b32_e32 v62, 16, v62
	v_pk_mul_f32 v[44:45], v[52:53], v[78:79]
	v_mov_b32_e32 v88, v81
	v_pk_mul_f32 v[56:57], v[92:93], v[64:65]
	v_and_or_b32 v77, v2, s77, v62
	v_pk_mul_f32 v[52:53], v[88:89], v[96:97]
	v_bfe_u32 v2, v57, 16, 1
	v_add3_u32 v2, v57, v2, s76
	v_bfe_u32 v62, v53, 16, 1
	v_add3_u32 v53, v53, v62, s76
	global_store_dwordx4 v[72:73], v[74:77], off offset:64
	v_lshrrev_b32_e32 v53, 16, v53
	s_nop 1
	v_cvt_pk_bf16_f32 v75, v45, v49
	v_cvt_pk_bf16_f32 v74, v44, v48
	v_and_or_b32 v77, v2, s77, v53
	v_cvt_pk_bf16_f32 v76, v52, v56
	v_mul_f32_e32 v48, v68, v50
	v_mul_f32_e32 v49, v69, v58
	v_mul_f32_e32 v52, v96, v82
	v_mul_f32_e32 v53, v97, v90
	v_mul_f32_e32 v56, v64, v86
	v_mul_f32_e32 v57, v65, v94
	v_bfe_u32 v50, v49, 16, 1
	v_mul_f32_e32 v44, v78, v46
	v_mul_f32_e32 v45, v79, v54
	v_bfe_u32 v2, v57, 16, 1
	v_bfe_u32 v46, v56, 16, 1
	v_bfe_u32 v54, v48, 16, 1
	v_add3_u32 v49, v49, v50, s76
	v_bfe_u32 v50, v52, 16, 1
	v_add3_u32 v48, v48, v54, s76
	v_add3_u32 v46, v56, v46, s76
	v_add3_u32 v2, v57, v2, s76
	v_bfe_u32 v54, v53, 16, 1
	v_bfe_u32 v56, v44, 16, 1
	v_bfe_u32 v57, v45, 16, 1
	v_add3_u32 v50, v52, v50, s76
	v_add3_u32 v53, v53, v54, s76
	v_add3_u32 v45, v45, v57, s76
	v_add3_u32 v44, v44, v56, s76
	v_lshrrev_b32_e32 v50, 16, v50
	v_mov_b32_e32 v58, v51
	v_mov_b32_e32 v94, v87
	global_store_dwordx4 v[72:73], v[74:77], off offset:2112
	v_lshrrev_b32_e32 v52, 16, v53
	v_lshrrev_b32_e32 v44, 16, v44
	v_lshrrev_b32_e32 v45, 16, v45
	v_and_or_b32 v76, v46, s77, v50
	v_mov_b32_e32 v54, v47
	v_pk_mul_f32 v[46:47], v[58:59], v[68:69]
	v_mov_b32_e32 v90, v83
	v_pk_mul_f32 v[50:51], v[94:95], v[64:65]
	v_and_or_b32 v77, v2, s77, v52
	v_and_or_b32 v75, v49, s77, v45
	v_and_or_b32 v74, v48, s77, v44
	v_pk_mul_f32 v[44:45], v[54:55], v[78:79]
	v_pk_mul_f32 v[48:49], v[90:91], v[96:97]
	v_bfe_u32 v2, v51, 16, 1
	v_bfe_u32 v52, v50, 16, 1
	v_bfe_u32 v53, v47, 16, 1
	v_bfe_u32 v54, v46, 16, 1
	v_add3_u32 v54, v46, v54, s76
	v_add3_u32 v53, v47, v53, s76
	v_add3_u32 v46, v50, v52, s76
	v_add3_u32 v2, v51, v2, s76
	v_bfe_u32 v47, v48, 16, 1
	v_bfe_u32 v50, v49, 16, 1
	v_bfe_u32 v51, v44, 16, 1
	v_bfe_u32 v52, v45, 16, 1
	v_add3_u32 v49, v49, v50, s76
	v_add3_u32 v47, v48, v47, s76
	v_add3_u32 v45, v45, v52, s76
	v_add3_u32 v44, v44, v51, s76
	v_lshrrev_b32_e32 v48, 16, v47
	v_lshrrev_b32_e32 v47, 16, v49
	v_lshrrev_b32_e32 v44, 16, v44
	v_lshrrev_b32_e32 v45, 16, v45
	v_and_or_b32 v47, v2, s77, v47
	v_and_or_b32 v46, v46, s77, v48
	v_and_or_b32 v45, v53, s77, v45
	v_and_or_b32 v44, v54, s77, v44
	global_store_dwordx4 v[60:61], v[44:47], off offset:2112
	s_waitcnt vmcnt(3)
	v_mov_b32_e32 v48, v40
	v_mov_b32_e32 v49, v42
	v_mov_b32_e32 v46, v4
	v_mov_b32_e32 v47, v12
	v_mov_b32_e32 v42, v41
	v_mul_f32_e32 v44, v48, v8
	v_mul_f32_e32 v45, v49, v20
	v_pk_mul_f32 v[40:41], v[46:47], v[42:43]
	v_mov_b32_e32 v50, v36
	v_mov_b32_e32 v51, v38
	v_mul_f32_e32 v46, v50, v24
	v_mul_f32_e32 v47, v51, v32
	v_mov_b32_e32 v52, v16
	v_mov_b32_e32 v53, v28
	v_mov_b32_e32 v38, v37
	v_pk_mul_f32 v[36:37], v[52:53], v[38:39]
	v_cvt_pk_bf16_f32 v44, v44, v40
	v_mov_b32_e32 v12, v5
	v_cvt_pk_bf16_f32 v47, v47, v37
	v_cvt_pk_bf16_f32 v46, v46, v36
	v_cvt_pk_bf16_f32 v45, v45, v41
	v_mov_b32_e32 v20, v9
	v_pk_mul_f32 v[4:5], v[12:13], v[42:43]
	v_mov_b32_e32 v28, v17
	v_pk_mul_f32 v[8:9], v[20:21], v[48:49]
	v_mov_b32_e32 v32, v25
	v_pk_mul_f32 v[16:17], v[28:29], v[38:39]
	v_pk_mul_f32 v[12:13], v[32:33], v[50:51]
	v_bfe_u32 v2, v17, 16, 1
	v_add3_u32 v2, v17, v2, s76
	v_bfe_u32 v20, v13, 16, 1
	v_add3_u32 v13, v13, v20, s76
	global_store_dwordx4 v[72:73], v[44:47], off offset:96
	v_lshrrev_b32_e32 v13, 16, v13
	s_nop 1
	v_cvt_pk_bf16_f32 v45, v9, v5
	v_cvt_pk_bf16_f32 v44, v8, v4
	v_and_or_b32 v47, v2, s77, v13
	v_cvt_pk_bf16_f32 v46, v12, v16
	v_mul_f32_e32 v8, v42, v6
	v_mul_f32_e32 v9, v43, v14
	v_mov_b32_e32 v4, v10
	v_mul_f32_e32 v12, v50, v26
	v_mul_f32_e32 v13, v51, v34
	v_mul_f32_e32 v16, v38, v18
	v_mul_f32_e32 v17, v39, v30
	v_bfe_u32 v10, v9, 16, 1
	v_mul_f32_e32 v4, v48, v4
	v_mul_f32_e32 v5, v49, v22
	v_bfe_u32 v2, v17, 16, 1
	v_bfe_u32 v6, v16, 16, 1
	v_add3_u32 v9, v9, v10, s76
	v_bfe_u32 v10, v12, 16, 1
	v_add3_u32 v6, v16, v6, s76
	v_add3_u32 v2, v17, v2, s76
	v_bfe_u32 v14, v13, 16, 1
	v_bfe_u32 v17, v5, 16, 1
	v_add3_u32 v10, v12, v10, s76
	v_add3_u32 v13, v13, v14, s76
	v_add3_u32 v5, v5, v17, s76
	v_lshrrev_b32_e32 v10, 16, v10
	v_mov_b32_e32 v14, v7
	v_mov_b32_e32 v30, v19
	global_store_dwordx4 v[72:73], v[44:47], off offset:2144
	v_lshrrev_b32_e32 v12, 16, v13
	v_lshrrev_b32_e32 v5, 16, v5
	v_and_or_b32 v46, v6, s77, v10
	v_mov_b32_e32 v22, v11
	v_pk_mul_f32 v[6:7], v[14:15], v[42:43]
	v_mov_b32_e32 v34, v27
	v_pk_mul_f32 v[10:11], v[30:31], v[38:39]
	v_and_or_b32 v47, v2, s77, v12
	v_and_or_b32 v45, v9, s77, v5
	v_cvt_pk_bf16_f32 v44, v4, v8
	v_pk_mul_f32 v[4:5], v[22:23], v[48:49]
	v_pk_mul_f32 v[8:9], v[34:35], v[50:51]
	v_bfe_u32 v2, v11, 16, 1
	v_bfe_u32 v12, v10, 16, 1
	v_bfe_u32 v13, v7, 16, 1
	v_bfe_u32 v14, v6, 16, 1
	v_add3_u32 v14, v6, v14, s76
	v_add3_u32 v13, v7, v13, s76
	v_add3_u32 v6, v10, v12, s76
	v_add3_u32 v2, v11, v2, s76
	v_bfe_u32 v7, v8, 16, 1
	v_bfe_u32 v10, v9, 16, 1
	v_bfe_u32 v11, v4, 16, 1
	v_bfe_u32 v12, v5, 16, 1
	v_add3_u32 v9, v9, v10, s76
	v_add3_u32 v7, v8, v7, s76
	v_add3_u32 v5, v5, v12, s76
	v_add3_u32 v4, v4, v11, s76
	v_lshrrev_b32_e32 v8, 16, v7
	v_lshrrev_b32_e32 v7, 16, v9
	v_lshrrev_b32_e32 v4, 16, v4
	v_lshrrev_b32_e32 v5, 16, v5
	v_and_or_b32 v7, v2, s77, v7
	v_and_or_b32 v6, v6, s77, v8
	v_and_or_b32 v5, v13, s77, v5
	v_and_or_b32 v4, v14, s77, v4
	global_store_dwordx4 v[60:61], v[74:77], off offset:64
	global_store_dwordx4 v[60:61], v[44:47], off offset:96
	global_store_dwordx4 v[60:61], v[4:7], off offset:2144

.LBB0_495:
	v_lshlrev_b32_e32 v2, 9, v84
	s_waitcnt vmcnt(15)
	s_waitcnt vmcnt(13)
	s_waitcnt vmcnt(11)
	s_waitcnt vmcnt(9)
	s_waitcnt lgkmcnt(0)
	v_lshl_add_u64 v[42:43], s[62:63], 0, v[2:3]
	s_lshl_b32 s24, s24, 1
	v_mul_f32_e32 v82, v76, v44
	v_mul_f32_e32 v83, v77, v52
	v_mul_f32_e32 v98, v80, v60
	v_mul_f32_e32 v99, v81, v68
	s_waitcnt vmcnt(8)
	v_lshl_add_u64 v[42:43], v[42:43], 0, s[24:25]
	v_lshlrev_b32_e32 v2, 1, v116
	v_mul_f32_e32 v96, v92, v48
	v_mul_f32_e32 v97, v93, v56
	v_mul_f32_e32 v100, v90, v64
	v_mul_f32_e32 v101, v91, v72
	v_lshl_add_u64 v[42:43], v[42:43], 0, v[2:3]
	s_mov_b64 s[60:61], 0x4f00000
	s_mov_b32 s24, 0x4f00000
	v_lshl_add_u64 v[84:85], v[42:43], 0, s[60:61]
	v_add_co_u32_e32 v42, vcc, s24, v42
	v_cvt_pk_bf16_f32 v99, v99, v101
	v_cvt_pk_bf16_f32 v98, v98, v100
	v_cvt_pk_bf16_f32 v97, v83, v97
	v_cvt_pk_bf16_f32 v96, v82, v96
	v_addc_co_u32_e32 v43, vcc, 0, v43, vcc
	v_mov_b32_e32 v52, v45
	v_mov_b32_e32 v56, v49
	v_mov_b32_e32 v72, v65
	global_store_dwordx4 v[42:43], v[96:99], off
	v_pk_mul_f32 v[42:43], v[52:53], v[76:77]
	v_pk_mul_f32 v[44:45], v[56:57], v[92:93]
	v_mov_b32_e32 v68, v61
	v_pk_mul_f32 v[52:53], v[72:73], v[90:91]
	v_pk_mul_f32 v[48:49], v[68:69], v[80:81]
	v_bfe_u32 v2, v53, 16, 1
	v_bfe_u32 v56, v52, 16, 1
	v_bfe_u32 v57, v45, 16, 1
	v_bfe_u32 v60, v44, 16, 1
	v_add3_u32 v60, v44, v60, s76
	v_add3_u32 v57, v45, v57, s76
	v_add3_u32 v44, v52, v56, s76
	v_add3_u32 v2, v53, v2, s76
	v_bfe_u32 v45, v42, 16, 1
	v_bfe_u32 v52, v43, 16, 1
	v_bfe_u32 v53, v48, 16, 1
	v_bfe_u32 v56, v49, 16, 1
	v_add3_u32 v49, v49, v56, s76
	v_add3_u32 v48, v48, v53, s76
	v_add3_u32 v43, v43, v52, s76
	v_add3_u32 v42, v42, v45, s76
	v_lshrrev_b32_e32 v42, 16, v42
	v_lshrrev_b32_e32 v43, 16, v43
	v_lshrrev_b32_e32 v48, 16, v48
	v_lshrrev_b32_e32 v45, 16, v49
	v_and_or_b32 v45, v2, s77, v45
	v_and_or_b32 v44, v44, s77, v48
	v_and_or_b32 v43, v57, s77, v43
	v_and_or_b32 v42, v60, s77, v42
	global_store_dwordx4 v[84:85], v[42:45], off offset:512
	s_nop 1
	v_mul_f32_e32 v44, v92, v50
	s_nop 1
	v_mul_f32_e32 v45, v93, v58
	v_mul_f32_e32 v52, v90, v66
	v_mul_f32_e32 v53, v91, v74
	v_mul_f32_e32 v42, v76, v46
	v_mul_f32_e32 v43, v77, v54
	v_mul_f32_e32 v48, v80, v62
	v_mul_f32_e32 v49, v81, v70
	v_bfe_u32 v50, v45, 16, 1
	v_bfe_u32 v54, v44, 16, 1
	v_add3_u32 v54, v44, v54, s76
	v_add3_u32 v50, v45, v50, s76
	v_bfe_u32 v45, v42, 16, 1
	v_bfe_u32 v46, v43, 16, 1
	v_add3_u32 v43, v43, v46, s76
	v_add3_u32 v42, v42, v45, s76
	v_lshrrev_b32_e32 v42, 16, v42
	v_lshrrev_b32_e32 v43, 16, v43
	v_cvt_pk_bf16_f32 v45, v49, v53
	v_cvt_pk_bf16_f32 v44, v48, v52
	v_and_or_b32 v43, v50, s77, v43
	v_and_or_b32 v42, v54, s77, v42
	v_mov_b32_e32 v58, v51
	v_mov_b32_e32 v74, v67
	global_store_dwordx4 v[84:85], v[42:45], off offset:1024
	v_mov_b32_e32 v54, v47
	v_mov_b32_e32 v70, v63
	v_pk_mul_f32 v[44:45], v[58:59], v[92:93]
	v_pk_mul_f32 v[48:49], v[74:75], v[90:91]
	v_pk_mul_f32 v[42:43], v[54:55], v[76:77]
	v_pk_mul_f32 v[46:47], v[70:71], v[80:81]
	v_bfe_u32 v2, v49, 16, 1
	v_bfe_u32 v50, v48, 16, 1
	v_bfe_u32 v51, v45, 16, 1
	v_bfe_u32 v52, v44, 16, 1
	v_add3_u32 v52, v44, v52, s76
	v_add3_u32 v51, v45, v51, s76
	v_add3_u32 v44, v48, v50, s76
	v_add3_u32 v2, v49, v2, s76
	v_bfe_u32 v45, v42, 16, 1
	v_bfe_u32 v48, v43, 16, 1
	v_bfe_u32 v49, v46, 16, 1
	v_bfe_u32 v50, v47, 16, 1
	v_add3_u32 v47, v47, v50, s76
	v_add3_u32 v46, v46, v49, s76
	v_add3_u32 v43, v43, v48, s76
	v_add3_u32 v42, v42, v45, s76
	v_lshrrev_b32_e32 v42, 16, v42
	v_lshrrev_b32_e32 v43, 16, v43
	v_lshrrev_b32_e32 v46, 16, v46
	v_lshrrev_b32_e32 v45, 16, v47
	v_and_or_b32 v45, v2, s77, v45
	v_and_or_b32 v44, v44, s77, v46
	v_and_or_b32 v43, v51, s77, v43
	v_and_or_b32 v42, v52, s77, v42
	global_store_dwordx4 v[84:85], v[42:45], off offset:1536
	s_waitcnt vmcnt(7)
	s_waitcnt vmcnt(5)
	v_mul_f32_e32 v42, v4, v12
	v_mul_f32_e32 v43, v5, v20
	v_mul_f32_e32 v46, v40, v28
	v_mul_f32_e32 v47, v41, v36
	s_waitcnt vmcnt(4)
	v_mul_f32_e32 v44, v78, v8
	v_mul_f32_e32 v45, v79, v16
	v_mul_f32_e32 v48, v6, v24
	v_mul_f32_e32 v49, v7, v32
	v_bfe_u32 v24, v43, 16, 1
	v_bfe_u32 v12, v45, 16, 1
	v_add3_u32 v24, v43, v24, s76
	v_add3_u32 v12, v45, v12, s76
	v_lshrrev_b32_e32 v24, 16, v24
	v_cvt_pk_bf16_f32 v45, v47, v49
	v_cvt_pk_bf16_f32 v42, v42, v44
	v_mov_b32_e32 v20, v13
	v_mov_b32_e32 v32, v25
	v_and_or_b32 v43, v12, s77, v24
	v_pk_mul_f32 v[12:13], v[20:21], v[4:5]
	v_mov_b32_e32 v16, v9
	v_pk_mul_f32 v[20:21], v[32:33], v[6:7]
	v_cvt_pk_bf16_f32 v44, v46, v48
	v_pk_mul_f32 v[8:9], v[16:17], v[78:79]
	v_mov_b32_e32 v36, v29
	v_bfe_u32 v2, v21, 16, 1
	v_pk_mul_f32 v[16:17], v[36:37], v[40:41]
	v_add3_u32 v2, v21, v2, s76
	v_bfe_u32 v28, v17, 16, 1
	global_store_dwordx4 v[84:85], v[42:45], off offset:32
	v_add3_u32 v17, v17, v28, s76
	s_nop 1
	v_cvt_pk_bf16_f32 v43, v13, v9
	v_cvt_pk_bf16_f32 v42, v12, v8
	v_lshrrev_b32_e32 v17, 16, v17
	v_cvt_pk_bf16_f32 v44, v16, v20
	v_mul_f32_e32 v12, v78, v10
	v_mul_f32_e32 v13, v79, v18
	v_and_or_b32 v45, v2, s77, v17
	v_mul_f32_e32 v8, v4, v14
	v_mul_f32_e32 v9, v5, v22
	v_mul_f32_e32 v20, v6, v26
	v_mul_f32_e32 v21, v7, v34
	v_bfe_u32 v14, v13, 16, 1
	v_bfe_u32 v18, v12, 16, 1
	v_mul_f32_e32 v16, v40, v30
	v_mul_f32_e32 v17, v41, v38
	v_add3_u32 v12, v12, v18, s76
	v_add3_u32 v13, v13, v14, s76
	v_bfe_u32 v14, v8, 16, 1
	v_bfe_u32 v18, v9, 16, 1
	v_add3_u32 v9, v9, v18, s76
	v_add3_u32 v8, v8, v14, s76
	v_lshrrev_b32_e32 v8, 16, v8
	v_lshrrev_b32_e32 v9, 16, v9
	v_mov_b32_e32 v18, v11
	v_mov_b32_e32 v34, v27
	global_store_dwordx4 v[84:85], v[42:45], off offset:544
	s_nop 1
	v_and_or_b32 v43, v13, s77, v9
	s_nop 1
	v_and_or_b32 v42, v12, s77, v8
	v_mov_b32_e32 v22, v15
	v_pk_mul_f32 v[8:9], v[18:19], v[78:79]
	v_mov_b32_e32 v38, v31
	v_pk_mul_f32 v[6:7], v[34:35], v[6:7]
	v_cvt_pk_bf16_f32 v45, v17, v21
	v_cvt_pk_bf16_f32 v44, v16, v20
	v_pk_mul_f32 v[4:5], v[22:23], v[4:5]
	v_pk_mul_f32 v[10:11], v[38:39], v[40:41]
	v_bfe_u32 v2, v7, 16, 1
	v_bfe_u32 v14, v8, 16, 1
	v_add3_u32 v8, v8, v14, s76
	v_add3_u32 v2, v7, v2, s76
	v_bfe_u32 v7, v4, 16, 1
	v_bfe_u32 v14, v11, 16, 1
	v_add3_u32 v11, v11, v14, s76
	v_add3_u32 v4, v4, v7, s76
	v_lshrrev_b32_e32 v4, 16, v4
	v_lshrrev_b32_e32 v7, 16, v11
	v_and_or_b32 v7, v2, s77, v7
	v_cvt_pk_bf16_f32 v6, v10, v6
	v_cvt_pk_bf16_f32 v5, v5, v9
	v_and_or_b32 v4, v8, s77, v4
	s_mov_b32 s24, 0x42000
	global_store_dwordx4 v[84:85], v[4:7], off offset:1568
	v_lshl_or_b32 v2, v95, 13, v168
	global_store_dwordx4 v[84:85], v[42:45], off offset:1056
	v_add_co_u32_e32 v6, vcc, s24, v86
	v_lshl_add_u64 v[4:5], v[88:89], 0, v[2:3]
	s_nop 0
	v_addc_co_u32_e32 v7, vcc, 0, v87, vcc
	s_mov_b32 s24, 0x44000
	global_load_dwordx4 v[44:47], v[4:5], off nt
	global_load_dwordx4 v[40:43], v[6:7], off nt
	v_add_co_u32_e32 v4, vcc, s24, v86
	s_mov_b32 s24, 0x48000
	s_nop 0
	v_addc_co_u32_e32 v5, vcc, 0, v87, vcc
	v_add_co_u32_e32 v6, vcc, 0x46000, v86
	v_mov_b32_e32 v76, 1.0
	s_nop 0
	v_addc_co_u32_e32 v7, vcc, 0, v87, vcc
	global_load_dwordx4 v[56:59], v[4:5], off nt
	global_load_dwordx4 v[52:55], v[6:7], off nt
	v_add_co_u32_e32 v4, vcc, s24, v86
	v_mov_b32_e32 v92, 1.0
	s_nop 0
	v_addc_co_u32_e32 v5, vcc, 0, v87, vcc
	v_add_co_u32_e32 v6, vcc, 0x4a000, v86
	v_mov_b32_e32 v77, 1.0
	s_nop 0
	v_addc_co_u32_e32 v7, vcc, 0, v87, vcc
	global_load_dwordx4 v[64:67], v[4:5], off nt
	global_load_dwordx4 v[60:63], v[6:7], off nt
	v_add_co_u32_e32 v4, vcc, 0x4c000, v86
	v_mov_b32_e32 v93, 1.0
	s_nop 0
	v_addc_co_u32_e32 v5, vcc, 0, v87, vcc
	v_add_co_u32_e32 v6, vcc, 0x4e000, v86
	v_mov_b32_e32 v80, 1.0
	s_nop 0
	v_addc_co_u32_e32 v7, vcc, 0, v87, vcc
	global_load_dwordx4 v[72:75], v[4:5], off nt
	global_load_dwordx4 v[68:71], v[6:7], off nt
	v_mov_b32_e32 v4, 1.0
	s_and_b64 vcc, exec, s[16:17]
	v_mov_b32_e32 v90, 1.0
	v_mov_b32_e32 v81, 1.0
	v_mov_b32_e32 v91, 1.0
	s_cbranch_vccnz .LBB0_497
	global_load_dwordx4 v[76:79], v94, s[26:27] offset:128
	global_load_dwordx4 v[80:83], v94, s[26:27] offset:144
	s_waitcnt vmcnt(1)
	v_mov_b32_e32 v92, v77
	v_mov_b32_e32 v77, v78
	v_mov_b32_e32 v93, v79
	s_waitcnt vmcnt(0)
	v_mov_b32_e32 v90, v81
	v_mov_b32_e32 v81, v82
	v_mov_b32_e32 v91, v83

.LBB0_499:
	s_waitcnt vmcnt(15)
	s_waitcnt vmcnt(13)
	v_mul_f32_e32 v50, v76, v44
	v_mul_f32_e32 v51, v77, v56
	s_waitcnt vmcnt(12)
	s_waitcnt vmcnt(11)
	s_waitcnt vmcnt(9)
	v_mul_f32_e32 v82, v92, v40
	v_mul_f32_e32 v83, v93, v52
	v_mul_f32_e32 v86, v80, v64
	v_mul_f32_e32 v87, v81, v72
	s_waitcnt vmcnt(8)
	v_bfe_u32 v56, v50, 16, 1
	v_mul_f32_e32 v88, v90, v60
	v_mul_f32_e32 v89, v91, v68
	v_bfe_u32 v52, v82, 16, 1
	v_bfe_u32 v64, v86, 16, 1
	v_add3_u32 v50, v50, v56, s76
	v_bfe_u32 v40, v88, 16, 1
	v_add3_u32 v52, v82, v52, s76
	v_add3_u32 v64, v86, v64, s76
	v_lshrrev_b32_e32 v50, 16, v50
	v_add3_u32 v40, v88, v40, s76
	v_lshrrev_b32_e32 v56, 16, v64
	v_and_or_b32 v86, v52, s77, v50
	v_mov_b32_e32 v52, v41
	v_mov_b32_e32 v68, v61
	v_and_or_b32 v88, v40, s77, v56
	v_mov_b32_e32 v56, v45
	v_pk_mul_f32 v[40:41], v[52:53], v[92:93]
	v_mov_b32_e32 v72, v65
	v_pk_mul_f32 v[52:53], v[68:69], v[90:91]
	v_cvt_pk_bf16_f32 v89, v87, v89
	v_cvt_pk_bf16_f32 v87, v51, v83
	v_pk_mul_f32 v[44:45], v[56:57], v[76:77]
	v_pk_mul_f32 v[50:51], v[72:73], v[80:81]
	v_bfe_u32 v2, v53, 16, 1
	v_bfe_u32 v60, v40, 16, 1
	v_add3_u32 v40, v40, v60, s76
	v_add3_u32 v2, v53, v2, s76
	v_bfe_u32 v53, v44, 16, 1
	v_bfe_u32 v60, v51, 16, 1
	v_add3_u32 v51, v51, v60, s76
	v_add3_u32 v44, v44, v53, s76
	v_lshrrev_b32_e32 v44, 16, v44
	v_lshrrev_b32_e32 v51, 16, v51
	v_and_or_b32 v53, v2, s77, v51
	v_cvt_pk_bf16_f32 v52, v50, v52
	v_cvt_pk_bf16_f32 v51, v45, v41
	v_and_or_b32 v50, v40, s77, v44
	global_store_dwordx4 v[84:85], v[50:53], off offset:576
	v_mul_f32_e32 v44, v92, v42
	v_mul_f32_e32 v45, v93, v54
	v_mul_f32_e32 v52, v90, v62
	v_mul_f32_e32 v53, v91, v70
	v_mul_f32_e32 v40, v76, v46
	v_mul_f32_e32 v41, v77, v58
	v_mul_f32_e32 v50, v80, v66
	v_mul_f32_e32 v51, v81, v74
	v_bfe_u32 v2, v53, 16, 1
	v_bfe_u32 v42, v52, 16, 1
	v_bfe_u32 v46, v45, 16, 1
	v_bfe_u32 v54, v44, 16, 1
	v_add3_u32 v44, v44, v54, s76
	v_add3_u32 v45, v45, v46, s76
	v_add3_u32 v42, v52, v42, s76
	v_add3_u32 v2, v53, v2, s76
	v_bfe_u32 v46, v40, 16, 1
	v_bfe_u32 v52, v41, 16, 1
	v_bfe_u32 v53, v50, 16, 1
	v_bfe_u32 v54, v51, 16, 1
	v_add3_u32 v51, v51, v54, s76
	v_add3_u32 v50, v50, v53, s76
	v_add3_u32 v41, v41, v52, s76
	v_add3_u32 v40, v40, v46, s76
	v_lshrrev_b32_e32 v40, 16, v40
	v_lshrrev_b32_e32 v41, 16, v41
	v_lshrrev_b32_e32 v46, 16, v50
	v_lshrrev_b32_e32 v50, 16, v51
	v_mov_b32_e32 v54, v43
	v_mov_b32_e32 v70, v63
	v_and_or_b32 v53, v2, s77, v50
	v_and_or_b32 v52, v42, s77, v46
	v_and_or_b32 v51, v45, s77, v41
	v_and_or_b32 v50, v44, s77, v40
	v_mov_b32_e32 v58, v47
	v_pk_mul_f32 v[42:43], v[54:55], v[92:93]
	v_mov_b32_e32 v74, v67
	v_pk_mul_f32 v[46:47], v[70:71], v[90:91]
	global_store_dwordx4 v[84:85], v[50:53], off offset:1088
	v_pk_mul_f32 v[40:41], v[58:59], v[76:77]
	v_pk_mul_f32 v[44:45], v[74:75], v[80:81]
	v_bfe_u32 v2, v47, 16, 1
	v_bfe_u32 v50, v46, 16, 1
	v_bfe_u32 v51, v43, 16, 1
	v_bfe_u32 v52, v42, 16, 1
	v_add3_u32 v52, v42, v52, s76
	v_add3_u32 v51, v43, v51, s76
	v_add3_u32 v42, v46, v50, s76
	v_add3_u32 v2, v47, v2, s76
	v_bfe_u32 v43, v40, 16, 1
	v_bfe_u32 v46, v41, 16, 1
	v_bfe_u32 v47, v44, 16, 1
	v_bfe_u32 v50, v45, 16, 1
	v_add3_u32 v45, v45, v50, s76
	v_add3_u32 v44, v44, v47, s76
	v_add3_u32 v41, v41, v46, s76
	v_add3_u32 v40, v40, v43, s76
	v_lshrrev_b32_e32 v40, 16, v40
	v_lshrrev_b32_e32 v41, 16, v41
	v_lshrrev_b32_e32 v44, 16, v44
	v_lshrrev_b32_e32 v43, 16, v45
	v_and_or_b32 v43, v2, s77, v43
	v_and_or_b32 v42, v42, s77, v44
	v_and_or_b32 v41, v51, s77, v41
	v_and_or_b32 v40, v52, s77, v40
	global_store_dwordx4 v[84:85], v[40:43], off offset:1600
	s_waitcnt vmcnt(6)
	s_waitcnt vmcnt(4)
	v_mul_f32_e32 v40, v4, v12
	v_mul_f32_e32 v41, v5, v20
	v_mul_f32_e32 v44, v48, v28
	v_mul_f32_e32 v45, v49, v36
	s_waitcnt vmcnt(3)
	v_mul_f32_e32 v42, v78, v8
	v_mul_f32_e32 v43, v79, v16
	v_mul_f32_e32 v46, v6, v24
	v_mul_f32_e32 v47, v7, v32
	v_bfe_u32 v24, v41, 16, 1
	v_bfe_u32 v12, v43, 16, 1
	v_add3_u32 v24, v41, v24, s76
	v_add3_u32 v12, v43, v12, s76
	v_lshrrev_b32_e32 v24, 16, v24
	v_cvt_pk_bf16_f32 v43, v45, v47
	v_cvt_pk_bf16_f32 v40, v40, v42
	v_mov_b32_e32 v20, v13
	v_mov_b32_e32 v32, v25
	v_and_or_b32 v41, v12, s77, v24
	v_pk_mul_f32 v[12:13], v[20:21], v[4:5]
	v_mov_b32_e32 v16, v9
	v_pk_mul_f32 v[20:21], v[32:33], v[6:7]
	v_cvt_pk_bf16_f32 v42, v44, v46
	v_pk_mul_f32 v[8:9], v[16:17], v[78:79]
	v_mov_b32_e32 v36, v29
	v_bfe_u32 v2, v21, 16, 1
	v_pk_mul_f32 v[16:17], v[36:37], v[48:49]
	v_add3_u32 v2, v21, v2, s76
	v_bfe_u32 v28, v17, 16, 1
	global_store_dwordx4 v[84:85], v[40:43], off offset:96
	v_add3_u32 v17, v17, v28, s76
	s_nop 1
	v_cvt_pk_bf16_f32 v41, v13, v9
	v_cvt_pk_bf16_f32 v40, v12, v8
	v_lshrrev_b32_e32 v17, 16, v17
	v_cvt_pk_bf16_f32 v42, v16, v20
	v_mul_f32_e32 v12, v78, v10
	v_mul_f32_e32 v13, v79, v18
	v_and_or_b32 v43, v2, s77, v17
	v_mul_f32_e32 v8, v4, v14
	v_mul_f32_e32 v9, v5, v22
	v_mul_f32_e32 v20, v6, v26
	v_mul_f32_e32 v21, v7, v34
	v_bfe_u32 v14, v13, 16, 1
	v_bfe_u32 v18, v12, 16, 1
	v_mul_f32_e32 v16, v48, v30
	v_mul_f32_e32 v17, v49, v38
	v_add3_u32 v12, v12, v18, s76
	v_add3_u32 v13, v13, v14, s76
	v_bfe_u32 v14, v8, 16, 1
	v_bfe_u32 v18, v9, 16, 1
	v_add3_u32 v9, v9, v18, s76
	v_add3_u32 v8, v8, v14, s76
	v_lshrrev_b32_e32 v8, 16, v8
	v_lshrrev_b32_e32 v9, 16, v9
	v_mov_b32_e32 v18, v11
	v_mov_b32_e32 v34, v27
	global_store_dwordx4 v[84:85], v[40:43], off offset:608
	s_nop 1
	v_and_or_b32 v41, v13, s77, v9
	s_nop 1
	v_and_or_b32 v40, v12, s77, v8
	v_mov_b32_e32 v22, v15
	v_pk_mul_f32 v[8:9], v[18:19], v[78:79]
	v_mov_b32_e32 v38, v31
	v_pk_mul_f32 v[6:7], v[34:35], v[6:7]
	v_cvt_pk_bf16_f32 v43, v17, v21
	v_cvt_pk_bf16_f32 v42, v16, v20
	v_pk_mul_f32 v[4:5], v[22:23], v[4:5]
	v_pk_mul_f32 v[10:11], v[38:39], v[48:49]
	v_bfe_u32 v2, v7, 16, 1
	v_bfe_u32 v14, v8, 16, 1
	v_add3_u32 v8, v8, v14, s76
	v_add3_u32 v2, v7, v2, s76
	v_bfe_u32 v7, v4, 16, 1
	v_bfe_u32 v14, v11, 16, 1
	v_add3_u32 v11, v11, v14, s76
	v_add3_u32 v4, v4, v7, s76
	v_lshrrev_b32_e32 v4, 16, v4
	v_lshrrev_b32_e32 v7, 16, v11
	v_and_or_b32 v7, v2, s77, v7
	v_cvt_pk_bf16_f32 v6, v10, v6
	v_cvt_pk_bf16_f32 v5, v5, v9
	v_and_or_b32 v4, v8, s77, v4
	global_store_dwordx4 v[84:85], v[86:89], off offset:64
	global_store_dwordx4 v[84:85], v[40:43], off offset:1120
	global_store_dwordx4 v[84:85], v[4:7], off offset:1632

.LBB0_507:
	s_waitcnt vmcnt(11)
	s_waitcnt vmcnt(9)
	v_mul_f32_e32 v94, v80, v64
	v_mul_f32_e32 v95, v81, v72
	s_waitcnt vmcnt(8)
	v_mul_f32_e32 v42, v76, v56
	v_mul_f32_e32 v43, v77, v60
	v_mul_f32_e32 v96, v90, v52
	v_mul_f32_e32 v97, v91, v68
	v_mul_f32_e32 v86, v92, v44
	v_mul_f32_e32 v87, v93, v48
	v_bfe_u32 v60, v42, 16, 1
	v_add3_u32 v42, v42, v60, s76
	v_bfe_u32 v56, v86, 16, 1
	v_cvt_pk_bf16_f32 v96, v94, v96
	v_mov_b32_e32 v48, v45
	v_mov_b32_e32 v68, v53
	v_add3_u32 v56, v86, v56, s76
	v_lshrrev_b32_e32 v42, 16, v42
	v_cvt_pk_bf16_f32 v97, v95, v97
	v_cvt_pk_bf16_f32 v95, v43, v87
	v_mov_b32_e32 v60, v57
	v_pk_mul_f32 v[44:45], v[48:49], v[92:93]
	v_mov_b32_e32 v72, v65
	v_pk_mul_f32 v[52:53], v[68:69], v[90:91]
	v_and_or_b32 v94, v56, s77, v42
	v_pk_mul_f32 v[42:43], v[60:61], v[76:77]
	v_pk_mul_f32 v[48:49], v[72:73], v[80:81]
	v_bfe_u32 v56, v53, 16, 1
	v_bfe_u32 v57, v52, 16, 1
	v_bfe_u32 v60, v45, 16, 1
	v_bfe_u32 v61, v44, 16, 1
	v_add3_u32 v61, v44, v61, s76
	v_add3_u32 v60, v45, v60, s76
	v_add3_u32 v44, v52, v57, s76
	v_add3_u32 v45, v53, v56, s76
	v_bfe_u32 v52, v42, 16, 1
	v_bfe_u32 v53, v43, 16, 1
	v_bfe_u32 v56, v48, 16, 1
	v_bfe_u32 v57, v49, 16, 1
	v_add3_u32 v49, v49, v57, s76
	v_add3_u32 v48, v48, v56, s76
	v_add3_u32 v43, v43, v53, s76
	v_add3_u32 v42, v42, v52, s76
	v_lshrrev_b32_e32 v42, 16, v42
	v_lshrrev_b32_e32 v43, 16, v43
	v_lshrrev_b32_e32 v48, 16, v48
	v_lshrrev_b32_e32 v49, 16, v49
	v_and_or_b32 v45, v45, s77, v49
	v_and_or_b32 v44, v44, s77, v48
	v_and_or_b32 v43, v60, s77, v43
	v_and_or_b32 v42, v61, s77, v42
	global_store_dwordx4 v[84:85], v[42:45], off offset:2048
	s_nop 1
	v_mul_f32_e32 v44, v92, v46
	s_nop 1
	v_mul_f32_e32 v45, v93, v50
	v_mul_f32_e32 v52, v90, v54
	v_mul_f32_e32 v53, v91, v70
	v_mul_f32_e32 v42, v76, v58
	v_mul_f32_e32 v43, v77, v62
	v_mul_f32_e32 v48, v80, v66
	v_mul_f32_e32 v49, v81, v74
	v_bfe_u32 v46, v53, 16, 1
	v_bfe_u32 v50, v52, 16, 1
	v_bfe_u32 v54, v45, 16, 1
	v_bfe_u32 v56, v44, 16, 1
	v_add3_u32 v56, v44, v56, s76
	v_add3_u32 v54, v45, v54, s76
	v_add3_u32 v44, v52, v50, s76
	v_add3_u32 v45, v53, v46, s76
	v_bfe_u32 v46, v42, 16, 1
	v_bfe_u32 v50, v43, 16, 1
	v_bfe_u32 v52, v48, 16, 1
	v_bfe_u32 v53, v49, 16, 1
	v_add3_u32 v49, v49, v53, s76
	v_add3_u32 v48, v48, v52, s76
	v_add3_u32 v43, v43, v50, s76
	v_add3_u32 v42, v42, v46, s76
	v_lshrrev_b32_e32 v42, 16, v42
	v_lshrrev_b32_e32 v43, 16, v43
	v_lshrrev_b32_e32 v46, 16, v48
	v_lshrrev_b32_e32 v48, 16, v49
	v_add_co_u32_e32 v86, vcc, s69, v84
	v_and_or_b32 v45, v45, s77, v48
	v_and_or_b32 v44, v44, s77, v46
	v_and_or_b32 v43, v54, s77, v43
	v_and_or_b32 v42, v56, s77, v42
	v_addc_co_u32_e32 v87, vcc, 0, v85, vcc
	v_mov_b32_e32 v50, v47
	v_mov_b32_e32 v70, v55
	global_store_dwordx4 v[86:87], v[42:45], off
	v_mov_b32_e32 v62, v59
	v_mov_b32_e32 v74, v67
	v_pk_mul_f32 v[44:45], v[50:51], v[92:93]
	v_pk_mul_f32 v[48:49], v[70:71], v[90:91]
	v_pk_mul_f32 v[42:43], v[62:63], v[76:77]
	v_pk_mul_f32 v[46:47], v[74:75], v[80:81]
	v_bfe_u32 v50, v49, 16, 1
	v_bfe_u32 v51, v48, 16, 1
	v_bfe_u32 v52, v45, 16, 1
	v_bfe_u32 v53, v44, 16, 1
	v_add3_u32 v53, v44, v53, s76
	v_add3_u32 v52, v45, v52, s76
	v_add3_u32 v44, v48, v51, s76
	v_add3_u32 v45, v49, v50, s76
	v_bfe_u32 v48, v42, 16, 1
	v_bfe_u32 v49, v43, 16, 1
	v_bfe_u32 v50, v46, 16, 1
	v_bfe_u32 v51, v47, 16, 1
	v_add3_u32 v47, v47, v51, s76
	v_add3_u32 v46, v46, v50, s76
	v_add3_u32 v43, v43, v49, s76
	v_add3_u32 v42, v42, v48, s76
	v_lshrrev_b32_e32 v42, 16, v42
	v_lshrrev_b32_e32 v43, 16, v43
	v_lshrrev_b32_e32 v46, 16, v46
	v_lshrrev_b32_e32 v47, 16, v47
	v_and_or_b32 v45, v45, s77, v47
	v_and_or_b32 v44, v44, s77, v46
	v_and_or_b32 v43, v52, s77, v43
	v_and_or_b32 v42, v53, s77, v42
	s_waitcnt vmcnt(5)
	s_waitcnt vmcnt(3)
	global_store_dwordx4 v[86:87], v[42:45], off offset:2048
	v_mul_f32_e32 v46, v40, v28
	v_mul_f32_e32 v47, v41, v36
	s_waitcnt vmcnt(3)
	v_mul_f32_e32 v42, v4, v16
	v_mul_f32_e32 v43, v5, v20
	v_mul_f32_e32 v48, v78, v24
	v_mul_f32_e32 v49, v79, v32
	v_mul_f32_e32 v44, v82, v8
	v_mul_f32_e32 v45, v83, v12
	v_bfe_u32 v24, v42, 16, 1
	v_bfe_u32 v20, v44, 16, 1
	v_bfe_u32 v28, v43, 16, 1
	v_add3_u32 v24, v42, v24, s76
	v_bfe_u32 v16, v45, 16, 1
	v_add3_u32 v20, v44, v20, s76
	v_add3_u32 v28, v43, v28, s76
	v_lshrrev_b32_e32 v24, 16, v24
	v_cvt_pk_bf16_f32 v44, v46, v48
	v_mov_b32_e32 v12, v9
	v_add3_u32 v16, v45, v16, s76
	v_lshrrev_b32_e32 v28, 16, v28
	v_cvt_pk_bf16_f32 v45, v47, v49
	v_and_or_b32 v42, v20, s77, v24
	v_mov_b32_e32 v20, v17
	v_pk_mul_f32 v[8:9], v[12:13], v[82:83]
	v_mov_b32_e32 v36, v29
	v_mov_b32_e32 v32, v25
	v_and_or_b32 v43, v16, s77, v28
	v_pk_mul_f32 v[16:17], v[20:21], v[4:5]
	v_pk_mul_f32 v[12:13], v[36:37], v[40:41]
	v_pk_mul_f32 v[20:21], v[32:33], v[78:79]
	global_store_dwordx4 v[84:85], v[42:45], off offset:32
	s_nop 1
	v_cvt_pk_bf16_f32 v45, v13, v21
	s_nop 1
	v_cvt_pk_bf16_f32 v44, v12, v20
	v_cvt_pk_bf16_f32 v43, v17, v9
	v_cvt_pk_bf16_f32 v42, v16, v8
	v_mul_f32_e32 v12, v82, v10
	v_mul_f32_e32 v13, v83, v14
	v_mul_f32_e32 v20, v78, v26
	v_mul_f32_e32 v21, v79, v34
	v_mul_f32_e32 v8, v4, v18
	v_mul_f32_e32 v9, v5, v22
	v_mul_f32_e32 v16, v40, v30
	v_mul_f32_e32 v17, v41, v38
	v_bfe_u32 v10, v21, 16, 1
	v_bfe_u32 v14, v20, 16, 1
	v_add3_u32 v14, v20, v14, s76
	v_add3_u32 v10, v21, v10, s76
	v_bfe_u32 v18, v8, 16, 1
	v_bfe_u32 v21, v16, 16, 1
	v_bfe_u32 v22, v12, 16, 1
	v_add3_u32 v16, v16, v21, s76
	v_add3_u32 v8, v8, v18, s76
	v_add3_u32 v12, v12, v22, s76
	v_bfe_u32 v22, v17, 16, 1
	v_lshrrev_b32_e32 v8, 16, v8
	v_lshrrev_b32_e32 v16, 16, v16
	v_mov_b32_e32 v34, v27
	global_store_dwordx4 v[84:85], v[42:45], off offset:2080
	v_add3_u32 v17, v17, v22, s76
	v_mov_b32_e32 v22, v19
	v_and_or_b32 v44, v14, s77, v16
	v_cvt_pk_bf16_f32 v43, v9, v13
	v_and_or_b32 v42, v12, s77, v8
	v_mov_b32_e32 v14, v11
	v_pk_mul_f32 v[12:13], v[34:35], v[78:79]
	v_lshrrev_b32_e32 v17, 16, v17
	v_pk_mul_f32 v[4:5], v[22:23], v[4:5]
	v_pk_mul_f32 v[8:9], v[14:15], v[82:83]
	v_mov_b32_e32 v38, v31
	v_and_or_b32 v45, v10, s77, v17
	v_pk_mul_f32 v[10:11], v[38:39], v[40:41]
	v_lshl_add_u64 v[6:7], v[88:89], 0, s[58:59]
	v_cvt_pk_bf16_f32 v8, v4, v8
	v_add_co_u32_e32 v4, vcc, s82, v6
	v_cvt_pk_bf16_f32 v11, v11, v13
	v_cvt_pk_bf16_f32 v10, v10, v12
	v_cvt_pk_bf16_f32 v9, v5, v9
	v_addc_co_u32_e32 v5, vcc, 0, v7, vcc
	s_mov_b32 s24, 0xa000
	global_store_dwordx4 v[86:87], v[8:11], off offset:2080
	global_store_dwordx4 v[84:85], v[94:97], off
	global_store_dwordx4 v[86:87], v[42:45], off offset:32
	v_add_co_u32_e32 v8, vcc, s24, v88
	v_mov_b32_e32 v76, 1.0
	s_nop 0
	v_addc_co_u32_e32 v9, vcc, 0, v89, vcc
	global_load_dwordx4 v[52:55], v[4:5], off nt
	global_load_dwordx4 v[44:47], v[8:9], off offset:1280 nt
	global_load_dwordx4 v[56:59], v[8:9], off offset:2560 nt
	global_load_dwordx4 v[48:51], v[8:9], off offset:3840 nt
	v_add_co_u32_e32 v4, vcc, 0xb000, v88
	v_mov_b32_e32 v92, 1.0
	s_nop 0
	v_addc_co_u32_e32 v5, vcc, 0, v89, vcc
	v_add_co_u32_e32 v8, vcc, 0xc000, v88
	global_load_dwordx4 v[64:67], v[4:5], off offset:1024 nt
	global_load_dwordx4 v[60:63], v[4:5], off offset:2304 nt
	v_addc_co_u32_e32 v9, vcc, 0, v89, vcc
	global_load_dwordx4 v[72:75], v[4:5], off offset:3584 nt
	global_load_dwordx4 v[68:71], v[8:9], off offset:768 nt
	v_mov_b32_e32 v4, 1.0
	s_and_b64 vcc, exec, s[16:17]
	v_mov_b32_e32 v77, 1.0
	v_mov_b32_e32 v93, 1.0
	v_mov_b32_e32 v80, 1.0
	v_mov_b32_e32 v90, 1.0
	v_mov_b32_e32 v81, 1.0
	v_mov_b32_e32 v91, 1.0
	s_cbranch_vccnz .LBB0_509
	global_load_dwordx4 v[76:79], v2, s[60:61] offset:128
	global_load_dwordx4 v[80:83], v2, s[60:61] offset:144
	s_waitcnt vmcnt(1)
	v_mov_b32_e32 v92, v77
	v_mov_b32_e32 v77, v78
	v_mov_b32_e32 v93, v79
	s_waitcnt vmcnt(0)
	v_mov_b32_e32 v90, v81
	v_mov_b32_e32 v81, v82
	v_mov_b32_e32 v91, v83

.LBB0_511:
	s_waitcnt vmcnt(14)
	s_waitcnt vmcnt(12)
	s_waitcnt vmcnt(11)
	s_waitcnt vmcnt(9)
	v_mul_f32_e32 v42, v92, v44
	v_mul_f32_e32 v43, v93, v48
	v_mul_f32_e32 v88, v80, v64
	v_mul_f32_e32 v89, v81, v72
	s_waitcnt vmcnt(8)
	v_mul_f32_e32 v6, v76, v52
	v_mul_f32_e32 v7, v77, v56
	v_mul_f32_e32 v94, v90, v60
	v_mul_f32_e32 v95, v91, v68
	v_bfe_u32 v48, v43, 16, 1
	v_bfe_u32 v52, v42, 16, 1
	v_add3_u32 v42, v42, v52, s76
	v_add3_u32 v43, v43, v48, s76
	v_bfe_u32 v48, v6, 16, 1
	v_bfe_u32 v52, v7, 16, 1
	v_bfe_u32 v60, v89, 16, 1
	v_add3_u32 v7, v7, v52, s76
	v_add3_u32 v6, v6, v48, s76
	v_bfe_u32 v2, v95, 16, 1
	v_add3_u32 v60, v89, v60, s76
	v_lshrrev_b32_e32 v6, 16, v6
	v_lshrrev_b32_e32 v7, 16, v7
	v_cvt_pk_bf16_f32 v96, v88, v94
	v_mov_b32_e32 v48, v45
	v_mov_b32_e32 v68, v61
	v_add3_u32 v2, v95, v2, s76
	v_lshrrev_b32_e32 v52, 16, v60
	v_and_or_b32 v95, v43, s77, v7
	v_and_or_b32 v94, v42, s77, v6
	v_mov_b32_e32 v56, v53
	v_pk_mul_f32 v[42:43], v[48:49], v[92:93]
	v_mov_b32_e32 v72, v65
	v_pk_mul_f32 v[48:49], v[68:69], v[90:91]
	v_and_or_b32 v97, v2, s77, v52
	v_pk_mul_f32 v[6:7], v[56:57], v[76:77]
	v_pk_mul_f32 v[44:45], v[72:73], v[80:81]
	v_bfe_u32 v2, v49, 16, 1
	v_add3_u32 v2, v49, v2, s76
	v_bfe_u32 v56, v45, 16, 1
	v_add3_u32 v45, v45, v56, s76
	v_lshrrev_b32_e32 v45, 16, v45
	v_and_or_b32 v45, v2, s77, v45
	v_cvt_pk_bf16_f32 v44, v44, v48
	v_cvt_pk_bf16_f32 v43, v7, v43
	v_cvt_pk_bf16_f32 v42, v6, v42
	global_store_dwordx4 v[84:85], v[42:45], off offset:2112
	s_nop 1
	v_mul_f32_e32 v42, v92, v46
	s_nop 1
	v_mul_f32_e32 v43, v93, v50
	v_mul_f32_e32 v48, v90, v62
	v_mul_f32_e32 v49, v91, v70
	v_mul_f32_e32 v6, v76, v54
	v_mul_f32_e32 v7, v77, v58
	v_mul_f32_e32 v44, v80, v66
	v_mul_f32_e32 v45, v81, v74
	v_bfe_u32 v2, v49, 16, 1
	v_bfe_u32 v46, v48, 16, 1
	v_add3_u32 v46, v48, v46, s76
	v_add3_u32 v2, v49, v2, s76
	v_bfe_u32 v50, v44, 16, 1
	v_bfe_u32 v52, v45, 16, 1
	v_add3_u32 v45, v45, v52, s76
	v_add3_u32 v44, v44, v50, s76
	v_lshrrev_b32_e32 v44, 16, v44
	v_lshrrev_b32_e32 v45, 16, v45
	v_and_or_b32 v45, v2, s77, v45
	v_and_or_b32 v44, v46, s77, v44
	v_cvt_pk_bf16_f32 v43, v7, v43
	v_cvt_pk_bf16_f32 v42, v6, v42
	v_mov_b32_e32 v50, v47
	v_mov_b32_e32 v70, v63
	global_store_dwordx4 v[86:87], v[42:45], off offset:64
	v_mov_b32_e32 v58, v55
	v_mov_b32_e32 v74, v67
	v_pk_mul_f32 v[42:43], v[50:51], v[92:93]
	v_pk_mul_f32 v[46:47], v[70:71], v[90:91]
	v_pk_mul_f32 v[6:7], v[58:59], v[76:77]
	v_pk_mul_f32 v[44:45], v[74:75], v[80:81]
	v_bfe_u32 v2, v47, 16, 1
	v_add3_u32 v2, v47, v2, s76
	v_bfe_u32 v50, v45, 16, 1
	v_add3_u32 v45, v45, v50, s76
	v_lshrrev_b32_e32 v45, 16, v45
	v_and_or_b32 v45, v2, s77, v45
	v_cvt_pk_bf16_f32 v44, v44, v46
	v_cvt_pk_bf16_f32 v43, v7, v43
	v_cvt_pk_bf16_f32 v42, v6, v42
	s_waitcnt vmcnt(9)
	s_waitcnt vmcnt(7)
	global_store_dwordx4 v[86:87], v[42:45], off offset:2112
	v_mul_f32_e32 v6, v4, v32
	v_mul_f32_e32 v7, v5, v36
	s_waitcnt vmcnt(5)
	s_waitcnt vmcnt(4)
	v_mul_f32_e32 v42, v82, v24
	v_mul_f32_e32 v43, v83, v28
	v_mul_f32_e32 v44, v40, v20
	v_mul_f32_e32 v45, v41, v16
	s_waitcnt vmcnt(3)
	v_bfe_u32 v24, v7, 16, 1
	v_mul_f32_e32 v46, v78, v8
	v_mul_f32_e32 v47, v79, v12
	v_bfe_u32 v12, v43, 16, 1
	v_bfe_u32 v28, v44, 16, 1
	v_add3_u32 v7, v7, v24, s76
	v_bfe_u32 v8, v46, 16, 1
	v_add3_u32 v12, v43, v12, s76
	v_add3_u32 v28, v44, v28, s76
	v_lshrrev_b32_e32 v7, 16, v7
	v_add3_u32 v8, v46, v8, s76
	v_lshrrev_b32_e32 v20, 16, v28
	v_and_or_b32 v43, v12, s77, v7
	v_mov_b32_e32 v28, v25
	v_mov_b32_e32 v12, v9
	v_cvt_pk_bf16_f32 v45, v45, v47
	v_and_or_b32 v44, v8, s77, v20
	v_cvt_pk_bf16_f32 v42, v6, v42
	v_mov_b32_e32 v36, v33
	v_pk_mul_f32 v[24:25], v[28:29], v[82:83]
	v_pk_mul_f32 v[8:9], v[12:13], v[78:79]
	v_pk_mul_f32 v[6:7], v[36:37], v[4:5]
	v_mul_f32_e32 v16, v40, v21
	v_mul_f32_e32 v17, v41, v17
	v_bfe_u32 v2, v9, 16, 1
	v_bfe_u32 v20, v24, 16, 1
	v_add3_u32 v20, v24, v20, s76
	v_add3_u32 v2, v9, v2, s76
	v_bfe_u32 v9, v6, 16, 1
	v_bfe_u32 v24, v17, 16, 1
	v_add3_u32 v17, v17, v24, s76
	v_add3_u32 v6, v6, v9, s76
	v_lshrrev_b32_e32 v6, 16, v6
	v_lshrrev_b32_e32 v9, 16, v17
	v_and_or_b32 v9, v2, s77, v9
	v_cvt_pk_bf16_f32 v8, v16, v8
	v_cvt_pk_bf16_f32 v7, v7, v25
	v_and_or_b32 v6, v20, s77, v6
	global_store_dwordx4 v[84:85], v[6:9], off offset:2144
	s_nop 1
	v_mul_f32_e32 v8, v82, v26
	s_nop 1
	v_mul_f32_e32 v9, v83, v30
	v_mul_f32_e32 v16, v78, v10
	v_mul_f32_e32 v17, v79, v14
	v_mul_f32_e32 v6, v4, v34
	v_mul_f32_e32 v7, v5, v38
	v_mul_f32_e32 v12, v40, v22
	v_mul_f32_e32 v13, v41, v18
	v_bfe_u32 v14, v9, 16, 1
	v_bfe_u32 v18, v8, 16, 1
	v_add3_u32 v18, v8, v18, s76
	v_add3_u32 v14, v9, v14, s76
	v_bfe_u32 v9, v6, 16, 1
	v_bfe_u32 v10, v7, 16, 1
	v_add3_u32 v7, v7, v10, s76
	v_add3_u32 v6, v6, v9, s76
	v_lshrrev_b32_e32 v6, 16, v6
	v_lshrrev_b32_e32 v7, 16, v7
	v_mov_b32_e32 v38, v35
	v_cvt_pk_bf16_f32 v9, v13, v17
	v_cvt_pk_bf16_f32 v8, v12, v16
	v_and_or_b32 v7, v14, s77, v7
	v_and_or_b32 v6, v18, s77, v6
	v_pk_mul_f32 v[4:5], v[38:39], v[4:5]
	v_mov_b32_e32 v30, v27
	global_store_dwordx4 v[86:87], v[6:9], off offset:96
	v_and_b32_sdwa v2, v5, v171 dst_sel:DWORD dst_unused:UNUSED_PAD src0_sel:WORD_1 src1_sel:DWORD
	v_add3_u32 v2, v5, v2, s76
	v_pk_mul_f32 v[6:7], v[30:31], v[82:83]
	v_and_b32_sdwa v8, v4, v171 dst_sel:DWORD dst_unused:UNUSED_PAD src0_sel:WORD_1 src1_sel:DWORD
	v_add3_u32 v4, v4, v8, s76
	v_and_b32_sdwa v8, v6, v171 dst_sel:DWORD dst_unused:UNUSED_PAD src0_sel:WORD_1 src1_sel:DWORD
	v_add3_u32 v6, v6, v8, s76
	v_and_b32_sdwa v5, v7, v171 dst_sel:DWORD dst_unused:UNUSED_PAD src0_sel:WORD_1 src1_sel:DWORD
	v_and_b32_e32 v6, 0xffff0000, v6
	v_add3_u32 v5, v7, v5, s76
	v_or_b32_sdwa v4, v6, v4 dst_sel:DWORD dst_unused:UNUSED_PAD src0_sel:DWORD src1_sel:WORD_1
	v_mov_b32_e32 v10, v23
	v_mov_b32_e32 v6, v40
	v_mov_b32_e32 v7, v78
	v_pk_mul_f32 v[6:7], v[10:11], v[6:7]
	v_and_b32_e32 v5, 0xffff0000, v5
	v_and_b32_sdwa v8, v6, v171 dst_sel:DWORD dst_unused:UNUSED_PAD src0_sel:WORD_1 src1_sel:DWORD
	v_mov_b32_e32 v14, v19
	v_mov_b32_e32 v78, v41
	v_or_b32_sdwa v5, v5, v2 dst_sel:DWORD dst_unused:UNUSED_PAD src0_sel:DWORD src1_sel:WORD_1
	v_and_b32_sdwa v2, v7, v171 dst_sel:DWORD dst_unused:UNUSED_PAD src0_sel:WORD_1 src1_sel:DWORD
	v_add3_u32 v6, v6, v8, s76
	v_pk_mul_f32 v[8:9], v[14:15], v[78:79]
	v_add3_u32 v2, v7, v2, s76
	v_lshrrev_b32_e32 v6, 16, v6
	v_and_b32_sdwa v7, v8, v171 dst_sel:DWORD dst_unused:UNUSED_PAD src0_sel:WORD_1 src1_sel:DWORD
	v_and_or_b32 v6, v2, s77, v6
	v_and_b32_sdwa v2, v9, v171 dst_sel:DWORD dst_unused:UNUSED_PAD src0_sel:WORD_1 src1_sel:DWORD
	v_add3_u32 v7, v8, v7, s76
	v_add3_u32 v2, v9, v2, s76
	v_lshrrev_b32_e32 v7, 16, v7
	v_and_or_b32 v7, v2, s77, v7
	global_store_dwordx4 v[84:85], v[94:97], off offset:64
	global_store_dwordx4 v[84:85], v[42:45], off offset:96

.LBB0_546:
	s_waitcnt vmcnt(15)
	s_waitcnt vmcnt(13)
	v_mul_f32_e32 v42, v76, v48
	v_mul_f32_e32 v43, v77, v60
	s_waitcnt vmcnt(12)
	s_waitcnt vmcnt(11)
	s_waitcnt vmcnt(9)
	v_mul_f32_e32 v82, v96, v44
	v_mul_f32_e32 v83, v97, v52
	v_mul_f32_e32 v86, v80, v64
	v_mul_f32_e32 v87, v81, v72
	v_mov_b32_e32 v98, v56
	s_waitcnt vmcnt(8)
	v_bfe_u32 v56, v42, 16, 1
	v_mul_f32_e32 v98, v94, v98
	v_mul_f32_e32 v99, v95, v68
	v_bfe_u32 v52, v82, 16, 1
	v_bfe_u32 v64, v86, 16, 1
	v_bfe_u32 v68, v87, 16, 1
	v_add3_u32 v42, v42, v56, s76
	v_bfe_u32 v2, v99, 16, 1
	v_bfe_u32 v44, v98, 16, 1
	v_add3_u32 v52, v82, v52, s76
	v_bfe_u32 v60, v43, 16, 1
	v_add3_u32 v68, v87, v68, s76
	v_add3_u32 v64, v86, v64, s76
	v_lshrrev_b32_e32 v42, 16, v42
	v_bfe_u32 v48, v83, 16, 1
	v_add3_u32 v44, v98, v44, s76
	v_add3_u32 v2, v99, v2, s76
	v_add3_u32 v43, v43, v60, s76
	v_lshrrev_b32_e32 v56, 16, v64
	v_lshrrev_b32_e32 v60, 16, v68
	v_and_or_b32 v98, v52, s77, v42
	v_mov_b32_e32 v52, v45
	v_mov_b32_e32 v68, v57
	v_add3_u32 v48, v83, v48, s76
	v_lshrrev_b32_e32 v43, 16, v43
	v_and_or_b32 v101, v2, s77, v60
	v_and_or_b32 v100, v44, s77, v56
	v_mov_b32_e32 v60, v49
	v_pk_mul_f32 v[44:45], v[52:53], v[96:97]
	v_mov_b32_e32 v72, v65
	v_pk_mul_f32 v[52:53], v[68:69], v[94:95]
	v_and_or_b32 v99, v48, s77, v43
	v_pk_mul_f32 v[42:43], v[60:61], v[76:77]
	v_pk_mul_f32 v[48:49], v[72:73], v[80:81]
	v_bfe_u32 v2, v53, 16, 1
	v_bfe_u32 v56, v52, 16, 1
	v_bfe_u32 v57, v45, 16, 1
	v_bfe_u32 v60, v44, 16, 1
	v_add3_u32 v60, v44, v60, s76
	v_add3_u32 v57, v45, v57, s76
	v_add3_u32 v44, v52, v56, s76
	v_add3_u32 v2, v53, v2, s76
	v_bfe_u32 v45, v42, 16, 1
	v_bfe_u32 v52, v43, 16, 1
	v_bfe_u32 v53, v48, 16, 1
	v_bfe_u32 v56, v49, 16, 1
	v_add3_u32 v49, v49, v56, s76
	v_add3_u32 v48, v48, v53, s76
	v_add3_u32 v43, v43, v52, s76
	v_add3_u32 v42, v42, v45, s76
	v_lshrrev_b32_e32 v42, 16, v42
	v_lshrrev_b32_e32 v43, 16, v43
	v_lshrrev_b32_e32 v48, 16, v48
	v_lshrrev_b32_e32 v45, 16, v49
	v_and_or_b32 v45, v2, s77, v45
	v_and_or_b32 v44, v44, s77, v48
	v_and_or_b32 v43, v57, s77, v43
	v_and_or_b32 v42, v60, s77, v42
	global_store_dwordx4 v[84:85], v[42:45], off offset:2048
	s_nop 1
	v_mul_f32_e32 v44, v96, v46
	s_nop 1
	v_mul_f32_e32 v45, v97, v54
	v_mul_f32_e32 v52, v94, v58
	v_mul_f32_e32 v53, v95, v70
	v_mul_f32_e32 v42, v76, v50
	v_mul_f32_e32 v43, v77, v62
	v_mul_f32_e32 v48, v80, v66
	v_mul_f32_e32 v49, v81, v74
	v_bfe_u32 v50, v45, 16, 1
	v_bfe_u32 v54, v44, 16, 1
	v_add3_u32 v54, v44, v54, s76
	v_add3_u32 v50, v45, v50, s76
	v_bfe_u32 v45, v42, 16, 1
	v_bfe_u32 v46, v43, 16, 1
	v_add3_u32 v43, v43, v46, s76
	v_add3_u32 v42, v42, v45, s76
	v_lshrrev_b32_e32 v42, 16, v42
	v_lshrrev_b32_e32 v43, 16, v43
	v_add_co_u32_e32 v86, vcc, s69, v84
	v_cvt_pk_bf16_f32 v45, v49, v53
	v_cvt_pk_bf16_f32 v44, v48, v52
	v_and_or_b32 v43, v50, s77, v43
	v_and_or_b32 v42, v54, s77, v42
	v_addc_co_u32_e32 v87, vcc, 0, v85, vcc
	v_mov_b32_e32 v54, v47
	v_mov_b32_e32 v70, v59
	global_store_dwordx4 v[86:87], v[42:45], off
	v_mov_b32_e32 v62, v51
	v_mov_b32_e32 v74, v67
	v_pk_mul_f32 v[44:45], v[54:55], v[96:97]
	v_pk_mul_f32 v[48:49], v[70:71], v[94:95]
	v_pk_mul_f32 v[42:43], v[62:63], v[76:77]
	v_pk_mul_f32 v[46:47], v[74:75], v[80:81]
	v_bfe_u32 v2, v49, 16, 1
	v_bfe_u32 v50, v48, 16, 1
	v_bfe_u32 v51, v45, 16, 1
	v_bfe_u32 v52, v44, 16, 1
	v_add3_u32 v52, v44, v52, s76
	v_add3_u32 v51, v45, v51, s76
	v_add3_u32 v44, v48, v50, s76
	v_add3_u32 v2, v49, v2, s76
	v_bfe_u32 v45, v42, 16, 1
	v_bfe_u32 v48, v43, 16, 1
	v_bfe_u32 v49, v46, 16, 1
	v_bfe_u32 v50, v47, 16, 1
	v_add3_u32 v47, v47, v50, s76
	v_add3_u32 v46, v46, v49, s76
	v_add3_u32 v43, v43, v48, s76
	v_add3_u32 v42, v42, v45, s76
	v_lshrrev_b32_e32 v42, 16, v42
	v_lshrrev_b32_e32 v43, 16, v43
	v_lshrrev_b32_e32 v46, 16, v46
	v_lshrrev_b32_e32 v45, 16, v47
	v_and_or_b32 v45, v2, s77, v45
	v_and_or_b32 v44, v44, s77, v46
	v_and_or_b32 v43, v51, s77, v43
	v_and_or_b32 v42, v52, s77, v42
	s_waitcnt vmcnt(5)
	s_waitcnt vmcnt(3)
	global_store_dwordx4 v[86:87], v[42:45], off offset:2048
	v_mul_f32_e32 v46, v40, v28
	v_mul_f32_e32 v47, v41, v36
	s_waitcnt vmcnt(3)
	v_mul_f32_e32 v42, v4, v12
	v_mul_f32_e32 v43, v5, v24
	v_mul_f32_e32 v48, v6, v20
	v_mul_f32_e32 v49, v7, v32
	v_mul_f32_e32 v44, v78, v8
	v_mul_f32_e32 v45, v79, v16
	v_bfe_u32 v24, v43, 16, 1
	v_bfe_u32 v12, v45, 16, 1
	v_add3_u32 v24, v43, v24, s76
	v_add3_u32 v12, v45, v12, s76
	v_lshrrev_b32_e32 v24, 16, v24
	v_cvt_pk_bf16_f32 v45, v47, v49
	v_mov_b32_e32 v32, v21
	v_and_or_b32 v43, v12, s77, v24
	v_cvt_pk_bf16_f32 v42, v42, v44
	v_mov_b32_e32 v24, v13
	v_mov_b32_e32 v16, v9
	v_pk_mul_f32 v[20:21], v[32:33], v[6:7]
	v_cvt_pk_bf16_f32 v44, v46, v48
	v_pk_mul_f32 v[12:13], v[24:25], v[4:5]
	v_pk_mul_f32 v[8:9], v[16:17], v[78:79]
	v_mov_b32_e32 v36, v29
	v_bfe_u32 v2, v21, 16, 1
	v_pk_mul_f32 v[16:17], v[36:37], v[40:41]
	v_add3_u32 v2, v21, v2, s76
	v_bfe_u32 v28, v17, 16, 1
	global_store_dwordx4 v[84:85], v[42:45], off offset:32
	v_add3_u32 v17, v17, v28, s76
	s_nop 1
	v_cvt_pk_bf16_f32 v43, v13, v9
	v_cvt_pk_bf16_f32 v42, v12, v8
	v_lshrrev_b32_e32 v17, 16, v17
	v_cvt_pk_bf16_f32 v44, v16, v20
	v_mul_f32_e32 v12, v78, v10
	v_mul_f32_e32 v13, v79, v18
	v_and_or_b32 v45, v2, s77, v17
	v_mul_f32_e32 v8, v4, v14
	v_mul_f32_e32 v9, v5, v26
	v_mul_f32_e32 v20, v6, v22
	v_mul_f32_e32 v21, v7, v34
	v_bfe_u32 v14, v13, 16, 1
	v_bfe_u32 v18, v12, 16, 1
	v_mul_f32_e32 v16, v40, v30
	v_mul_f32_e32 v17, v41, v38
	v_add3_u32 v12, v12, v18, s76
	v_add3_u32 v13, v13, v14, s76
	v_bfe_u32 v14, v8, 16, 1
	v_bfe_u32 v18, v9, 16, 1
	v_add3_u32 v9, v9, v18, s76
	v_add3_u32 v8, v8, v14, s76
	v_lshrrev_b32_e32 v8, 16, v8
	v_lshrrev_b32_e32 v9, 16, v9
	v_mov_b32_e32 v18, v11
	v_mov_b32_e32 v34, v23
	global_store_dwordx4 v[84:85], v[42:45], off offset:2080
	s_nop 1
	v_and_or_b32 v43, v13, s77, v9
	s_nop 1
	v_and_or_b32 v42, v12, s77, v8
	v_mov_b32_e32 v26, v15
	v_pk_mul_f32 v[8:9], v[18:19], v[78:79]
	v_mov_b32_e32 v38, v31
	v_pk_mul_f32 v[6:7], v[34:35], v[6:7]
	v_cvt_pk_bf16_f32 v45, v17, v21
	v_cvt_pk_bf16_f32 v44, v16, v20
	v_pk_mul_f32 v[4:5], v[26:27], v[4:5]
	v_pk_mul_f32 v[10:11], v[38:39], v[40:41]
	v_bfe_u32 v2, v7, 16, 1
	v_bfe_u32 v14, v8, 16, 1
	v_add3_u32 v8, v8, v14, s76
	v_add3_u32 v2, v7, v2, s76
	v_bfe_u32 v7, v4, 16, 1
	v_bfe_u32 v14, v11, 16, 1
	v_add3_u32 v11, v11, v14, s76
	v_add3_u32 v4, v4, v7, s76
	v_lshrrev_b32_e32 v4, 16, v4
	v_lshrrev_b32_e32 v7, 16, v11
	v_and_or_b32 v7, v2, s77, v7
	v_cvt_pk_bf16_f32 v6, v10, v6
	v_cvt_pk_bf16_f32 v5, v5, v9
	v_and_or_b32 v4, v8, s77, v4
	v_or_b32_e32 v2, 32, v88
	global_store_dwordx4 v[86:87], v[4:7], off offset:2080
	global_store_dwordx4 v[84:85], v[98:101], off
	global_store_dwordx4 v[86:87], v[42:45], off offset:32
	v_mad_i64_i32 v[4:5], s[26:27], v2, s91, v[90:91]
	v_or_b32_e32 v2, 33, v88
	v_mad_i64_i32 v[6:7], s[26:27], v2, s91, v[90:91]
	v_or_b32_e32 v2, 34, v88
	global_load_dwordx4 v[48:51], v[4:5], off nt
	global_load_dwordx4 v[44:47], v[6:7], off nt
	v_mad_i64_i32 v[4:5], s[26:27], v2, s91, v[90:91]
	v_or_b32_e32 v2, 35, v88
	v_mad_i64_i32 v[6:7], s[26:27], v2, s91, v[90:91]
	v_or_b32_e32 v2, 36, v88
	global_load_dwordx4 v[60:63], v[4:5], off nt
	global_load_dwordx4 v[52:55], v[6:7], off nt
	v_mad_i64_i32 v[4:5], s[26:27], v2, s91, v[90:91]
	v_or_b32_e32 v2, 37, v88
	v_mad_i64_i32 v[6:7], s[26:27], v2, s91, v[90:91]
	v_or_b32_e32 v2, 38, v88
	global_load_dwordx4 v[64:67], v[4:5], off nt
	global_load_dwordx4 v[56:59], v[6:7], off nt
	v_mad_i64_i32 v[4:5], s[26:27], v2, s91, v[90:91]
	v_or_b32_e32 v2, 39, v88
	v_mad_i64_i32 v[6:7], s[26:27], v2, s91, v[90:91]
	global_load_dwordx4 v[72:75], v[4:5], off nt
	global_load_dwordx4 v[68:71], v[6:7], off nt
	v_mov_b32_e32 v4, 1.0
	s_and_b64 vcc, exec, s[16:17]
	v_mov_b32_e32 v76, 1.0
	v_mov_b32_e32 v96, 1.0
	v_mov_b32_e32 v77, 1.0
	v_mov_b32_e32 v97, 1.0
	v_mov_b32_e32 v80, 1.0
	v_mov_b32_e32 v94, 1.0
	v_mov_b32_e32 v81, 1.0
	v_mov_b32_e32 v95, 1.0
	s_cbranch_vccnz .LBB0_548
	global_load_dwordx4 v[76:79], v[92:93], off offset:128
	global_load_dwordx4 v[80:83], v[92:93], off offset:144
	s_waitcnt vmcnt(1)
	v_mov_b32_e32 v96, v77
	v_mov_b32_e32 v77, v78
	v_mov_b32_e32 v97, v79
	s_waitcnt vmcnt(0)
	v_mov_b32_e32 v94, v81
	v_mov_b32_e32 v81, v82
	v_mov_b32_e32 v95, v83

.LBB0_550:
	s_waitcnt vmcnt(14)
	s_waitcnt vmcnt(12)
	s_waitcnt vmcnt(11)
	s_waitcnt vmcnt(9)
	v_mul_f32_e32 v34, v96, v44
	v_mul_f32_e32 v35, v97, v52
	v_mul_f32_e32 v88, v80, v64
	v_mul_f32_e32 v89, v81, v72
	s_waitcnt vmcnt(8)
	v_mul_f32_e32 v6, v76, v48
	v_mul_f32_e32 v7, v77, v60
	v_mul_f32_e32 v90, v94, v56
	v_mul_f32_e32 v91, v95, v68
	v_bfe_u32 v48, v35, 16, 1
	v_bfe_u32 v52, v34, 16, 1
	v_add3_u32 v34, v34, v52, s76
	v_add3_u32 v35, v35, v48, s76
	v_bfe_u32 v48, v6, 16, 1
	v_bfe_u32 v52, v7, 16, 1
	v_add3_u32 v7, v7, v52, s76
	v_add3_u32 v6, v6, v48, s76
	v_lshrrev_b32_e32 v6, 16, v6
	v_lshrrev_b32_e32 v7, 16, v7
	v_cvt_pk_bf16_f32 v91, v89, v91
	v_mov_b32_e32 v52, v45
	v_mov_b32_e32 v68, v57
	v_cvt_pk_bf16_f32 v90, v88, v90
	v_and_or_b32 v89, v35, s77, v7
	v_and_or_b32 v88, v34, s77, v6
	v_mov_b32_e32 v60, v49
	v_pk_mul_f32 v[34:35], v[52:53], v[96:97]
	v_mov_b32_e32 v72, v65
	v_pk_mul_f32 v[48:49], v[68:69], v[94:95]
	v_pk_mul_f32 v[6:7], v[60:61], v[76:77]
	v_pk_mul_f32 v[44:45], v[72:73], v[80:81]
	v_bfe_u32 v2, v49, 16, 1
	v_bfe_u32 v56, v34, 16, 1
	v_add3_u32 v2, v49, v2, s76
	v_bfe_u32 v49, v6, 16, 1
	v_add3_u32 v34, v34, v56, s76
	v_bfe_u32 v56, v45, 16, 1
	v_add3_u32 v6, v6, v49, s76
	v_add3_u32 v45, v45, v56, s76
	v_lshrrev_b32_e32 v6, 16, v6
	global_store_dwordx4 v[84:85], v[88:91], off offset:64
	v_lshrrev_b32_e32 v45, 16, v45
	s_nop 1
	v_cvt_pk_bf16_f32 v90, v44, v48
	v_cvt_pk_bf16_f32 v89, v7, v35
	v_and_or_b32 v88, v34, s77, v6
	v_and_or_b32 v91, v2, s77, v45
	v_mul_f32_e32 v34, v96, v46
	v_mul_f32_e32 v35, v97, v54
	v_mul_f32_e32 v48, v94, v58
	v_mul_f32_e32 v49, v95, v70
	v_mul_f32_e32 v6, v76, v50
	v_mul_f32_e32 v7, v77, v62
	v_mul_f32_e32 v44, v80, v66
	v_mul_f32_e32 v45, v81, v74
	v_bfe_u32 v46, v48, 16, 1
	v_add3_u32 v46, v48, v46, s76
	v_bfe_u32 v50, v44, 16, 1
	v_add3_u32 v44, v44, v50, s76
	v_lshrrev_b32_e32 v44, 16, v44
	v_mov_b32_e32 v54, v47
	v_mov_b32_e32 v70, v59
	global_store_dwordx4 v[84:85], v[88:91], off offset:2112
	v_mov_b32_e32 v62, v51
	s_nop 1
	v_and_or_b32 v90, v46, s77, v44
	v_cvt_pk_bf16_f32 v89, v7, v35
	v_cvt_pk_bf16_f32 v88, v6, v34
	v_pk_mul_f32 v[34:35], v[54:55], v[96:97]
	v_mov_b32_e32 v74, v67
	v_pk_mul_f32 v[46:47], v[70:71], v[94:95]
	v_cvt_pk_bf16_f32 v91, v45, v49
	v_pk_mul_f32 v[6:7], v[62:63], v[76:77]
	v_pk_mul_f32 v[44:45], v[74:75], v[80:81]
	v_bfe_u32 v2, v47, 16, 1
	v_bfe_u32 v50, v34, 16, 1
	v_add3_u32 v34, v34, v50, s76
	v_add3_u32 v2, v47, v2, s76
	v_bfe_u32 v47, v6, 16, 1
	v_bfe_u32 v50, v45, 16, 1
	v_add3_u32 v45, v45, v50, s76
	v_add3_u32 v6, v6, v47, s76
	v_lshrrev_b32_e32 v6, 16, v6
	v_lshrrev_b32_e32 v45, 16, v45
	v_and_or_b32 v47, v2, s77, v45
	v_cvt_pk_bf16_f32 v46, v44, v46
	v_cvt_pk_bf16_f32 v45, v7, v35
	v_and_or_b32 v44, v34, s77, v6
	global_store_dwordx4 v[86:87], v[44:47], off offset:2112
	s_waitcnt vmcnt(9)
	s_waitcnt vmcnt(7)
	s_waitcnt vmcnt(6)
	s_waitcnt vmcnt(4)
	v_mul_f32_e32 v34, v82, v24
	v_mul_f32_e32 v35, v83, v36
	v_mul_f32_e32 v44, v32, v20
	v_mul_f32_e32 v45, v33, v12
	s_waitcnt vmcnt(3)
	v_mul_f32_e32 v6, v4, v28
	v_mul_f32_e32 v7, v5, v40
	v_mul_f32_e32 v46, v78, v16
	v_mul_f32_e32 v47, v79, v8
	v_cvt_pk_bf16_f32 v46, v44, v46
	v_mov_b32_e32 v36, v25
	v_cvt_pk_bf16_f32 v47, v45, v47
	v_cvt_pk_bf16_f32 v45, v7, v35
	v_mov_b32_e32 v40, v29
	v_pk_mul_f32 v[24:25], v[36:37], v[82:83]
	v_mul_f32_e32 v8, v78, v17
	v_mul_f32_e32 v9, v79, v9
	v_cvt_pk_bf16_f32 v44, v6, v34
	v_pk_mul_f32 v[6:7], v[40:41], v[4:5]
	v_mul_f32_e32 v12, v32, v21
	v_mul_f32_e32 v13, v33, v13
	v_bfe_u32 v2, v9, 16, 1
	v_bfe_u32 v20, v24, 16, 1
	v_add3_u32 v20, v24, v20, s76
	v_add3_u32 v2, v9, v2, s76
	v_bfe_u32 v9, v6, 16, 1
	v_bfe_u32 v24, v13, 16, 1
	v_add3_u32 v13, v13, v24, s76
	v_add3_u32 v6, v6, v9, s76
	v_lshrrev_b32_e32 v6, 16, v6
	v_lshrrev_b32_e32 v9, 16, v13
	v_and_or_b32 v9, v2, s77, v9
	v_cvt_pk_bf16_f32 v8, v12, v8
	v_cvt_pk_bf16_f32 v7, v7, v25
	v_and_or_b32 v6, v20, s77, v6
	global_store_dwordx4 v[84:85], v[6:9], off offset:2144
	s_nop 1
	v_mul_f32_e32 v8, v82, v26
	s_nop 1
	v_mul_f32_e32 v9, v83, v38
	v_mul_f32_e32 v16, v78, v18
	v_mul_f32_e32 v17, v79, v10
	v_mul_f32_e32 v6, v4, v30
	v_mul_f32_e32 v7, v5, v42
	v_mul_f32_e32 v12, v32, v22
	v_mul_f32_e32 v13, v33, v14
	v_bfe_u32 v14, v9, 16, 1
	v_bfe_u32 v18, v8, 16, 1
	v_add3_u32 v18, v8, v18, s76
	v_add3_u32 v14, v9, v14, s76
	v_bfe_u32 v9, v6, 16, 1
	v_bfe_u32 v10, v7, 16, 1
	v_add3_u32 v7, v7, v10, s76
	v_add3_u32 v6, v6, v9, s76
	v_lshrrev_b32_e32 v6, 16, v6
	v_lshrrev_b32_e32 v7, 16, v7
	v_mov_b32_e32 v42, v31
	v_cvt_pk_bf16_f32 v9, v13, v17
	v_cvt_pk_bf16_f32 v8, v12, v16
	v_and_or_b32 v7, v14, s77, v7
	v_and_or_b32 v6, v18, s77, v6
	v_pk_mul_f32 v[4:5], v[42:43], v[4:5]
	v_mov_b32_e32 v38, v27
	global_store_dwordx4 v[86:87], v[6:9], off offset:96
	v_and_b32_sdwa v2, v5, v171 dst_sel:DWORD dst_unused:UNUSED_PAD src0_sel:WORD_1 src1_sel:DWORD
	v_add3_u32 v2, v5, v2, s76
	v_pk_mul_f32 v[6:7], v[38:39], v[82:83]
	v_and_b32_sdwa v8, v4, v171 dst_sel:DWORD dst_unused:UNUSED_PAD src0_sel:WORD_1 src1_sel:DWORD
	v_add3_u32 v4, v4, v8, s76
	v_and_b32_sdwa v8, v6, v171 dst_sel:DWORD dst_unused:UNUSED_PAD src0_sel:WORD_1 src1_sel:DWORD
	v_add3_u32 v6, v6, v8, s76
	v_and_b32_sdwa v5, v7, v171 dst_sel:DWORD dst_unused:UNUSED_PAD src0_sel:WORD_1 src1_sel:DWORD
	v_and_b32_e32 v6, 0xffff0000, v6
	v_add3_u32 v5, v7, v5, s76
	v_or_b32_sdwa v4, v6, v4 dst_sel:DWORD dst_unused:UNUSED_PAD src0_sel:DWORD src1_sel:WORD_1
	v_mov_b32_e32 v18, v23
	v_mov_b32_e32 v6, v32
	v_mov_b32_e32 v7, v78
	v_pk_mul_f32 v[6:7], v[18:19], v[6:7]
	v_and_b32_e32 v5, 0xffff0000, v5
	v_and_b32_sdwa v8, v6, v171 dst_sel:DWORD dst_unused:UNUSED_PAD src0_sel:WORD_1 src1_sel:DWORD
	v_mov_b32_e32 v10, v15
	v_mov_b32_e32 v78, v33
	v_or_b32_sdwa v5, v5, v2 dst_sel:DWORD dst_unused:UNUSED_PAD src0_sel:DWORD src1_sel:WORD_1
	v_and_b32_sdwa v2, v7, v171 dst_sel:DWORD dst_unused:UNUSED_PAD src0_sel:WORD_1 src1_sel:DWORD
	v_add3_u32 v6, v6, v8, s76
	v_pk_mul_f32 v[8:9], v[10:11], v[78:79]
	v_add3_u32 v2, v7, v2, s76
	v_lshrrev_b32_e32 v6, 16, v6
	v_and_b32_sdwa v7, v8, v171 dst_sel:DWORD dst_unused:UNUSED_PAD src0_sel:WORD_1 src1_sel:DWORD
	v_and_or_b32 v6, v2, s77, v6
	v_and_b32_sdwa v2, v9, v171 dst_sel:DWORD dst_unused:UNUSED_PAD src0_sel:WORD_1 src1_sel:DWORD
	v_add3_u32 v7, v8, v7, s76
	v_add3_u32 v2, v9, v2, s76
	v_lshrrev_b32_e32 v7, 16, v7
	v_and_or_b32 v7, v2, s77, v7
	s_mov_b64 s[62:63], 0
	global_store_dwordx4 v[86:87], v[88:91], off offset:64
	global_store_dwordx4 v[84:85], v[44:47], off offset:96

.LBB0_573:
	v_or_b32_e32 v40, s8, v83
	v_mul_u32_u24_e32 v40, 0x300, v40
	v_lshlrev_b32_e32 v84, 1, v40
	v_lshl_add_u64 v[40:41], s[48:49], 0, v[84:85]
	s_lshl_b32 s8, s52, 1
	v_lshl_add_u64 v[40:41], v[40:41], 0, s[8:9]
	v_lshlrev_b32_e32 v84, 1, v82
	v_lshl_add_u64 v[98:99], v[40:41], 0, v[84:85]
	s_waitcnt vmcnt(15)
	s_waitcnt vmcnt(13)
	v_mul_f32_e32 v40, v74, v46
	v_mul_f32_e32 v41, v75, v54
	s_waitcnt vmcnt(12)
	s_waitcnt vmcnt(11)
	s_waitcnt vmcnt(9)
	v_mul_f32_e32 v108, v94, v42
	v_mul_f32_e32 v109, v95, v50
	v_mul_f32_e32 v110, v78, v62
	v_mul_f32_e32 v111, v79, v70
	v_mov_b32_e32 v112, v58
	s_waitcnt vmcnt(8)
	v_bfe_u32 v58, v40, 16, 1
	v_bfe_u32 v62, v41, 16, 1
	v_mul_f32_e32 v112, v92, v112
	v_mul_f32_e32 v113, v93, v66
	v_bfe_u32 v50, v109, 16, 1
	v_bfe_u32 v54, v108, 16, 1
	v_bfe_u32 v66, v110, 16, 1
	v_add3_u32 v41, v41, v62, s68
	v_add3_u32 v40, v40, v58, s68
	v_bfe_u32 v46, v112, 16, 1
	v_add3_u32 v54, v108, v54, s68
	v_add3_u32 v50, v109, v50, s68
	v_add3_u32 v66, v110, v66, s68
	v_lshrrev_b32_e32 v40, 16, v40
	v_lshrrev_b32_e32 v41, 16, v41
	s_mov_b32 s8, 0x5180000
	v_add3_u32 v46, v112, v46, s68
	v_lshrrev_b32_e32 v58, 16, v66
	v_and_or_b32 v109, v50, s69, v41
	v_and_or_b32 v108, v54, s69, v40
	v_add_co_u32_e32 v40, vcc, s8, v98
	v_mov_b32_e32 v50, v43
	v_mov_b32_e32 v66, v59
	v_cvt_pk_bf16_f32 v111, v111, v113
	v_and_or_b32 v110, v46, s69, v58
	v_addc_co_u32_e32 v41, vcc, 0, v99, vcc
	v_mov_b32_e32 v54, v47
	v_pk_mul_f32 v[42:43], v[50:51], v[94:95]
	v_mov_b32_e32 v70, v63
	v_pk_mul_f32 v[50:51], v[66:67], v[92:93]
	global_store_dwordx4 v[40:41], v[108:111], off
	v_pk_mul_f32 v[40:41], v[54:55], v[74:75]
	v_pk_mul_f32 v[46:47], v[70:71], v[78:79]
	v_bfe_u32 v54, v51, 16, 1
	v_bfe_u32 v55, v50, 16, 1
	v_bfe_u32 v58, v43, 16, 1
	v_bfe_u32 v59, v42, 16, 1
	v_add3_u32 v59, v42, v59, s68
	v_add3_u32 v58, v43, v58, s68
	v_add3_u32 v42, v50, v55, s68
	v_add3_u32 v43, v51, v54, s68
	v_bfe_u32 v50, v40, 16, 1
	v_bfe_u32 v51, v41, 16, 1
	v_bfe_u32 v54, v46, 16, 1
	v_bfe_u32 v55, v47, 16, 1
	v_add3_u32 v47, v47, v55, s68
	v_add3_u32 v46, v46, v54, s68
	v_add3_u32 v41, v41, v51, s68
	v_add3_u32 v40, v40, v50, s68
	s_mov_b64 s[48:49], 0x5180000
	v_lshrrev_b32_e32 v40, 16, v40
	v_lshrrev_b32_e32 v41, 16, v41
	v_lshrrev_b32_e32 v46, 16, v46
	v_lshrrev_b32_e32 v47, 16, v47
	v_lshl_add_u64 v[86:87], v[98:99], 0, s[48:49]
	v_and_or_b32 v43, v43, s69, v47
	v_and_or_b32 v42, v42, s69, v46
	v_and_or_b32 v41, v58, s69, v41
	v_and_or_b32 v40, v59, s69, v40
	global_store_dwordx4 v[86:87], v[40:43], off offset:1536
	s_nop 1
	v_mul_f32_e32 v42, v94, v44
	s_nop 1
	v_mul_f32_e32 v43, v95, v52
	v_mul_f32_e32 v50, v92, v60
	v_mul_f32_e32 v51, v93, v68
	v_mul_f32_e32 v40, v74, v48
	v_mul_f32_e32 v41, v75, v56
	v_mul_f32_e32 v46, v78, v64
	v_mul_f32_e32 v47, v79, v72
	v_bfe_u32 v44, v51, 16, 1
	v_bfe_u32 v48, v50, 16, 1
	v_bfe_u32 v52, v43, 16, 1
	v_bfe_u32 v54, v42, 16, 1
	v_add3_u32 v54, v42, v54, s68
	v_add3_u32 v52, v43, v52, s68
	v_add3_u32 v42, v50, v48, s68
	v_add3_u32 v43, v51, v44, s68
	v_bfe_u32 v44, v40, 16, 1
	v_bfe_u32 v48, v41, 16, 1
	v_bfe_u32 v50, v46, 16, 1
	v_bfe_u32 v51, v47, 16, 1
	v_add3_u32 v47, v47, v51, s68
	v_add3_u32 v46, v46, v50, s68
	v_add3_u32 v41, v41, v48, s68
	v_add3_u32 v40, v40, v44, s68
	v_lshrrev_b32_e32 v40, 16, v40
	v_lshrrev_b32_e32 v41, 16, v41
	v_lshrrev_b32_e32 v44, 16, v46
	v_lshrrev_b32_e32 v46, 16, v47
	v_and_or_b32 v43, v43, s69, v46
	v_and_or_b32 v42, v42, s69, v44
	v_and_or_b32 v41, v52, s69, v41
	v_and_or_b32 v40, v54, s69, v40
	v_mov_b32_e32 v52, v45
	v_mov_b32_e32 v68, v61
	global_store_dwordx4 v[86:87], v[40:43], off offset:3072
	v_mov_b32_e32 v72, v65
	v_pk_mul_f32 v[46:47], v[68:69], v[92:93]
	v_pk_mul_f32 v[42:43], v[52:53], v[94:95]
	v_mov_b32_e32 v56, v49
	v_pk_mul_f32 v[44:45], v[72:73], v[78:79]
	v_bfe_u32 v48, v47, 16, 1
	v_bfe_u32 v50, v43, 16, 1
	v_pk_mul_f32 v[40:41], v[56:57], v[74:75]
	v_bfe_u32 v49, v46, 16, 1
	v_bfe_u32 v51, v42, 16, 1
	v_add3_u32 v50, v43, v50, s68
	v_add3_u32 v43, v47, v48, s68
	v_bfe_u32 v48, v44, 16, 1
	v_add3_u32 v51, v42, v51, s68
	v_add3_u32 v42, v46, v49, s68
	v_bfe_u32 v46, v40, 16, 1
	v_bfe_u32 v47, v41, 16, 1
	v_bfe_u32 v49, v45, 16, 1
	v_add3_u32 v44, v44, v48, s68
	v_add3_u32 v45, v45, v49, s68
	v_add3_u32 v41, v41, v47, s68
	v_add3_u32 v40, v40, v46, s68
	v_lshrrev_b32_e32 v44, 16, v44
	s_mov_b32 s8, 0x5181000
	v_lshrrev_b32_e32 v40, 16, v40
	v_lshrrev_b32_e32 v41, 16, v41
	v_lshrrev_b32_e32 v45, 16, v45
	v_and_or_b32 v42, v42, s69, v44
	v_add_co_u32_e32 v44, vcc, s8, v98
	v_and_or_b32 v43, v43, s69, v45
	v_and_or_b32 v41, v50, s69, v41
	v_and_or_b32 v40, v51, s69, v40
	v_addc_co_u32_e32 v45, vcc, 0, v99, vcc
	global_store_dwordx4 v[44:45], v[40:43], off offset:512
	s_waitcnt vmcnt(7)
	s_waitcnt vmcnt(5)
	v_mul_f32_e32 v40, v2, v10
	v_mul_f32_e32 v41, v3, v18
	v_mul_f32_e32 v46, v38, v26
	v_mul_f32_e32 v47, v39, v34
	s_waitcnt vmcnt(4)
	v_mul_f32_e32 v42, v80, v6
	v_mul_f32_e32 v43, v81, v14
	v_mul_f32_e32 v48, v76, v22
	v_mul_f32_e32 v49, v77, v30
	v_bfe_u32 v22, v40, 16, 1
	v_bfe_u32 v18, v42, 16, 1
	v_add3_u32 v22, v40, v22, s68
	v_add3_u32 v18, v42, v18, s68
	v_lshrrev_b32_e32 v22, 16, v22
	v_cvt_pk_bf16_f32 v42, v46, v48
	v_cvt_pk_bf16_f32 v41, v41, v43
	v_and_or_b32 v40, v18, s69, v22
	v_mov_b32_e32 v18, v11
	v_mov_b32_e32 v14, v7
	v_mov_b32_e32 v30, v23
	v_cvt_pk_bf16_f32 v43, v47, v49
	v_pk_mul_f32 v[10:11], v[18:19], v[2:3]
	v_pk_mul_f32 v[6:7], v[14:15], v[80:81]
	v_mov_b32_e32 v34, v27
	v_pk_mul_f32 v[18:19], v[30:31], v[76:77]
	v_pk_mul_f32 v[14:15], v[34:35], v[38:39]
	global_store_dwordx4 v[86:87], v[40:43], off offset:32
	s_mov_b64 s[50:51], 0x18000
	v_lshl_add_u64 v[4:5], v[88:89], 0, s[50:51]
	v_cvt_pk_bf16_f32 v43, v15, v19
	v_cvt_pk_bf16_f32 v42, v14, v18
	v_cvt_pk_bf16_f32 v41, v11, v7
	v_cvt_pk_bf16_f32 v40, v10, v6
	v_mul_f32_e32 v10, v80, v8
	v_mul_f32_e32 v11, v81, v16
	v_mul_f32_e32 v18, v76, v24
	v_mul_f32_e32 v19, v77, v32
	v_mul_f32_e32 v6, v2, v12
	v_mul_f32_e32 v7, v3, v20
	v_mul_f32_e32 v14, v38, v28
	v_mul_f32_e32 v15, v39, v36
	v_mov_b32_e32 v32, v25
	global_store_dwordx4 v[86:87], v[40:43], off offset:1568
	s_nop 1
	v_cvt_pk_bf16_f32 v41, v7, v11
	s_nop 1
	v_cvt_pk_bf16_f32 v40, v6, v10
	v_mov_b32_e32 v20, v13
	v_pk_mul_f32 v[10:11], v[32:33], v[76:77]
	v_cvt_pk_bf16_f32 v42, v14, v18
	v_pk_mul_f32 v[2:3], v[20:21], v[2:3]
	v_mov_b32_e32 v16, v9
	v_pk_mul_f32 v[6:7], v[16:17], v[80:81]
	v_mov_b32_e32 v36, v29
	v_cvt_pk_bf16_f32 v43, v15, v19
	v_pk_mul_f32 v[8:9], v[36:37], v[38:39]
	v_cvt_pk_bf16_f32 v6, v2, v6
	v_add_co_u32_e32 v2, vcc, s66, v4
	v_cvt_pk_bf16_f32 v7, v3, v7
	v_addc_co_u32_e32 v3, vcc, 0, v5, vcc
	v_cvt_pk_bf16_f32 v9, v9, v11
	v_cvt_pk_bf16_f32 v8, v8, v10
	v_add_co_u32_e32 v4, vcc, s70, v88
	global_store_dwordx4 v[86:87], v[40:43], off offset:3104
	global_store_dwordx4 v[44:45], v[6:9], off offset:544
	v_addc_co_u32_e32 v5, vcc, 0, v89, vcc
	global_load_dwordx4 v[46:49], v[2:3], off nt
	global_load_dwordx4 v[42:45], v[4:5], off offset:2048 nt
	v_add_co_u32_e32 v2, vcc, s71, v88
	s_mov_b32 s8, 0x34000
	s_nop 0
	v_addc_co_u32_e32 v3, vcc, 0, v89, vcc
	v_add_co_u32_e32 v4, vcc, s8, v88
	s_mov_b32 s8, 0x36000
	s_nop 0
	v_addc_co_u32_e32 v5, vcc, 0, v89, vcc
	global_load_dwordx4 v[54:57], v[2:3], off nt
	global_load_dwordx4 v[50:53], v[4:5], off offset:2048 nt
	v_add_co_u32_e32 v2, vcc, s8, v88
	v_mov_b32_e32 v74, 1.0
	s_nop 0
	v_addc_co_u32_e32 v3, vcc, 0, v89, vcc
	v_add_co_u32_e32 v4, vcc, 0x37000, v88
	v_mov_b32_e32 v94, 1.0
	s_nop 0
	v_addc_co_u32_e32 v5, vcc, 0, v89, vcc
	global_load_dwordx4 v[62:65], v[2:3], off nt
	global_load_dwordx4 v[58:61], v[4:5], off offset:2048 nt
	v_add_co_u32_e32 v2, vcc, 0x39000, v88
	v_mov_b32_e32 v75, 1.0
	s_nop 0
	v_addc_co_u32_e32 v3, vcc, 0, v89, vcc
	v_add_co_u32_e32 v4, vcc, 0x3a000, v88
	v_mov_b32_e32 v95, 1.0
	s_nop 0
	v_addc_co_u32_e32 v5, vcc, 0, v89, vcc
	global_load_dwordx4 v[70:73], v[2:3], off nt
	global_load_dwordx4 v[66:69], v[4:5], off offset:2048 nt
	v_mov_b32_e32 v2, 1.0
	s_and_b64 vcc, exec, s[6:7]
	v_mov_b32_e32 v78, 1.0
	v_mov_b32_e32 v92, 1.0
	v_mov_b32_e32 v79, 1.0
	v_mov_b32_e32 v93, 1.0
	s_cbranch_vccnz .LBB0_575
	global_load_dwordx4 v[74:77], v96, s[10:11] offset:128
	global_load_dwordx4 v[78:81], v96, s[10:11] offset:144
	s_waitcnt vmcnt(1)
	v_mov_b32_e32 v94, v75
	v_mov_b32_e32 v75, v76
	v_mov_b32_e32 v95, v77
	s_waitcnt vmcnt(0)
	v_mov_b32_e32 v92, v79
	v_mov_b32_e32 v79, v80
	v_mov_b32_e32 v93, v81

.LBB0_577:
	s_waitcnt vmcnt(15)
	s_waitcnt vmcnt(13)
	v_mul_f32_e32 v40, v74, v46
	v_mul_f32_e32 v41, v75, v54
	s_waitcnt vmcnt(12)
	s_waitcnt vmcnt(11)
	s_waitcnt vmcnt(9)
	v_mul_f32_e32 v80, v94, v42
	v_mul_f32_e32 v81, v95, v50
	v_mul_f32_e32 v88, v78, v62
	v_mul_f32_e32 v89, v79, v70
	s_waitcnt vmcnt(8)
	v_bfe_u32 v62, v41, 16, 1
	v_mul_f32_e32 v90, v92, v58
	v_mul_f32_e32 v91, v93, v66
	v_bfe_u32 v50, v81, 16, 1
	v_bfe_u32 v58, v40, 16, 1
	v_bfe_u32 v66, v88, 16, 1
	v_bfe_u32 v70, v89, 16, 1
	v_add3_u32 v41, v41, v62, s68
	v_bfe_u32 v42, v91, 16, 1
	v_bfe_u32 v54, v80, 16, 1
	v_add3_u32 v50, v81, v50, s68
	v_add3_u32 v70, v89, v70, s68
	v_add3_u32 v66, v88, v66, s68
	v_add3_u32 v40, v40, v58, s68
	v_lshrrev_b32_e32 v41, 16, v41
	v_bfe_u32 v46, v90, 16, 1
	v_add3_u32 v54, v80, v54, s68
	v_add3_u32 v42, v91, v42, s68
	v_lshrrev_b32_e32 v40, 16, v40
	v_lshrrev_b32_e32 v58, 16, v66
	v_lshrrev_b32_e32 v62, 16, v70
	v_and_or_b32 v89, v50, s69, v41
	v_mov_b32_e32 v50, v43
	v_mov_b32_e32 v66, v59
	v_add3_u32 v46, v90, v46, s68
	v_and_or_b32 v91, v42, s69, v62
	v_and_or_b32 v88, v54, s69, v40
	v_mov_b32_e32 v54, v47
	v_pk_mul_f32 v[42:43], v[50:51], v[94:95]
	v_mov_b32_e32 v70, v63
	v_pk_mul_f32 v[50:51], v[66:67], v[92:93]
	v_and_or_b32 v90, v46, s69, v58
	v_pk_mul_f32 v[40:41], v[54:55], v[74:75]
	v_pk_mul_f32 v[46:47], v[70:71], v[78:79]
	v_bfe_u32 v54, v51, 16, 1
	v_bfe_u32 v55, v50, 16, 1
	v_bfe_u32 v58, v43, 16, 1
	v_bfe_u32 v59, v42, 16, 1
	v_add3_u32 v59, v42, v59, s68
	v_add3_u32 v58, v43, v58, s68
	v_add3_u32 v42, v50, v55, s68
	v_add3_u32 v43, v51, v54, s68
	v_bfe_u32 v50, v40, 16, 1
	v_bfe_u32 v51, v41, 16, 1
	v_bfe_u32 v54, v46, 16, 1
	v_bfe_u32 v55, v47, 16, 1
	v_add3_u32 v47, v47, v55, s68
	v_add3_u32 v46, v46, v54, s68
	v_add3_u32 v41, v41, v51, s68
	v_add3_u32 v40, v40, v50, s68
	v_lshrrev_b32_e32 v40, 16, v40
	v_lshrrev_b32_e32 v41, 16, v41
	v_lshrrev_b32_e32 v46, 16, v46
	v_lshrrev_b32_e32 v47, 16, v47
	v_and_or_b32 v43, v43, s69, v47
	v_and_or_b32 v42, v42, s69, v46
	v_and_or_b32 v41, v58, s69, v41
	v_and_or_b32 v40, v59, s69, v40
	global_store_dwordx4 v[86:87], v[40:43], off offset:1600
	s_nop 1
	v_mul_f32_e32 v42, v94, v44
	s_nop 1
	v_mul_f32_e32 v43, v95, v52
	v_mul_f32_e32 v50, v92, v60
	v_mul_f32_e32 v51, v93, v68
	v_mul_f32_e32 v40, v74, v48
	v_mul_f32_e32 v41, v75, v56
	v_mul_f32_e32 v46, v78, v64
	v_mul_f32_e32 v47, v79, v72
	v_bfe_u32 v44, v51, 16, 1
	v_bfe_u32 v48, v50, 16, 1
	v_bfe_u32 v52, v43, 16, 1
	v_bfe_u32 v54, v42, 16, 1
	v_add3_u32 v54, v42, v54, s68
	v_add3_u32 v52, v43, v52, s68
	v_add3_u32 v42, v50, v48, s68
	v_add3_u32 v43, v51, v44, s68
	v_bfe_u32 v44, v40, 16, 1
	v_bfe_u32 v48, v41, 16, 1
	v_bfe_u32 v50, v46, 16, 1
	v_bfe_u32 v51, v47, 16, 1
	v_add3_u32 v47, v47, v51, s68
	v_add3_u32 v46, v46, v50, s68
	v_add3_u32 v41, v41, v48, s68
	v_add3_u32 v40, v40, v44, s68
	v_lshrrev_b32_e32 v40, 16, v40
	v_lshrrev_b32_e32 v41, 16, v41
	v_lshrrev_b32_e32 v44, 16, v46
	v_lshrrev_b32_e32 v46, 16, v47
	v_and_or_b32 v43, v43, s69, v46
	v_and_or_b32 v42, v42, s69, v44
	v_and_or_b32 v41, v52, s69, v41
	v_and_or_b32 v40, v54, s69, v40
	v_mov_b32_e32 v52, v45
	v_mov_b32_e32 v68, v61
	global_store_dwordx4 v[86:87], v[40:43], off offset:3136
	v_mov_b32_e32 v72, v65
	v_pk_mul_f32 v[46:47], v[68:69], v[92:93]
	v_pk_mul_f32 v[42:43], v[52:53], v[94:95]
	v_mov_b32_e32 v56, v49
	v_pk_mul_f32 v[44:45], v[72:73], v[78:79]
	v_bfe_u32 v48, v47, 16, 1
	v_bfe_u32 v50, v43, 16, 1
	v_pk_mul_f32 v[40:41], v[56:57], v[74:75]
	v_bfe_u32 v49, v46, 16, 1
	v_bfe_u32 v51, v42, 16, 1
	v_add3_u32 v50, v43, v50, s68
	v_add3_u32 v43, v47, v48, s68
	v_bfe_u32 v48, v44, 16, 1
	v_add3_u32 v51, v42, v51, s68
	v_add3_u32 v42, v46, v49, s68
	v_bfe_u32 v46, v40, 16, 1
	v_bfe_u32 v47, v41, 16, 1
	v_bfe_u32 v49, v45, 16, 1
	v_add3_u32 v44, v44, v48, s68
	v_add3_u32 v45, v45, v49, s68
	v_add3_u32 v41, v41, v47, s68
	v_add3_u32 v40, v40, v46, s68
	v_lshrrev_b32_e32 v44, 16, v44
	v_lshrrev_b32_e32 v40, 16, v40
	v_lshrrev_b32_e32 v41, 16, v41
	v_lshrrev_b32_e32 v45, 16, v45
	v_and_or_b32 v42, v42, s69, v44
	v_add_co_u32_e32 v44, vcc, s61, v86
	v_and_or_b32 v43, v43, s69, v45
	v_and_or_b32 v41, v50, s69, v41
	v_and_or_b32 v40, v51, s69, v40
	v_addc_co_u32_e32 v45, vcc, 0, v87, vcc
	global_store_dwordx4 v[44:45], v[40:43], off offset:576
	s_waitcnt vmcnt(6)
	s_waitcnt vmcnt(4)
	v_mul_f32_e32 v40, v2, v10
	v_mul_f32_e32 v41, v3, v18
	v_mul_f32_e32 v46, v38, v26
	v_mul_f32_e32 v47, v39, v34
	s_waitcnt vmcnt(3)
	v_mul_f32_e32 v42, v76, v6
	v_mul_f32_e32 v43, v77, v14
	v_mul_f32_e32 v48, v4, v22
	v_mul_f32_e32 v49, v5, v30
	v_bfe_u32 v22, v40, 16, 1
	v_bfe_u32 v18, v42, 16, 1
	v_add3_u32 v22, v40, v22, s68
	v_add3_u32 v18, v42, v18, s68
	v_lshrrev_b32_e32 v22, 16, v22
	v_cvt_pk_bf16_f32 v42, v46, v48
	v_cvt_pk_bf16_f32 v41, v41, v43
	v_and_or_b32 v40, v18, s69, v22
	v_mov_b32_e32 v18, v11
	v_mov_b32_e32 v14, v7
	v_mov_b32_e32 v30, v23
	v_cvt_pk_bf16_f32 v43, v47, v49
	v_pk_mul_f32 v[10:11], v[18:19], v[2:3]
	v_pk_mul_f32 v[6:7], v[14:15], v[76:77]
	v_mov_b32_e32 v34, v27
	v_pk_mul_f32 v[18:19], v[30:31], v[4:5]
	v_pk_mul_f32 v[14:15], v[34:35], v[38:39]
	global_store_dwordx4 v[86:87], v[40:43], off offset:96
	global_store_dwordx4 v[86:87], v[88:91], off offset:64
	s_mov_b64 s[6:7], 0
	v_cvt_pk_bf16_f32 v43, v15, v19
	v_cvt_pk_bf16_f32 v42, v14, v18
	v_cvt_pk_bf16_f32 v41, v11, v7
	v_cvt_pk_bf16_f32 v40, v10, v6
	v_mul_f32_e32 v10, v76, v8
	v_mul_f32_e32 v11, v77, v16
	v_mul_f32_e32 v18, v4, v24
	v_mul_f32_e32 v19, v5, v32
	v_mul_f32_e32 v6, v2, v12
	v_mul_f32_e32 v7, v3, v20
	v_bfe_u32 v12, v18, 16, 1
	v_bfe_u32 v16, v11, 16, 1
	v_mul_f32_e32 v14, v38, v28
	v_mul_f32_e32 v15, v39, v36
	v_bfe_u32 v8, v19, 16, 1
	v_bfe_u32 v20, v10, 16, 1
	v_add3_u32 v11, v11, v16, s68
	v_add3_u32 v12, v18, v12, s68
	v_bfe_u32 v16, v6, 16, 1
	v_bfe_u32 v18, v7, 16, 1
	v_add3_u32 v10, v10, v20, s68
	v_add3_u32 v8, v19, v8, s68
	v_bfe_u32 v19, v14, 16, 1
	v_bfe_u32 v20, v15, 16, 1
	v_add3_u32 v7, v7, v18, s68
	v_add3_u32 v6, v6, v16, s68
	v_add3_u32 v15, v15, v20, s68
	v_add3_u32 v14, v14, v19, s68
	v_lshrrev_b32_e32 v6, 16, v6
	v_lshrrev_b32_e32 v7, 16, v7
	v_mov_b32_e32 v16, v9
	v_mov_b32_e32 v32, v25
	global_store_dwordx4 v[86:87], v[40:43], off offset:1632
	v_lshrrev_b32_e32 v14, 16, v14
	v_lshrrev_b32_e32 v15, 16, v15
	v_and_or_b32 v41, v11, s69, v7
	v_and_or_b32 v40, v10, s69, v6
	v_mov_b32_e32 v20, v13
	v_pk_mul_f32 v[6:7], v[16:17], v[76:77]
	v_mov_b32_e32 v36, v29
	v_pk_mul_f32 v[4:5], v[32:33], v[4:5]
	v_and_or_b32 v43, v8, s69, v15
	v_and_or_b32 v42, v12, s69, v14
	v_pk_mul_f32 v[2:3], v[20:21], v[2:3]
	v_pk_mul_f32 v[8:9], v[36:37], v[38:39]
	v_cvt_pk_bf16_f32 v5, v9, v5
	v_cvt_pk_bf16_f32 v4, v8, v4
	v_cvt_pk_bf16_f32 v3, v3, v7
	v_cvt_pk_bf16_f32 v2, v2, v6
	global_store_dwordx4 v[86:87], v[40:43], off offset:3168
	global_store_dwordx4 v[44:45], v[2:5], off offset:608
.LBB0_578:
	s_mov_b32 s8, 0
	s_and_b64 vcc, exec, s[6:7]
	s_cbranch_vccz .LBB0_580
	s_mov_b64 s[6:7], s[0:1]
	s_load_dwordx2 s[10:11], s[6:7], 0x78
	s_mov_b64 s[6:7], s[0:1]
	s_load_dwordx2 s[48:49], s[6:7], 0xa8
	s_mov_b64 s[6:7], s[0:1]
	s_load_dwordx2 s[6:7], s[6:7], 0x20
	s_waitcnt lgkmcnt(0)
	s_add_u32 s6, s6, 0x1000
	s_addc_u32 s7, s7, 0
	s_add_i32 s8, s77, 32
	s_and_b32 s50, s8, 0xff
	s_mulk_i32 s50, 0xab
	s_lshr_b32 s50, s50, 10
	s_mul_i32 s51, s50, 6
	s_sub_i32 s8, s8, s51
	s_and_b32 s8, s8, 0xff
	v_lshl_or_b32 v4, s8, 7, v83
	v_lshlrev_b32_e32 v84, 11, v4
	v_lshl_add_u64 v[2:3], s[48:49], 0, v[84:85]
	s_lshl_b32 s8, s50, 7
	v_lshl_add_u64 v[2:3], v[2:3], 0, s[8:9]
	v_lshlrev_b32_e32 v84, 1, v82
	v_lshl_or_b32 v72, s50, 6, v82
	v_lshl_add_u64 v[98:99], v[2:3], 0, v[84:85]
	v_lshlrev_b32_e32 v84, 2, v4
	v_mul_u32_u24_e32 v4, 0x300, v72
	v_lshl_add_u64 v[70:71], s[10:11], 0, v[84:85]
	v_lshlrev_b32_e32 v84, 2, v4
	v_mad_u64_u32 v[2:3], s[10:11], v72, s73, v[70:71]
	v_lshl_add_u64 v[68:69], v[70:71], 0, v[84:85]
	global_load_dwordx4 v[46:49], v[2:3], off nt
	global_load_dwordx4 v[42:45], v[68:69], off offset:3072 nt
	v_add_co_u32_e32 v2, vcc, s61, v68
	s_mov_b32 s8, 0xc000
	s_nop 0
	v_addc_co_u32_e32 v3, vcc, 0, v69, vcc
	v_add_co_u32_e32 v4, vcc, s74, v68
	v_or_b32_e32 v10, 16, v72
	s_nop 0
	v_addc_co_u32_e32 v5, vcc, 0, v69, vcc
	global_load_dwordx4 v[54:57], v[2:3], off offset:2048 nt
	global_load_dwordx4 v[50:53], v[4:5], off offset:1024 nt
	v_lshlrev_b32_e32 v2, 2, v72
	global_load_dwordx4 v[58:61], v2, s[6:7] offset:16
	global_load_dwordx4 v[74:77], v2, s[6:7]
	v_add_co_u32_e32 v2, vcc, s62, v68
	s_mov_b64 s[10:11], 0x5000000
	s_nop 0
	v_addc_co_u32_e32 v3, vcc, 0, v69, vcc
	global_load_dwordx4 v[78:81], v[2:3], off nt
	global_load_dwordx4 v[62:65], v[2:3], off offset:3072 nt
	v_add_co_u32_e32 v2, vcc, s63, v68
	v_lshlrev_b32_e32 v6, 2, v10
	s_nop 0
	v_addc_co_u32_e32 v3, vcc, 0, v69, vcc
	global_load_dwordx4 v[86:89], v[2:3], off offset:2048 nt
	v_add_co_u32_e32 v2, vcc, s75, v68
	v_lshl_add_u64 v[66:67], v[98:99], 0, s[10:11]
	s_nop 0
	v_addc_co_u32_e32 v3, vcc, 0, v69, vcc
	global_load_dwordx4 v[90:93], v[2:3], off offset:1024 nt
	v_add_co_u32_e32 v12, vcc, s8, v68
	s_mov_b32 s8, 0xd000
	s_nop 0
	v_addc_co_u32_e32 v13, vcc, 0, v69, vcc
	v_add_co_u32_e32 v14, vcc, s8, v68
	s_mov_b32 s8, 0x10000
	s_nop 0
	v_addc_co_u32_e32 v15, vcc, 0, v69, vcc
	v_add_co_u32_e32 v16, vcc, s78, v68
	v_mad_u64_u32 v[10:11], s[10:11], v10, s73, v[70:71]
	s_nop 0
	v_addc_co_u32_e32 v17, vcc, 0, v69, vcc
	v_add_co_u32_e32 v26, vcc, s80, v68
	global_load_dwordx4 v[2:5], v6, s[6:7] offset:16
	s_nop 0
	global_load_dwordx4 v[6:9], v6, s[6:7]
	v_addc_co_u32_e32 v27, vcc, 0, v69, vcc
	v_add_co_u32_e32 v28, vcc, s8, v68
	s_mov_b32 s8, 0x5001000
	s_nop 0
	v_addc_co_u32_e32 v29, vcc, 0, v69, vcc
	v_add_co_u32_e32 v94, vcc, s79, v68
	s_waitcnt vmcnt(10)
	v_mov_b32_e32 v96, v42
	v_addc_co_u32_e32 v95, vcc, 0, v69, vcc
	global_load_dwordx4 v[18:21], v[10:11], off nt
	global_load_dwordx4 v[30:33], v[12:13], off offset:3072 nt
	global_load_dwordx4 v[38:41], v[14:15], off offset:2048 nt
	global_load_dwordx4 v[34:37], v[16:17], off offset:1024 nt
	global_load_dwordx4 v[22:25], v[26:27], off nt
	s_nop 0
	global_load_dwordx4 v[10:13], v[26:27], off offset:3072 nt
	s_nop 0
	global_load_dwordx4 v[26:29], v[28:29], off offset:2048 nt
	s_nop 0
	global_load_dwordx4 v[14:17], v[94:95], off offset:1024 nt
	s_waitcnt vmcnt(17)
	s_waitcnt vmcnt(16)
	v_mov_b32_e32 v97, v50
	s_waitcnt vmcnt(15)
	v_mov_b32_e32 v111, v60
	s_waitcnt vmcnt(14)
	v_mov_b32_e32 v108, v74
	v_mov_b32_e32 v109, v76
	v_mov_b32_e32 v76, v75
	v_mov_b32_e32 v60, v59
	v_mul_f32_e32 v94, v108, v46
	v_mul_f32_e32 v95, v109, v54
	v_pk_mul_f32 v[74:75], v[96:97], v[76:77]
	s_waitcnt vmcnt(12)
	v_mov_b32_e32 v112, v62
	v_mov_b32_e32 v110, v58
	s_waitcnt vmcnt(11)
	v_mul_f32_e32 v96, v110, v78
	v_mul_f32_e32 v97, v111, v86
	s_waitcnt vmcnt(10)
	v_mov_b32_e32 v113, v90
	v_pk_mul_f32 v[58:59], v[112:113], v[60:61]
	v_cvt_pk_bf16_f32 v95, v95, v75
	v_cvt_pk_bf16_f32 v94, v94, v74
	v_mov_b32_e32 v54, v47
	v_mov_b32_e32 v50, v43
	v_mov_b32_e32 v90, v63
	v_cvt_pk_bf16_f32 v97, v97, v59
	v_cvt_pk_bf16_f32 v96, v96, v58
	v_pk_mul_f32 v[46:47], v[54:55], v[108:109]
	v_pk_mul_f32 v[42:43], v[50:51], v[76:77]
	v_mov_b32_e32 v86, v79
	v_pk_mul_f32 v[54:55], v[90:91], v[60:61]
	v_pk_mul_f32 v[50:51], v[86:87], v[110:111]
	v_add_co_u32_e32 v58, vcc, s8, v98
	v_addc_co_u32_e32 v59, vcc, 0, v99, vcc
	global_store_dwordx4 v[58:59], v[94:97], off offset:-4096
	s_mov_b32 s8, 0x19000
	s_nop 0
	v_cvt_pk_bf16_f32 v97, v51, v55
	v_cvt_pk_bf16_f32 v96, v50, v54
	v_cvt_pk_bf16_f32 v95, v47, v43
	v_cvt_pk_bf16_f32 v94, v46, v42
	v_mul_f32_e32 v46, v76, v44
	v_mul_f32_e32 v47, v77, v52
	v_mul_f32_e32 v54, v60, v64
	v_mul_f32_e32 v55, v61, v92
	v_mov_b32_e32 v42, v48
	v_mul_f32_e32 v50, v110, v80
	v_mul_f32_e32 v51, v111, v88
	v_bfe_u32 v48, v54, 16, 1
	v_bfe_u32 v52, v47, 16, 1
	v_mul_f32_e32 v42, v108, v42
	v_mul_f32_e32 v43, v109, v56
	v_bfe_u32 v44, v55, 16, 1
	v_bfe_u32 v56, v46, 16, 1
	v_add3_u32 v48, v54, v48, s68
	v_add3_u32 v47, v47, v52, s68
	v_bfe_u32 v52, v50, 16, 1
	v_bfe_u32 v54, v51, 16, 1
	v_add3_u32 v44, v55, v44, s68
	v_add3_u32 v46, v46, v56, s68
	v_bfe_u32 v55, v42, 16, 1
	v_bfe_u32 v56, v43, 16, 1
	v_add3_u32 v51, v51, v54, s68
	v_add3_u32 v50, v50, v52, s68
	v_add3_u32 v43, v43, v56, s68
	v_add3_u32 v42, v42, v55, s68
	v_lshrrev_b32_e32 v50, 16, v50
	v_lshrrev_b32_e32 v51, 16, v51
	v_mov_b32_e32 v52, v45
	v_mov_b32_e32 v92, v65
	global_store_dwordx4 v[66:67], v[94:97], off offset:2048
	v_lshrrev_b32_e32 v42, 16, v42
	v_lshrrev_b32_e32 v43, 16, v43
	v_and_or_b32 v97, v44, s69, v51
	v_and_or_b32 v96, v48, s69, v50
	v_mov_b32_e32 v56, v49
	v_pk_mul_f32 v[44:45], v[52:53], v[76:77]
	v_mov_b32_e32 v88, v81
	v_pk_mul_f32 v[48:49], v[92:93], v[60:61]
	v_and_or_b32 v95, v47, s69, v43
	v_and_or_b32 v94, v46, s69, v42
	v_pk_mul_f32 v[42:43], v[56:57], v[108:109]
	v_pk_mul_f32 v[46:47], v[88:89], v[110:111]
	v_bfe_u32 v50, v49, 16, 1
	v_bfe_u32 v51, v48, 16, 1
	v_bfe_u32 v52, v45, 16, 1
	v_bfe_u32 v53, v44, 16, 1
	v_add3_u32 v48, v48, v51, s68
	v_add3_u32 v49, v49, v50, s68
	v_add3_u32 v50, v44, v53, s68
	v_add3_u32 v51, v45, v52, s68
	v_bfe_u32 v44, v46, 16, 1
	v_bfe_u32 v45, v47, 16, 1
	v_bfe_u32 v52, v42, 16, 1
	v_bfe_u32 v53, v43, 16, 1
	v_add3_u32 v45, v47, v45, s68
	v_add3_u32 v44, v46, v44, s68
	v_add3_u32 v43, v43, v53, s68
	v_add3_u32 v42, v42, v52, s68
	v_lshrrev_b32_e32 v44, 16, v44
	v_lshrrev_b32_e32 v45, 16, v45
	v_lshrrev_b32_e32 v42, 16, v42
	v_lshrrev_b32_e32 v43, 16, v43
	v_and_or_b32 v45, v49, s69, v45
	v_and_or_b32 v44, v48, s69, v44
	v_and_or_b32 v43, v51, s69, v43
	v_and_or_b32 v42, v50, s69, v42
	global_store_dwordx4 v[58:59], v[42:45], off offset:2048
	s_waitcnt vmcnt(11)
	v_mov_b32_e32 v47, v8
	v_mov_b32_e32 v8, v7
	s_waitcnt vmcnt(9)
	v_mov_b32_e32 v44, v30
	s_waitcnt vmcnt(7)
	v_mov_b32_e32 v45, v34
	v_mov_b32_e32 v49, v4
	s_waitcnt vmcnt(5)
	v_mov_b32_e32 v50, v10
	s_waitcnt vmcnt(3)
	v_mov_b32_e32 v51, v14
	v_mov_b32_e32 v4, v3
	v_mov_b32_e32 v46, v6
	v_pk_mul_f32 v[6:7], v[44:45], v[8:9]
	v_mov_b32_e32 v48, v2
	v_pk_mul_f32 v[2:3], v[50:51], v[4:5]
	v_mul_f32_e32 v42, v46, v18
	v_mul_f32_e32 v43, v47, v38
	v_mul_f32_e32 v44, v48, v22
	v_mul_f32_e32 v45, v49, v26
	v_bfe_u32 v14, v2, 16, 1
	v_bfe_u32 v18, v7, 16, 1
	v_bfe_u32 v10, v3, 16, 1
	v_add3_u32 v7, v7, v18, s68
	v_add3_u32 v2, v2, v14, s68
	v_bfe_u32 v14, v45, 16, 1
	v_bfe_u32 v22, v43, 16, 1
	v_add3_u32 v3, v3, v10, s68
	v_bfe_u32 v10, v44, 16, 1
	v_add3_u32 v14, v45, v14, s68
	v_add3_u32 v22, v43, v22, s68
	v_add3_u32 v10, v44, v10, s68
	v_lshrrev_b32_e32 v14, 16, v14
	v_lshrrev_b32_e32 v22, 16, v22
	v_mov_b32_e32 v34, v31
	v_lshrrev_b32_e32 v10, 16, v10
	v_and_or_b32 v45, v3, s69, v14
	v_and_or_b32 v43, v7, s69, v22
	v_cvt_pk_bf16_f32 v42, v42, v6
	v_mov_b32_e32 v38, v19
	v_pk_mul_f32 v[6:7], v[34:35], v[8:9]
	v_mov_b32_e32 v14, v11
	v_and_or_b32 v44, v2, s69, v10
	v_pk_mul_f32 v[2:3], v[38:39], v[46:47]
	v_mov_b32_e32 v26, v23
	v_pk_mul_f32 v[10:11], v[14:15], v[4:5]
	v_pk_mul_f32 v[18:19], v[26:27], v[48:49]
	v_bfe_u32 v14, v11, 16, 1
	v_add3_u32 v11, v11, v14, s68
	v_bfe_u32 v15, v19, 16, 1
	v_add3_u32 v15, v19, v15, s68
	global_store_dwordx4 v[66:67], v[42:45], off offset:32
	v_lshrrev_b32_e32 v15, 16, v15
	s_nop 1
	v_cvt_pk_bf16_f32 v43, v3, v7
	v_cvt_pk_bf16_f32 v42, v2, v6
	v_and_or_b32 v45, v11, s69, v15
	v_cvt_pk_bf16_f32 v44, v18, v10
	v_mul_f32_e32 v6, v8, v32
	v_mul_f32_e32 v7, v9, v36
	v_mul_f32_e32 v2, v46, v20
	v_mul_f32_e32 v3, v47, v40
	v_mul_f32_e32 v14, v4, v12
	v_mul_f32_e32 v15, v5, v16
	v_mul_f32_e32 v10, v48, v24
	v_mul_f32_e32 v11, v49, v28
	v_bfe_u32 v12, v15, 16, 1
	v_add3_u32 v12, v15, v12, s68
	v_bfe_u32 v16, v11, 16, 1
	v_add3_u32 v11, v11, v16, s68
	v_mov_b32_e32 v36, v33
	v_mov_b32_e32 v16, v13
	global_store_dwordx4 v[66:67], v[42:45], off offset:2080
	v_lshrrev_b32_e32 v11, 16, v11
	s_nop 1
	v_cvt_pk_bf16_f32 v43, v3, v7
	v_cvt_pk_bf16_f32 v42, v2, v6
	v_mov_b32_e32 v40, v21
	v_pk_mul_f32 v[6:7], v[36:37], v[8:9]
	v_mov_b32_e32 v28, v25
	v_pk_mul_f32 v[4:5], v[16:17], v[4:5]
	v_and_or_b32 v45, v12, s69, v11
	v_cvt_pk_bf16_f32 v44, v10, v14
	v_pk_mul_f32 v[2:3], v[40:41], v[46:47]
	v_pk_mul_f32 v[8:9], v[28:29], v[48:49]
	v_cvt_pk_bf16_f32 v5, v9, v5
	v_cvt_pk_bf16_f32 v4, v8, v4
	v_cvt_pk_bf16_f32 v3, v3, v7
	v_cvt_pk_bf16_f32 v2, v2, v6
	global_store_dwordx4 v[58:59], v[2:5], off offset:2080
	v_or_b32_e32 v6, 32, v72
	global_store_dwordx4 v[58:59], v[94:97], off
	v_add_co_u32_e32 v4, vcc, s66, v68
	global_store_dwordx4 v[58:59], v[42:45], off offset:32
	v_mad_u64_u32 v[2:3], s[10:11], v6, s73, v[70:71]
	v_addc_co_u32_e32 v5, vcc, 0, v69, vcc
	global_load_dwordx4 v[42:45], v[2:3], off nt
	global_load_dwordx4 v[46:49], v[4:5], off offset:3072 nt
	v_add_co_u32_e32 v2, vcc, s8, v68
	s_mov_b32 s8, 0x1a000
	s_nop 0
	v_addc_co_u32_e32 v3, vcc, 0, v69, vcc
	v_add_co_u32_e32 v4, vcc, s8, v68
	s_mov_b32 s8, 0x1b000
	s_nop 0
	v_addc_co_u32_e32 v5, vcc, 0, v69, vcc
	global_load_dwordx4 v[50:53], v[2:3], off offset:2048 nt
	global_load_dwordx4 v[54:57], v[4:5], off offset:1024 nt
	v_lshlrev_b32_e32 v2, 2, v6
	global_load_dwordx4 v[60:63], v2, s[6:7] offset:16
	global_load_dwordx4 v[74:77], v2, s[6:7]
	v_add_co_u32_e32 v2, vcc, s8, v68
	s_mov_b32 s8, 0x1c000
	s_nop 0
	v_addc_co_u32_e32 v3, vcc, 0, v69, vcc
	global_load_dwordx4 v[78:81], v[2:3], off nt
	global_load_dwordx4 v[86:89], v[2:3], off offset:3072 nt
	v_add_co_u32_e32 v2, vcc, s8, v68
	v_or_b32_e32 v34, 48, v72
	s_nop 0
	v_addc_co_u32_e32 v3, vcc, 0, v69, vcc
	global_load_dwordx4 v[90:93], v[2:3], off offset:2048 nt
	v_add_co_u32_e32 v2, vcc, s82, v68
	v_lshlrev_b32_e32 v38, 2, v34
	s_nop 0
	v_addc_co_u32_e32 v3, vcc, 0, v69, vcc
	global_load_dwordx4 v[94:97], v[2:3], off offset:1024 nt
	v_add_co_u32_e32 v4, vcc, s83, v68
	v_mad_u64_u32 v[2:3], s[10:11], v34, s73, v[70:71]
	s_nop 0
	v_addc_co_u32_e32 v5, vcc, 0, v69, vcc
	v_add_co_u32_e32 v10, vcc, s84, v68
	global_load_dwordx4 v[6:9], v[2:3], off nt
	s_nop 0
	global_load_dwordx4 v[2:5], v[4:5], off offset:3072 nt
	v_addc_co_u32_e32 v11, vcc, 0, v69, vcc
	v_add_co_u32_e32 v12, vcc, s85, v68
	s_mov_b32 s8, 4
	s_nop 0
	v_addc_co_u32_e32 v13, vcc, 0, v69, vcc
	v_add_co_u32_e32 v14, vcc, s86, v68
	global_load_dwordx4 v[18:21], v[10:11], off offset:2048 nt
	s_nop 0
	global_load_dwordx4 v[10:13], v[12:13], off offset:1024 nt
	v_addc_co_u32_e32 v15, vcc, 0, v69, vcc
	v_add_co_u32_e32 v26, vcc, s87, v68
	global_load_dwordx4 v[22:25], v[14:15], off nt
	s_nop 0
	global_load_dwordx4 v[14:17], v[14:15], off offset:3072 nt
	v_addc_co_u32_e32 v27, vcc, 0, v69, vcc
	v_add_co_u32_e32 v28, vcc, s88, v68
	s_waitcnt vmcnt(15)
	v_addc_co_u32_e32 v29, vcc, 0, v69, vcc
	global_load_dwordx4 v[30:33], v[26:27], off offset:2048 nt
	s_nop 0
	global_load_dwordx4 v[26:29], v[28:29], off offset:1024 nt
	s_nop 0
	global_load_dwordx4 v[34:37], v38, s[6:7] offset:16
	s_nop 0
	global_load_dwordx4 v[38:41], v38, s[6:7]
	s_waitcnt vmcnt(18)
	s_waitcnt vmcnt(17)
	s_waitcnt vmcnt(16)
	s_waitcnt vmcnt(14)
	v_mov_b32_e32 v73, v76
	v_mov_b32_e32 v76, v75
	v_mov_b32_e32 v72, v74
	v_mul_f32_e32 v68, v76, v46
	v_mul_f32_e32 v69, v77, v54
	v_mov_b32_e32 v75, v62
	v_mov_b32_e32 v62, v61
	s_waitcnt vmcnt(12)
	v_mov_b32_e32 v98, v86
	v_mul_f32_e32 v64, v72, v42
	v_mul_f32_e32 v65, v73, v50
	v_mov_b32_e32 v74, v60
	s_waitcnt vmcnt(11)
	v_mul_f32_e32 v70, v74, v78
	v_mul_f32_e32 v71, v75, v90
	s_waitcnt vmcnt(10)
	v_mov_b32_e32 v99, v94
	v_pk_mul_f32 v[60:61], v[98:99], v[62:63]
	v_cvt_pk_bf16_f32 v68, v64, v68
	v_mov_b32_e32 v54, v47
	v_mov_b32_e32 v94, v87
	v_cvt_pk_bf16_f32 v70, v70, v60
	v_cvt_pk_bf16_f32 v69, v65, v69
	v_mov_b32_e32 v50, v43
	v_pk_mul_f32 v[46:47], v[54:55], v[76:77]
	v_mov_b32_e32 v90, v79
	v_pk_mul_f32 v[54:55], v[94:95], v[62:63]
	v_cvt_pk_bf16_f32 v71, v71, v61
	v_pk_mul_f32 v[42:43], v[50:51], v[72:73]
	v_pk_mul_f32 v[50:51], v[90:91], v[74:75]
	global_store_dwordx4 v[66:67], v[68:71], off offset:64
	s_nop 1
	v_cvt_pk_bf16_f32 v71, v51, v55
	v_cvt_pk_bf16_f32 v70, v50, v54
	v_cvt_pk_bf16_f32 v69, v43, v47
	v_cvt_pk_bf16_f32 v68, v42, v46
	v_mul_f32_e32 v46, v76, v48
	v_mul_f32_e32 v47, v77, v56
	v_mul_f32_e32 v54, v62, v88
	v_mul_f32_e32 v55, v63, v96
	v_mov_b32_e32 v43, v52
	v_mul_f32_e32 v50, v74, v80
	v_mul_f32_e32 v51, v75, v92
	v_bfe_u32 v48, v54, 16, 1
	v_bfe_u32 v52, v47, 16, 1
	v_mul_f32_e32 v42, v72, v44
	v_mul_f32_e32 v43, v73, v43
	v_bfe_u32 v44, v55, 16, 1
	v_add3_u32 v47, v47, v52, s68
	v_add3_u32 v48, v54, v48, s68
	v_bfe_u32 v52, v50, 16, 1
	v_bfe_u32 v54, v51, 16, 1
	v_add3_u32 v44, v55, v44, s68
	v_bfe_u32 v56, v43, 16, 1
	v_add3_u32 v51, v51, v54, s68
	v_add3_u32 v50, v50, v52, s68
	v_add3_u32 v43, v43, v56, s68
	v_lshrrev_b32_e32 v50, 16, v50
	v_lshrrev_b32_e32 v51, 16, v51
	v_mov_b32_e32 v56, v49
	v_mov_b32_e32 v96, v89
	global_store_dwordx4 v[66:67], v[68:71], off offset:2112
	v_lshrrev_b32_e32 v43, 16, v43
	s_nop 1
	v_and_or_b32 v71, v44, s69, v51
	v_and_or_b32 v70, v48, s69, v50
	v_mov_b32_e32 v52, v45
	v_pk_mul_f32 v[44:45], v[56:57], v[76:77]
	v_mov_b32_e32 v92, v81
	v_pk_mul_f32 v[48:49], v[96:97], v[62:63]
	v_and_or_b32 v69, v47, s69, v43
	v_cvt_pk_bf16_f32 v68, v42, v46
	v_pk_mul_f32 v[42:43], v[52:53], v[72:73]
	v_pk_mul_f32 v[46:47], v[92:93], v[74:75]
	v_bfe_u32 v52, v45, 16, 1
	v_bfe_u32 v53, v44, 16, 1
	v_add3_u32 v53, v44, v53, s68
	v_add3_u32 v52, v45, v52, s68
	v_bfe_u32 v50, v42, 16, 1
	v_bfe_u32 v51, v43, 16, 1
	v_add3_u32 v43, v43, v51, s68
	v_add3_u32 v42, v42, v50, s68
	v_lshrrev_b32_e32 v42, 16, v42
	v_lshrrev_b32_e32 v43, 16, v43
	v_cvt_pk_bf16_f32 v45, v47, v49
	v_cvt_pk_bf16_f32 v44, v46, v48
	v_and_or_b32 v43, v52, s69, v43
	v_and_or_b32 v42, v53, s69, v42
	global_store_dwordx4 v[58:59], v[42:45], off offset:2112
	s_waitcnt vmcnt(3)
	v_mov_b32_e32 v46, v38
	v_mov_b32_e32 v47, v40
	v_mov_b32_e32 v44, v2
	v_mov_b32_e32 v45, v10
	v_mov_b32_e32 v40, v39
	v_mul_f32_e32 v42, v46, v6
	v_mul_f32_e32 v43, v47, v18
	v_pk_mul_f32 v[38:39], v[44:45], v[40:41]
	v_mov_b32_e32 v48, v34
	v_mov_b32_e32 v49, v36
	v_mul_f32_e32 v44, v48, v22
	v_mul_f32_e32 v45, v49, v30
	v_mov_b32_e32 v50, v14
	v_mov_b32_e32 v51, v26
	v_mov_b32_e32 v36, v35
	v_pk_mul_f32 v[34:35], v[50:51], v[36:37]
	v_cvt_pk_bf16_f32 v43, v43, v39
	v_cvt_pk_bf16_f32 v42, v42, v38
	v_mov_b32_e32 v10, v3
	v_mov_b32_e32 v26, v15
	v_cvt_pk_bf16_f32 v45, v45, v35
	v_cvt_pk_bf16_f32 v44, v44, v34
	v_mov_b32_e32 v18, v7
	v_pk_mul_f32 v[2:3], v[10:11], v[40:41]
	v_mov_b32_e32 v30, v23
	v_pk_mul_f32 v[14:15], v[26:27], v[36:37]
	v_pk_mul_f32 v[6:7], v[18:19], v[46:47]
	v_pk_mul_f32 v[10:11], v[30:31], v[48:49]
	global_store_dwordx4 v[66:67], v[42:45], off offset:96
	global_store_dwordx4 v[58:59], v[68:71], off offset:64
	s_nop 0
	v_cvt_pk_bf16_f32 v45, v11, v15
	v_cvt_pk_bf16_f32 v44, v10, v14
	v_cvt_pk_bf16_f32 v43, v7, v3
	v_cvt_pk_bf16_f32 v42, v6, v2
	v_mul_f32_e32 v6, v40, v4
	v_mul_f32_e32 v7, v41, v12
	v_mul_f32_e32 v14, v36, v16
	v_mul_f32_e32 v15, v37, v28
	v_mov_b32_e32 v2, v8
	v_mul_f32_e32 v10, v48, v24
	v_mul_f32_e32 v11, v49, v32
	v_bfe_u32 v8, v14, 16, 1
	v_mul_f32_e32 v2, v46, v2
	v_mul_f32_e32 v3, v47, v20
	v_bfe_u32 v4, v15, 16, 1
	v_add3_u32 v8, v14, v8, s68
	v_bfe_u32 v12, v10, 16, 1
	v_bfe_u32 v14, v11, 16, 1
	v_add3_u32 v4, v15, v4, s68
	v_add3_u32 v11, v11, v14, s68
	v_add3_u32 v10, v10, v12, s68
	v_lshrrev_b32_e32 v10, 16, v10
	v_lshrrev_b32_e32 v11, 16, v11
	v_mov_b32_e32 v12, v5
	v_mov_b32_e32 v28, v17
	global_store_dwordx4 v[66:67], v[42:45], off offset:2144
	s_nop 1
	v_and_or_b32 v45, v4, s69, v11
	s_nop 1
	v_and_or_b32 v44, v8, s69, v10
	v_mov_b32_e32 v20, v9
	v_pk_mul_f32 v[4:5], v[12:13], v[40:41]
	v_mov_b32_e32 v32, v25
	v_pk_mul_f32 v[8:9], v[28:29], v[36:37]
	v_cvt_pk_bf16_f32 v43, v3, v7
	v_cvt_pk_bf16_f32 v42, v2, v6
	v_pk_mul_f32 v[2:3], v[20:21], v[46:47]
	v_pk_mul_f32 v[6:7], v[32:33], v[48:49]
	v_bfe_u32 v12, v5, 16, 1
	v_bfe_u32 v13, v4, 16, 1
	v_add3_u32 v13, v4, v13, s68
	v_add3_u32 v12, v5, v12, s68
	v_bfe_u32 v10, v2, 16, 1
	v_bfe_u32 v11, v3, 16, 1
	v_add3_u32 v3, v3, v11, s68
	v_add3_u32 v2, v2, v10, s68
	v_lshrrev_b32_e32 v2, 16, v2
	v_lshrrev_b32_e32 v3, 16, v3
	v_cvt_pk_bf16_f32 v5, v7, v9
	v_cvt_pk_bf16_f32 v4, v6, v8
	v_and_or_b32 v3, v12, s69, v3
	v_and_or_b32 v2, v13, s69, v2
	global_store_dwordx4 v[58:59], v[42:45], off offset:96
	global_store_dwordx4 v[58:59], v[2:5], off offset:2144

.LBB0_586:
	v_lshlrev_b32_e32 v84, 9, v86
	s_waitcnt vmcnt(15)
	s_waitcnt vmcnt(13)
	s_waitcnt vmcnt(11)
	s_waitcnt vmcnt(9)
	s_waitcnt lgkmcnt(0)
	v_lshl_add_u64 v[40:41], s[50:51], 0, v[84:85]
	s_lshl_b32 s8, s8, 1
	v_mul_f32_e32 v80, v74, v42
	v_mul_f32_e32 v81, v75, v50
	v_mul_f32_e32 v108, v78, v58
	v_mul_f32_e32 v109, v79, v66
	s_waitcnt vmcnt(8)
	v_lshl_add_u64 v[40:41], v[40:41], 0, s[8:9]
	v_lshlrev_b32_e32 v84, 1, v82
	v_mul_f32_e32 v98, v94, v46
	v_mul_f32_e32 v99, v95, v54
	v_mul_f32_e32 v110, v92, v62
	v_mul_f32_e32 v111, v93, v70
	v_lshl_add_u64 v[40:41], v[40:41], 0, v[84:85]
	v_lshl_add_u64 v[86:87], v[40:41], 0, s[12:13]
	v_add_co_u32_e32 v40, vcc, s89, v40
	v_cvt_pk_bf16_f32 v111, v109, v111
	v_cvt_pk_bf16_f32 v110, v108, v110
	v_cvt_pk_bf16_f32 v109, v81, v99
	v_cvt_pk_bf16_f32 v108, v80, v98
	v_addc_co_u32_e32 v41, vcc, 0, v41, vcc
	v_mov_b32_e32 v50, v43
	v_mov_b32_e32 v54, v47
	v_mov_b32_e32 v70, v63
	global_store_dwordx4 v[40:41], v[108:111], off
	v_pk_mul_f32 v[40:41], v[50:51], v[74:75]
	v_pk_mul_f32 v[42:43], v[54:55], v[94:95]
	v_mov_b32_e32 v66, v59
	v_pk_mul_f32 v[50:51], v[70:71], v[92:93]
	v_pk_mul_f32 v[46:47], v[66:67], v[78:79]
	v_bfe_u32 v54, v51, 16, 1
	v_bfe_u32 v55, v50, 16, 1
	v_bfe_u32 v58, v43, 16, 1
	v_bfe_u32 v59, v42, 16, 1
	v_add3_u32 v59, v42, v59, s68
	v_add3_u32 v58, v43, v58, s68
	v_add3_u32 v42, v50, v55, s68
	v_add3_u32 v43, v51, v54, s68
	v_bfe_u32 v50, v40, 16, 1
	v_bfe_u32 v51, v41, 16, 1
	v_bfe_u32 v54, v46, 16, 1
	v_bfe_u32 v55, v47, 16, 1
	v_add3_u32 v47, v47, v55, s68
	v_add3_u32 v46, v46, v54, s68
	v_add3_u32 v41, v41, v51, s68
	v_add3_u32 v40, v40, v50, s68
	v_lshrrev_b32_e32 v40, 16, v40
	v_lshrrev_b32_e32 v41, 16, v41
	v_lshrrev_b32_e32 v46, 16, v46
	v_lshrrev_b32_e32 v47, 16, v47
	v_and_or_b32 v43, v43, s69, v47
	v_and_or_b32 v42, v42, s69, v46
	v_and_or_b32 v41, v58, s69, v41
	v_and_or_b32 v40, v59, s69, v40
	global_store_dwordx4 v[86:87], v[40:43], off offset:512
	s_nop 1
	v_mul_f32_e32 v42, v94, v48
	s_nop 1
	v_mul_f32_e32 v43, v95, v56
	v_mul_f32_e32 v50, v92, v64
	v_mul_f32_e32 v51, v93, v72
	v_mul_f32_e32 v40, v74, v44
	v_mul_f32_e32 v41, v75, v52
	v_mul_f32_e32 v46, v78, v60
	v_mul_f32_e32 v47, v79, v68
	v_bfe_u32 v44, v51, 16, 1
	v_bfe_u32 v48, v50, 16, 1
	v_bfe_u32 v52, v43, 16, 1
	v_bfe_u32 v54, v42, 16, 1
	v_add3_u32 v54, v42, v54, s68
	v_add3_u32 v52, v43, v52, s68
	v_add3_u32 v42, v50, v48, s68
	v_add3_u32 v43, v51, v44, s68
	v_bfe_u32 v44, v40, 16, 1
	v_bfe_u32 v48, v41, 16, 1
	v_bfe_u32 v50, v46, 16, 1
	v_bfe_u32 v51, v47, 16, 1
	v_add3_u32 v47, v47, v51, s68
	v_add3_u32 v46, v46, v50, s68
	v_add3_u32 v41, v41, v48, s68
	v_add3_u32 v40, v40, v44, s68
	v_lshrrev_b32_e32 v40, 16, v40
	v_lshrrev_b32_e32 v41, 16, v41
	v_lshrrev_b32_e32 v44, 16, v46
	v_lshrrev_b32_e32 v46, 16, v47
	v_and_or_b32 v43, v43, s69, v46
	v_and_or_b32 v42, v42, s69, v44
	v_and_or_b32 v41, v52, s69, v41
	v_and_or_b32 v40, v54, s69, v40
	v_mov_b32_e32 v56, v49
	v_mov_b32_e32 v72, v65
	global_store_dwordx4 v[86:87], v[40:43], off offset:1024
	v_mov_b32_e32 v52, v45
	v_mov_b32_e32 v68, v61
	v_pk_mul_f32 v[42:43], v[56:57], v[94:95]
	v_pk_mul_f32 v[46:47], v[72:73], v[92:93]
	v_pk_mul_f32 v[40:41], v[52:53], v[74:75]
	v_pk_mul_f32 v[44:45], v[68:69], v[78:79]
	v_bfe_u32 v48, v47, 16, 1
	v_bfe_u32 v49, v46, 16, 1
	v_bfe_u32 v50, v43, 16, 1
	v_bfe_u32 v51, v42, 16, 1
	v_add3_u32 v51, v42, v51, s68
	v_add3_u32 v50, v43, v50, s68
	v_add3_u32 v42, v46, v49, s68
	v_add3_u32 v43, v47, v48, s68
	v_bfe_u32 v46, v40, 16, 1
	v_bfe_u32 v47, v41, 16, 1
	v_bfe_u32 v48, v44, 16, 1
	v_bfe_u32 v49, v45, 16, 1
	v_add3_u32 v45, v45, v49, s68
	v_add3_u32 v44, v44, v48, s68
	v_add3_u32 v41, v41, v47, s68
	v_add3_u32 v40, v40, v46, s68
	v_lshrrev_b32_e32 v40, 16, v40
	v_lshrrev_b32_e32 v41, 16, v41
	v_lshrrev_b32_e32 v44, 16, v44
	v_lshrrev_b32_e32 v45, 16, v45
	v_and_or_b32 v43, v43, s69, v45
	v_and_or_b32 v42, v42, s69, v44
	v_and_or_b32 v41, v50, s69, v41
	v_and_or_b32 v40, v51, s69, v40
	global_store_dwordx4 v[86:87], v[40:43], off offset:1536
	s_waitcnt vmcnt(7)
	s_waitcnt vmcnt(5)
	v_mul_f32_e32 v40, v2, v10
	v_mul_f32_e32 v41, v3, v18
	v_mul_f32_e32 v44, v38, v26
	v_mul_f32_e32 v45, v39, v34
	s_waitcnt vmcnt(4)
	v_mul_f32_e32 v42, v76, v6
	v_mul_f32_e32 v43, v77, v14
	v_mul_f32_e32 v46, v4, v22
	v_mul_f32_e32 v47, v5, v30
	v_bfe_u32 v22, v40, 16, 1
	v_bfe_u32 v18, v42, 16, 1
	v_add3_u32 v22, v40, v22, s68
	v_add3_u32 v18, v42, v18, s68
	v_lshrrev_b32_e32 v22, 16, v22
	v_cvt_pk_bf16_f32 v42, v44, v46
	v_cvt_pk_bf16_f32 v41, v41, v43
	v_and_or_b32 v40, v18, s69, v22
	v_mov_b32_e32 v18, v11
	v_mov_b32_e32 v14, v7
	v_mov_b32_e32 v30, v23
	v_cvt_pk_bf16_f32 v43, v45, v47
	v_pk_mul_f32 v[10:11], v[18:19], v[2:3]
	v_pk_mul_f32 v[6:7], v[14:15], v[76:77]
	v_mov_b32_e32 v34, v27
	v_pk_mul_f32 v[18:19], v[30:31], v[4:5]
	v_pk_mul_f32 v[14:15], v[34:35], v[38:39]
	global_store_dwordx4 v[86:87], v[40:43], off offset:32
	v_lshl_or_b32 v84, v97, 13, v104
	s_mov_b32 s8, 0x48000
	v_cvt_pk_bf16_f32 v43, v15, v19
	v_cvt_pk_bf16_f32 v42, v14, v18
	v_cvt_pk_bf16_f32 v41, v11, v7
	v_cvt_pk_bf16_f32 v40, v10, v6
	v_mul_f32_e32 v10, v76, v8
	v_mul_f32_e32 v11, v77, v16
	v_mul_f32_e32 v18, v4, v24
	v_mul_f32_e32 v19, v5, v32
	v_mul_f32_e32 v6, v2, v12
	v_mul_f32_e32 v7, v3, v20
	v_bfe_u32 v12, v18, 16, 1
	v_bfe_u32 v16, v11, 16, 1
	v_mul_f32_e32 v14, v38, v28
	v_mul_f32_e32 v15, v39, v36
	v_bfe_u32 v8, v19, 16, 1
	v_bfe_u32 v20, v10, 16, 1
	v_add3_u32 v11, v11, v16, s68
	v_add3_u32 v12, v18, v12, s68
	v_bfe_u32 v16, v6, 16, 1
	v_bfe_u32 v18, v7, 16, 1
	v_add3_u32 v10, v10, v20, s68
	v_add3_u32 v8, v19, v8, s68
	v_bfe_u32 v19, v14, 16, 1
	v_bfe_u32 v20, v15, 16, 1
	v_add3_u32 v7, v7, v18, s68
	v_add3_u32 v6, v6, v16, s68
	v_add3_u32 v15, v15, v20, s68
	v_add3_u32 v14, v14, v19, s68
	v_lshrrev_b32_e32 v6, 16, v6
	v_lshrrev_b32_e32 v7, 16, v7
	v_mov_b32_e32 v16, v9
	v_mov_b32_e32 v32, v25
	global_store_dwordx4 v[86:87], v[40:43], off offset:544
	v_lshrrev_b32_e32 v14, 16, v14
	v_lshrrev_b32_e32 v15, 16, v15
	v_and_or_b32 v41, v11, s69, v7
	v_and_or_b32 v40, v10, s69, v6
	v_mov_b32_e32 v20, v13
	v_pk_mul_f32 v[6:7], v[16:17], v[76:77]
	v_mov_b32_e32 v36, v29
	v_pk_mul_f32 v[4:5], v[32:33], v[4:5]
	v_and_or_b32 v43, v8, s69, v15
	v_and_or_b32 v42, v12, s69, v14
	v_pk_mul_f32 v[2:3], v[20:21], v[2:3]
	v_pk_mul_f32 v[8:9], v[36:37], v[38:39]
	v_cvt_pk_bf16_f32 v5, v9, v5
	v_cvt_pk_bf16_f32 v4, v8, v4
	v_cvt_pk_bf16_f32 v3, v3, v7
	v_cvt_pk_bf16_f32 v2, v2, v6
	global_store_dwordx4 v[86:87], v[2:5], off offset:1568
	global_store_dwordx4 v[86:87], v[40:43], off offset:1056
	v_mov_b32_e32 v74, 1.0
	v_add_co_u32_e32 v4, vcc, s90, v88
	v_lshl_add_u64 v[2:3], v[90:91], 0, v[84:85]
	s_nop 0
	v_addc_co_u32_e32 v5, vcc, 0, v89, vcc
	global_load_dwordx4 v[46:49], v[2:3], off nt
	global_load_dwordx4 v[38:41], v[4:5], off nt
	v_add_co_u32_e32 v2, vcc, s91, v88
	v_mov_b32_e32 v94, 1.0
	s_nop 0
	v_addc_co_u32_e32 v3, vcc, 0, v89, vcc
	v_add_co_u32_e32 v4, vcc, 0x46000, v88
	v_mov_b32_e32 v75, 1.0
	s_nop 0
	v_addc_co_u32_e32 v5, vcc, 0, v89, vcc
	global_load_dwordx4 v[54:57], v[2:3], off nt
	global_load_dwordx4 v[50:53], v[4:5], off nt
	v_add_co_u32_e32 v2, vcc, s8, v88
	v_mov_b32_e32 v95, 1.0
	s_nop 0
	v_addc_co_u32_e32 v3, vcc, 0, v89, vcc
	v_add_co_u32_e32 v4, vcc, 0x4a000, v88
	v_mov_b32_e32 v78, 1.0
	s_nop 0
	v_addc_co_u32_e32 v5, vcc, 0, v89, vcc
	global_load_dwordx4 v[62:65], v[2:3], off nt
	global_load_dwordx4 v[58:61], v[4:5], off nt
	v_add_co_u32_e32 v2, vcc, 0x4c000, v88
	v_mov_b32_e32 v92, 1.0
	s_nop 0
	v_addc_co_u32_e32 v3, vcc, 0, v89, vcc
	v_add_co_u32_e32 v4, vcc, 0x4e000, v88
	v_mov_b32_e32 v79, 1.0
	s_nop 0
	v_addc_co_u32_e32 v5, vcc, 0, v89, vcc
	global_load_dwordx4 v[70:73], v[2:3], off nt
	global_load_dwordx4 v[66:69], v[4:5], off nt
	v_mov_b32_e32 v2, 1.0
	s_and_b64 vcc, exec, s[6:7]
	v_mov_b32_e32 v93, 1.0
	s_cbranch_vccnz .LBB0_588
	global_load_dwordx4 v[74:77], v96, s[10:11] offset:128
	global_load_dwordx4 v[78:81], v96, s[10:11] offset:144
	s_waitcnt vmcnt(1)
	v_mov_b32_e32 v94, v75
	v_mov_b32_e32 v75, v76
	v_mov_b32_e32 v95, v77
	s_waitcnt vmcnt(0)
	v_mov_b32_e32 v92, v79
	v_mov_b32_e32 v79, v80
	v_mov_b32_e32 v93, v81

.LBB0_590:
	s_waitcnt vmcnt(15)
	s_waitcnt vmcnt(13)
	v_mul_f32_e32 v44, v74, v46
	v_mul_f32_e32 v45, v75, v54
	s_waitcnt vmcnt(12)
	s_waitcnt vmcnt(11)
	s_waitcnt vmcnt(9)
	v_mul_f32_e32 v80, v94, v38
	v_mul_f32_e32 v81, v95, v50
	v_mul_f32_e32 v88, v78, v62
	v_mul_f32_e32 v89, v79, v70
	s_waitcnt vmcnt(8)
	v_bfe_u32 v62, v45, 16, 1
	v_mul_f32_e32 v90, v92, v58
	v_mul_f32_e32 v91, v93, v66
	v_bfe_u32 v50, v81, 16, 1
	v_bfe_u32 v58, v44, 16, 1
	v_bfe_u32 v66, v88, 16, 1
	v_bfe_u32 v70, v89, 16, 1
	v_add3_u32 v45, v45, v62, s68
	v_bfe_u32 v38, v91, 16, 1
	v_bfe_u32 v54, v80, 16, 1
	v_add3_u32 v50, v81, v50, s68
	v_add3_u32 v70, v89, v70, s68
	v_add3_u32 v66, v88, v66, s68
	v_add3_u32 v44, v44, v58, s68
	v_lshrrev_b32_e32 v45, 16, v45
	v_bfe_u32 v46, v90, 16, 1
	v_add3_u32 v54, v80, v54, s68
	v_add3_u32 v38, v91, v38, s68
	v_lshrrev_b32_e32 v44, 16, v44
	v_lshrrev_b32_e32 v58, 16, v66
	v_lshrrev_b32_e32 v62, 16, v70
	v_and_or_b32 v89, v50, s69, v45
	v_mov_b32_e32 v50, v39
	v_mov_b32_e32 v66, v59
	v_add3_u32 v46, v90, v46, s68
	v_and_or_b32 v91, v38, s69, v62
	v_and_or_b32 v88, v54, s69, v44
	v_mov_b32_e32 v54, v47
	v_pk_mul_f32 v[38:39], v[50:51], v[94:95]
	v_mov_b32_e32 v70, v63
	v_pk_mul_f32 v[50:51], v[66:67], v[92:93]
	v_and_or_b32 v90, v46, s69, v58
	v_pk_mul_f32 v[44:45], v[54:55], v[74:75]
	v_pk_mul_f32 v[46:47], v[70:71], v[78:79]
	v_cvt_pk_bf16_f32 v47, v47, v51
	v_cvt_pk_bf16_f32 v46, v46, v50
	v_cvt_pk_bf16_f32 v45, v45, v39
	v_cvt_pk_bf16_f32 v44, v44, v38
	global_store_dwordx4 v[86:87], v[44:47], off offset:576
	s_nop 1
	v_mul_f32_e32 v44, v94, v40
	s_nop 1
	v_mul_f32_e32 v45, v95, v52
	v_mul_f32_e32 v50, v92, v60
	v_mul_f32_e32 v51, v93, v68
	v_mul_f32_e32 v38, v74, v48
	v_mul_f32_e32 v39, v75, v56
	v_mul_f32_e32 v46, v78, v64
	v_mul_f32_e32 v47, v79, v72
	v_bfe_u32 v40, v51, 16, 1
	v_bfe_u32 v48, v50, 16, 1
	v_add3_u32 v48, v50, v48, s68
	v_add3_u32 v40, v51, v40, s68
	v_bfe_u32 v52, v46, 16, 1
	v_bfe_u32 v54, v47, 16, 1
	v_add3_u32 v47, v47, v54, s68
	v_add3_u32 v46, v46, v52, s68
	v_lshrrev_b32_e32 v46, 16, v46
	v_lshrrev_b32_e32 v47, 16, v47
	v_and_or_b32 v47, v40, s69, v47
	v_and_or_b32 v46, v48, s69, v46
	v_cvt_pk_bf16_f32 v45, v39, v45
	v_cvt_pk_bf16_f32 v44, v38, v44
	v_mov_b32_e32 v52, v41
	v_mov_b32_e32 v68, v61
	global_store_dwordx4 v[86:87], v[44:47], off offset:1088
	v_mov_b32_e32 v56, v49
	v_pk_mul_f32 v[40:41], v[52:53], v[94:95]
	v_mov_b32_e32 v72, v65
	v_pk_mul_f32 v[46:47], v[68:69], v[92:93]
	v_pk_mul_f32 v[38:39], v[56:57], v[74:75]
	v_pk_mul_f32 v[44:45], v[72:73], v[78:79]
	v_bfe_u32 v48, v47, 16, 1
	v_bfe_u32 v49, v46, 16, 1
	v_bfe_u32 v50, v41, 16, 1
	v_bfe_u32 v51, v40, 16, 1
	v_add3_u32 v51, v40, v51, s68
	v_add3_u32 v50, v41, v50, s68
	v_add3_u32 v40, v46, v49, s68
	v_add3_u32 v41, v47, v48, s68
	v_bfe_u32 v46, v38, 16, 1
	v_bfe_u32 v47, v39, 16, 1
	v_bfe_u32 v48, v44, 16, 1
	v_bfe_u32 v49, v45, 16, 1
	v_add3_u32 v45, v45, v49, s68
	v_add3_u32 v44, v44, v48, s68
	v_add3_u32 v39, v39, v47, s68
	v_add3_u32 v38, v38, v46, s68
	v_lshrrev_b32_e32 v38, 16, v38
	v_lshrrev_b32_e32 v39, 16, v39
	v_lshrrev_b32_e32 v44, 16, v44
	v_lshrrev_b32_e32 v45, 16, v45
	v_and_or_b32 v41, v41, s69, v45
	v_and_or_b32 v40, v40, s69, v44
	v_and_or_b32 v39, v50, s69, v39
	v_and_or_b32 v38, v51, s69, v38
	global_store_dwordx4 v[86:87], v[38:41], off offset:1600
	s_waitcnt vmcnt(6)
	s_waitcnt vmcnt(4)
	v_mul_f32_e32 v38, v2, v10
	v_mul_f32_e32 v39, v3, v18
	v_mul_f32_e32 v44, v42, v26
	v_mul_f32_e32 v45, v43, v34
	s_waitcnt vmcnt(3)
	v_mul_f32_e32 v40, v76, v6
	v_mul_f32_e32 v41, v77, v14
	v_mul_f32_e32 v46, v4, v22
	v_mul_f32_e32 v47, v5, v30
	v_bfe_u32 v22, v38, 16, 1
	v_bfe_u32 v18, v40, 16, 1
	v_add3_u32 v22, v38, v22, s68
	v_add3_u32 v18, v40, v18, s68
	v_lshrrev_b32_e32 v22, 16, v22
	v_cvt_pk_bf16_f32 v40, v44, v46
	v_cvt_pk_bf16_f32 v39, v39, v41
	v_and_or_b32 v38, v18, s69, v22
	v_mov_b32_e32 v18, v11
	v_mov_b32_e32 v14, v7
	v_mov_b32_e32 v30, v23
	v_cvt_pk_bf16_f32 v41, v45, v47
	v_pk_mul_f32 v[10:11], v[18:19], v[2:3]
	v_pk_mul_f32 v[6:7], v[14:15], v[76:77]
	v_mov_b32_e32 v34, v27
	v_pk_mul_f32 v[18:19], v[30:31], v[4:5]
	v_pk_mul_f32 v[14:15], v[34:35], v[42:43]
	global_store_dwordx4 v[86:87], v[38:41], off offset:96
	s_mov_b32 s8, 4
	global_store_dwordx4 v[86:87], v[88:91], off offset:64
	v_cvt_pk_bf16_f32 v41, v15, v19
	v_cvt_pk_bf16_f32 v40, v14, v18
	v_cvt_pk_bf16_f32 v39, v11, v7
	v_cvt_pk_bf16_f32 v38, v10, v6
	v_mul_f32_e32 v10, v76, v8
	v_mul_f32_e32 v11, v77, v16
	v_mul_f32_e32 v18, v4, v24
	v_mul_f32_e32 v19, v5, v32
	v_mul_f32_e32 v6, v2, v12
	v_mul_f32_e32 v7, v3, v20
	v_bfe_u32 v12, v18, 16, 1
	v_bfe_u32 v16, v11, 16, 1
	v_mul_f32_e32 v14, v42, v28
	v_mul_f32_e32 v15, v43, v36
	v_bfe_u32 v8, v19, 16, 1
	v_bfe_u32 v20, v10, 16, 1
	v_add3_u32 v11, v11, v16, s68
	v_add3_u32 v12, v18, v12, s68
	v_bfe_u32 v16, v6, 16, 1
	v_bfe_u32 v18, v7, 16, 1
	v_add3_u32 v10, v10, v20, s68
	v_add3_u32 v8, v19, v8, s68
	v_bfe_u32 v19, v14, 16, 1
	v_bfe_u32 v20, v15, 16, 1
	v_add3_u32 v7, v7, v18, s68
	v_add3_u32 v6, v6, v16, s68
	v_add3_u32 v15, v15, v20, s68
	v_add3_u32 v14, v14, v19, s68
	v_lshrrev_b32_e32 v6, 16, v6
	v_lshrrev_b32_e32 v7, 16, v7
	v_mov_b32_e32 v16, v9
	v_mov_b32_e32 v32, v25
	global_store_dwordx4 v[86:87], v[38:41], off offset:608
	v_lshrrev_b32_e32 v14, 16, v14
	v_lshrrev_b32_e32 v15, 16, v15
	v_and_or_b32 v39, v11, s69, v7
	v_and_or_b32 v38, v10, s69, v6
	v_mov_b32_e32 v20, v13
	v_pk_mul_f32 v[6:7], v[16:17], v[76:77]
	v_mov_b32_e32 v36, v29
	v_pk_mul_f32 v[4:5], v[32:33], v[4:5]
	v_and_or_b32 v41, v8, s69, v15
	v_and_or_b32 v40, v12, s69, v14
	v_pk_mul_f32 v[2:3], v[20:21], v[2:3]
	v_pk_mul_f32 v[8:9], v[36:37], v[42:43]
	v_cvt_pk_bf16_f32 v5, v9, v5
	v_cvt_pk_bf16_f32 v4, v8, v4
	v_cvt_pk_bf16_f32 v3, v3, v7
	v_cvt_pk_bf16_f32 v2, v2, v6
	global_store_dwordx4 v[86:87], v[38:41], off offset:1120
	global_store_dwordx4 v[86:87], v[2:5], off offset:1632

.LBB0_598:
	s_waitcnt vmcnt(11)
	s_waitcnt vmcnt(9)
	v_mul_f32_e32 v96, v78, v62
	v_mul_f32_e32 v97, v79, v70
	s_waitcnt vmcnt(8)
	v_mul_f32_e32 v40, v74, v54
	v_mul_f32_e32 v41, v75, v58
	v_mul_f32_e32 v98, v92, v50
	v_mul_f32_e32 v99, v93, v66
	v_mul_f32_e32 v88, v94, v42
	v_mul_f32_e32 v89, v95, v46
	v_bfe_u32 v58, v40, 16, 1
	v_add3_u32 v40, v40, v58, s68
	v_bfe_u32 v54, v88, 16, 1
	v_cvt_pk_bf16_f32 v98, v96, v98
	v_mov_b32_e32 v46, v43
	v_mov_b32_e32 v66, v51
	v_add3_u32 v54, v88, v54, s68
	v_lshrrev_b32_e32 v40, 16, v40
	v_cvt_pk_bf16_f32 v99, v97, v99
	v_cvt_pk_bf16_f32 v97, v41, v89
	v_mov_b32_e32 v58, v55
	v_pk_mul_f32 v[42:43], v[46:47], v[94:95]
	v_mov_b32_e32 v70, v63
	v_pk_mul_f32 v[50:51], v[66:67], v[92:93]
	v_and_or_b32 v96, v54, s69, v40
	v_pk_mul_f32 v[40:41], v[58:59], v[74:75]
	v_pk_mul_f32 v[46:47], v[70:71], v[78:79]
	v_bfe_u32 v54, v51, 16, 1
	v_bfe_u32 v55, v50, 16, 1
	v_bfe_u32 v58, v43, 16, 1
	v_bfe_u32 v59, v42, 16, 1
	v_add3_u32 v59, v42, v59, s68
	v_add3_u32 v58, v43, v58, s68
	v_add3_u32 v42, v50, v55, s68
	v_add3_u32 v43, v51, v54, s68
	v_bfe_u32 v50, v40, 16, 1
	v_bfe_u32 v51, v41, 16, 1
	v_bfe_u32 v54, v46, 16, 1
	v_bfe_u32 v55, v47, 16, 1
	v_add3_u32 v47, v47, v55, s68
	v_add3_u32 v46, v46, v54, s68
	v_add3_u32 v41, v41, v51, s68
	v_add3_u32 v40, v40, v50, s68
	v_lshrrev_b32_e32 v40, 16, v40
	v_lshrrev_b32_e32 v41, 16, v41
	v_lshrrev_b32_e32 v46, 16, v46
	v_lshrrev_b32_e32 v47, 16, v47
	v_and_or_b32 v43, v43, s69, v47
	v_and_or_b32 v42, v42, s69, v46
	v_and_or_b32 v41, v58, s69, v41
	v_and_or_b32 v40, v59, s69, v40
	global_store_dwordx4 v[86:87], v[40:43], off offset:2048
	s_nop 1
	v_mul_f32_e32 v42, v94, v44
	s_nop 1
	v_mul_f32_e32 v43, v95, v48
	v_mul_f32_e32 v50, v92, v52
	v_mul_f32_e32 v51, v93, v68
	v_mul_f32_e32 v40, v74, v56
	v_mul_f32_e32 v41, v75, v60
	v_mul_f32_e32 v46, v78, v64
	v_mul_f32_e32 v47, v79, v72
	v_bfe_u32 v44, v51, 16, 1
	v_bfe_u32 v48, v50, 16, 1
	v_bfe_u32 v52, v43, 16, 1
	v_bfe_u32 v54, v42, 16, 1
	v_add3_u32 v54, v42, v54, s68
	v_add3_u32 v52, v43, v52, s68
	v_add3_u32 v42, v50, v48, s68
	v_add3_u32 v43, v51, v44, s68
	v_bfe_u32 v44, v40, 16, 1
	v_bfe_u32 v48, v41, 16, 1
	v_bfe_u32 v50, v46, 16, 1
	v_bfe_u32 v51, v47, 16, 1
	v_add3_u32 v47, v47, v51, s68
	v_add3_u32 v46, v46, v50, s68
	v_add3_u32 v41, v41, v48, s68
	v_add3_u32 v40, v40, v44, s68
	v_lshrrev_b32_e32 v40, 16, v40
	v_lshrrev_b32_e32 v41, 16, v41
	v_lshrrev_b32_e32 v44, 16, v46
	v_lshrrev_b32_e32 v46, 16, v47
	v_add_co_u32_e32 v88, vcc, s61, v86
	v_and_or_b32 v43, v43, s69, v46
	v_and_or_b32 v42, v42, s69, v44
	v_and_or_b32 v41, v52, s69, v41
	v_and_or_b32 v40, v54, s69, v40
	v_addc_co_u32_e32 v89, vcc, 0, v87, vcc
	v_mov_b32_e32 v48, v45
	v_mov_b32_e32 v68, v53
	global_store_dwordx4 v[88:89], v[40:43], off
	v_mov_b32_e32 v60, v57
	v_mov_b32_e32 v72, v65
	v_pk_mul_f32 v[42:43], v[48:49], v[94:95]
	v_pk_mul_f32 v[46:47], v[68:69], v[92:93]
	v_pk_mul_f32 v[40:41], v[60:61], v[74:75]
	v_pk_mul_f32 v[44:45], v[72:73], v[78:79]
	v_bfe_u32 v48, v47, 16, 1
	v_bfe_u32 v49, v46, 16, 1
	v_bfe_u32 v50, v43, 16, 1
	v_bfe_u32 v51, v42, 16, 1
	v_add3_u32 v51, v42, v51, s68
	v_add3_u32 v50, v43, v50, s68
	v_add3_u32 v42, v46, v49, s68
	v_add3_u32 v43, v47, v48, s68
	v_bfe_u32 v46, v40, 16, 1
	v_bfe_u32 v47, v41, 16, 1
	v_bfe_u32 v48, v44, 16, 1
	v_bfe_u32 v49, v45, 16, 1
	v_add3_u32 v45, v45, v49, s68
	v_add3_u32 v44, v44, v48, s68
	v_add3_u32 v41, v41, v47, s68
	v_add3_u32 v40, v40, v46, s68
	v_lshrrev_b32_e32 v40, 16, v40
	v_lshrrev_b32_e32 v41, 16, v41
	v_lshrrev_b32_e32 v44, 16, v44
	v_lshrrev_b32_e32 v45, 16, v45
	v_and_or_b32 v43, v43, s69, v45
	v_and_or_b32 v42, v42, s69, v44
	v_and_or_b32 v41, v50, s69, v41
	v_and_or_b32 v40, v51, s69, v40
	s_waitcnt vmcnt(5)
	s_waitcnt vmcnt(3)
	global_store_dwordx4 v[88:89], v[40:43], off offset:2048
	v_mul_f32_e32 v44, v38, v26
	v_mul_f32_e32 v45, v39, v34
	s_waitcnt vmcnt(3)
	v_mul_f32_e32 v40, v2, v14
	v_mul_f32_e32 v41, v3, v18
	v_mul_f32_e32 v46, v76, v22
	v_mul_f32_e32 v47, v77, v30
	v_mul_f32_e32 v42, v80, v6
	v_mul_f32_e32 v43, v81, v10
	v_bfe_u32 v22, v40, 16, 1
	v_bfe_u32 v18, v42, 16, 1
	v_bfe_u32 v26, v41, 16, 1
	v_add3_u32 v22, v40, v22, s68
	v_bfe_u32 v14, v43, 16, 1
	v_add3_u32 v18, v42, v18, s68
	v_add3_u32 v26, v41, v26, s68
	v_lshrrev_b32_e32 v22, 16, v22
	v_cvt_pk_bf16_f32 v42, v44, v46
	v_mov_b32_e32 v10, v7
	v_add3_u32 v14, v43, v14, s68
	v_lshrrev_b32_e32 v26, 16, v26
	v_cvt_pk_bf16_f32 v43, v45, v47
	v_and_or_b32 v40, v18, s69, v22
	v_mov_b32_e32 v18, v15
	v_pk_mul_f32 v[6:7], v[10:11], v[80:81]
	v_mov_b32_e32 v34, v27
	v_mov_b32_e32 v30, v23
	v_and_or_b32 v41, v14, s69, v26
	v_pk_mul_f32 v[14:15], v[18:19], v[2:3]
	v_pk_mul_f32 v[10:11], v[34:35], v[38:39]
	v_pk_mul_f32 v[18:19], v[30:31], v[76:77]
	global_store_dwordx4 v[86:87], v[40:43], off offset:32
	s_nop 1
	v_cvt_pk_bf16_f32 v43, v11, v19
	s_nop 1
	v_cvt_pk_bf16_f32 v42, v10, v18
	v_cvt_pk_bf16_f32 v41, v15, v7
	v_cvt_pk_bf16_f32 v40, v14, v6
	v_mul_f32_e32 v10, v80, v8
	v_mul_f32_e32 v11, v81, v12
	v_mul_f32_e32 v18, v76, v24
	v_mul_f32_e32 v19, v77, v32
	v_mul_f32_e32 v6, v2, v16
	v_mul_f32_e32 v7, v3, v20
	v_mul_f32_e32 v14, v38, v28
	v_mul_f32_e32 v15, v39, v36
	v_bfe_u32 v8, v19, 16, 1
	v_bfe_u32 v12, v18, 16, 1
	v_add3_u32 v12, v18, v12, s68
	v_add3_u32 v8, v19, v8, s68
	v_bfe_u32 v16, v6, 16, 1
	v_bfe_u32 v19, v14, 16, 1
	v_bfe_u32 v20, v10, 16, 1
	v_add3_u32 v14, v14, v19, s68
	v_add3_u32 v6, v6, v16, s68
	v_add3_u32 v10, v10, v20, s68
	v_bfe_u32 v20, v15, 16, 1
	v_lshrrev_b32_e32 v6, 16, v6
	v_lshrrev_b32_e32 v14, 16, v14
	v_mov_b32_e32 v32, v25
	global_store_dwordx4 v[86:87], v[40:43], off offset:2080
	v_add3_u32 v15, v15, v20, s68
	v_mov_b32_e32 v20, v17
	v_and_or_b32 v42, v12, s69, v14
	v_cvt_pk_bf16_f32 v41, v7, v11
	v_and_or_b32 v40, v10, s69, v6
	v_mov_b32_e32 v12, v9
	v_pk_mul_f32 v[10:11], v[32:33], v[76:77]
	v_lshrrev_b32_e32 v15, 16, v15
	v_pk_mul_f32 v[2:3], v[20:21], v[2:3]
	v_pk_mul_f32 v[6:7], v[12:13], v[80:81]
	v_mov_b32_e32 v36, v29
	v_and_or_b32 v43, v8, s69, v15
	v_pk_mul_f32 v[8:9], v[36:37], v[38:39]
	v_lshl_add_u64 v[4:5], v[90:91], 0, s[16:17]
	v_cvt_pk_bf16_f32 v6, v2, v6
	v_add_co_u32_e32 v2, vcc, s75, v4
	v_cvt_pk_bf16_f32 v9, v9, v11
	v_cvt_pk_bf16_f32 v8, v8, v10
	v_cvt_pk_bf16_f32 v7, v3, v7
	v_addc_co_u32_e32 v3, vcc, 0, v5, vcc
	s_mov_b32 s8, 0xa000
	global_store_dwordx4 v[88:89], v[6:9], off offset:2080
	global_store_dwordx4 v[86:87], v[96:99], off
	global_store_dwordx4 v[88:89], v[40:43], off offset:32
	v_add_co_u32_e32 v6, vcc, s8, v90
	v_mov_b32_e32 v74, 1.0
	s_nop 0
	v_addc_co_u32_e32 v7, vcc, 0, v91, vcc
	global_load_dwordx4 v[50:53], v[2:3], off nt
	global_load_dwordx4 v[42:45], v[6:7], off offset:1280 nt
	global_load_dwordx4 v[54:57], v[6:7], off offset:2560 nt
	global_load_dwordx4 v[46:49], v[6:7], off offset:3840 nt
	v_add_co_u32_e32 v2, vcc, 0xb000, v90
	v_mov_b32_e32 v94, 1.0
	s_nop 0
	v_addc_co_u32_e32 v3, vcc, 0, v91, vcc
	v_add_co_u32_e32 v6, vcc, 0xc000, v90
	global_load_dwordx4 v[62:65], v[2:3], off offset:1024 nt
	global_load_dwordx4 v[58:61], v[2:3], off offset:2304 nt
	v_addc_co_u32_e32 v7, vcc, 0, v91, vcc
	global_load_dwordx4 v[70:73], v[2:3], off offset:3584 nt
	global_load_dwordx4 v[66:69], v[6:7], off offset:768 nt
	v_mov_b32_e32 v2, 1.0
	s_and_b64 vcc, exec, s[6:7]
	v_mov_b32_e32 v75, 1.0
	v_mov_b32_e32 v95, 1.0
	v_mov_b32_e32 v78, 1.0
	v_mov_b32_e32 v92, 1.0
	v_mov_b32_e32 v79, 1.0
	v_mov_b32_e32 v93, 1.0
	s_cbranch_vccnz .LBB0_600
	global_load_dwordx4 v[74:77], v84, s[48:49] offset:128
	global_load_dwordx4 v[78:81], v84, s[48:49] offset:144
	s_waitcnt vmcnt(1)
	v_mov_b32_e32 v94, v75
	v_mov_b32_e32 v75, v76
	v_mov_b32_e32 v95, v77
	s_waitcnt vmcnt(0)
	v_mov_b32_e32 v92, v79
	v_mov_b32_e32 v79, v80
	v_mov_b32_e32 v93, v81

.LBB0_602:
	s_waitcnt vmcnt(14)
	s_waitcnt vmcnt(12)
	s_waitcnt vmcnt(11)
	s_waitcnt vmcnt(9)
	v_mul_f32_e32 v40, v94, v42
	v_mul_f32_e32 v41, v95, v46
	v_mul_f32_e32 v90, v78, v62
	v_mul_f32_e32 v91, v79, v70
	s_waitcnt vmcnt(8)
	v_mul_f32_e32 v4, v74, v50
	v_mul_f32_e32 v5, v75, v54
	v_mul_f32_e32 v96, v92, v58
	v_mul_f32_e32 v97, v93, v66
	v_cvt_pk_bf16_f32 v98, v90, v96
	v_mov_b32_e32 v46, v43
	v_mov_b32_e32 v66, v59
	v_cvt_pk_bf16_f32 v99, v91, v97
	v_cvt_pk_bf16_f32 v97, v5, v41
	v_cvt_pk_bf16_f32 v96, v4, v40
	v_mov_b32_e32 v54, v51
	v_pk_mul_f32 v[40:41], v[46:47], v[94:95]
	v_mov_b32_e32 v70, v63
	v_pk_mul_f32 v[46:47], v[66:67], v[92:93]
	v_pk_mul_f32 v[4:5], v[54:55], v[74:75]
	v_pk_mul_f32 v[42:43], v[70:71], v[78:79]
	v_cvt_pk_bf16_f32 v43, v43, v47
	v_cvt_pk_bf16_f32 v42, v42, v46
	v_cvt_pk_bf16_f32 v41, v5, v41
	v_cvt_pk_bf16_f32 v40, v4, v40
	global_store_dwordx4 v[86:87], v[40:43], off offset:2112
	s_nop 1
	v_mul_f32_e32 v40, v94, v44
	s_nop 1
	v_mul_f32_e32 v41, v95, v48
	v_mul_f32_e32 v46, v92, v60
	v_mul_f32_e32 v47, v93, v68
	v_mul_f32_e32 v4, v74, v52
	v_mul_f32_e32 v5, v75, v56
	v_mul_f32_e32 v42, v78, v64
	v_mul_f32_e32 v43, v79, v72
	v_bfe_u32 v44, v47, 16, 1
	v_add3_u32 v44, v47, v44, s68
	v_bfe_u32 v51, v43, 16, 1
	v_add3_u32 v43, v43, v51, s68
	v_lshrrev_b32_e32 v43, 16, v43
	v_and_or_b32 v43, v44, s69, v43
	v_cvt_pk_bf16_f32 v42, v42, v46
	v_cvt_pk_bf16_f32 v41, v5, v41
	v_cvt_pk_bf16_f32 v40, v4, v40
	v_mov_b32_e32 v48, v45
	v_mov_b32_e32 v68, v61
	global_store_dwordx4 v[88:89], v[40:43], off offset:64
	v_mov_b32_e32 v56, v53
	v_mov_b32_e32 v72, v65
	v_pk_mul_f32 v[40:41], v[48:49], v[94:95]
	v_pk_mul_f32 v[44:45], v[68:69], v[92:93]
	v_pk_mul_f32 v[4:5], v[56:57], v[74:75]
	v_pk_mul_f32 v[42:43], v[72:73], v[78:79]
	v_cvt_pk_bf16_f32 v43, v43, v45
	v_cvt_pk_bf16_f32 v42, v42, v44
	v_cvt_pk_bf16_f32 v41, v5, v41
	v_cvt_pk_bf16_f32 v40, v4, v40
	global_store_dwordx4 v[88:89], v[40:43], off offset:2112
	s_waitcnt vmcnt(10)
	s_waitcnt vmcnt(8)
	s_waitcnt vmcnt(6)
	s_waitcnt vmcnt(4)
	v_mul_f32_e32 v42, v38, v18
	v_mul_f32_e32 v43, v39, v14
	s_waitcnt vmcnt(3)
	v_mul_f32_e32 v4, v2, v30
	v_mul_f32_e32 v5, v3, v34
	v_mul_f32_e32 v44, v76, v6
	v_mul_f32_e32 v45, v77, v10
	v_mul_f32_e32 v40, v80, v22
	v_mul_f32_e32 v41, v81, v26
	v_bfe_u32 v22, v4, 16, 1
	v_bfe_u32 v26, v5, 16, 1
	v_bfe_u32 v14, v41, 16, 1
	v_add3_u32 v5, v5, v26, s68
	v_add3_u32 v4, v4, v22, s68
	v_bfe_u32 v18, v40, 16, 1
	v_add3_u32 v14, v41, v14, s68
	v_lshrrev_b32_e32 v5, 16, v5
	v_cvt_pk_bf16_f32 v43, v43, v45
	v_cvt_pk_bf16_f32 v42, v42, v44
	v_mov_b32_e32 v26, v23
	v_mov_b32_e32 v10, v7
	v_add3_u32 v18, v40, v18, s68
	v_lshrrev_b32_e32 v4, 16, v4
	v_and_or_b32 v41, v14, s69, v5
	v_mov_b32_e32 v34, v31
	v_pk_mul_f32 v[22:23], v[26:27], v[80:81]
	v_pk_mul_f32 v[6:7], v[10:11], v[76:77]
	v_and_or_b32 v40, v18, s69, v4
	v_pk_mul_f32 v[4:5], v[34:35], v[2:3]
	v_mul_f32_e32 v14, v38, v19
	v_mul_f32_e32 v15, v39, v15
	v_bfe_u32 v10, v7, 16, 1
	v_bfe_u32 v18, v23, 16, 1
	v_add3_u32 v18, v23, v18, s68
	v_add3_u32 v7, v7, v10, s68
	v_bfe_u32 v11, v5, 16, 1
	v_bfe_u32 v23, v15, 16, 1
	v_add3_u32 v15, v15, v23, s68
	v_add3_u32 v5, v5, v11, s68
	v_lshrrev_b32_e32 v5, 16, v5
	v_lshrrev_b32_e32 v11, 16, v15
	v_and_or_b32 v7, v7, s69, v11
	v_cvt_pk_bf16_f32 v6, v14, v6
	v_and_or_b32 v5, v18, s69, v5
	v_cvt_pk_bf16_f32 v4, v4, v22
	global_store_dwordx4 v[86:87], v[4:7], off offset:2144
	s_nop 1
	v_mul_f32_e32 v6, v80, v24
	s_nop 1
	v_mul_f32_e32 v7, v81, v28
	v_mul_f32_e32 v14, v76, v8
	v_mul_f32_e32 v15, v77, v12
	v_mul_f32_e32 v4, v2, v32
	v_mul_f32_e32 v5, v3, v36
	v_mul_f32_e32 v10, v38, v20
	v_mul_f32_e32 v11, v39, v16
	v_bfe_u32 v8, v15, 16, 1
	v_bfe_u32 v12, v14, 16, 1
	v_bfe_u32 v16, v7, 16, 1
	v_bfe_u32 v18, v6, 16, 1
	v_add3_u32 v18, v6, v18, s68
	v_add3_u32 v16, v7, v16, s68
	v_add3_u32 v6, v14, v12, s68
	v_add3_u32 v7, v15, v8, s68
	v_bfe_u32 v8, v4, 16, 1
	v_bfe_u32 v12, v5, 16, 1
	v_bfe_u32 v14, v10, 16, 1
	v_bfe_u32 v15, v11, 16, 1
	v_add3_u32 v11, v11, v15, s68
	v_add3_u32 v10, v10, v14, s68
	v_add3_u32 v5, v5, v12, s68
	v_add3_u32 v4, v4, v8, s68
	v_lshrrev_b32_e32 v4, 16, v4
	v_lshrrev_b32_e32 v5, 16, v5
	v_lshrrev_b32_e32 v8, 16, v10
	v_lshrrev_b32_e32 v10, 16, v11
	v_mov_b32_e32 v36, v33
	v_and_or_b32 v7, v7, s69, v10
	v_and_or_b32 v6, v6, s69, v8
	v_and_or_b32 v5, v16, s69, v5
	v_and_or_b32 v4, v18, s69, v4
	v_pk_mul_f32 v[2:3], v[36:37], v[2:3]
	v_mov_b32_e32 v28, v25
	global_store_dwordx4 v[88:89], v[4:7], off offset:96
	v_mov_b32_e32 v8, v21
	v_mov_b32_e32 v12, v17
	v_pk_mul_f32 v[4:5], v[28:29], v[80:81]
	v_and_b32_sdwa v6, v3, v107 dst_sel:DWORD dst_unused:UNUSED_PAD src0_sel:WORD_1 src1_sel:DWORD
	v_and_b32_sdwa v7, v2, v107 dst_sel:DWORD dst_unused:UNUSED_PAD src0_sel:WORD_1 src1_sel:DWORD
	v_add3_u32 v2, v2, v7, s68
	v_add3_u32 v3, v3, v6, s68
	v_and_b32_sdwa v6, v5, v107 dst_sel:DWORD dst_unused:UNUSED_PAD src0_sel:WORD_1 src1_sel:DWORD
	v_and_b32_sdwa v7, v4, v107 dst_sel:DWORD dst_unused:UNUSED_PAD src0_sel:WORD_1 src1_sel:DWORD
	v_add3_u32 v5, v5, v6, s68
	v_add3_u32 v4, v4, v7, s68
	v_and_b32_e32 v5, 0xffff0000, v5
	v_and_b32_e32 v4, 0xffff0000, v4
	v_or_b32_sdwa v3, v5, v3 dst_sel:DWORD dst_unused:UNUSED_PAD src0_sel:DWORD src1_sel:WORD_1
	v_or_b32_sdwa v2, v4, v2 dst_sel:DWORD dst_unused:UNUSED_PAD src0_sel:DWORD src1_sel:WORD_1
	v_mov_b32_e32 v4, v38
	v_mov_b32_e32 v5, v76
	v_pk_mul_f32 v[4:5], v[8:9], v[4:5]
	v_mov_b32_e32 v76, v39
	v_and_b32_sdwa v6, v5, v107 dst_sel:DWORD dst_unused:UNUSED_PAD src0_sel:WORD_1 src1_sel:DWORD
	v_and_b32_sdwa v7, v4, v107 dst_sel:DWORD dst_unused:UNUSED_PAD src0_sel:WORD_1 src1_sel:DWORD
	v_add3_u32 v5, v5, v6, s68
	v_add3_u32 v4, v4, v7, s68
	v_pk_mul_f32 v[6:7], v[12:13], v[76:77]
	v_lshrrev_b32_e32 v4, 16, v4
	v_and_b32_sdwa v8, v6, v107 dst_sel:DWORD dst_unused:UNUSED_PAD src0_sel:WORD_1 src1_sel:DWORD
	v_and_or_b32 v4, v5, s69, v4
	v_and_b32_sdwa v5, v7, v107 dst_sel:DWORD dst_unused:UNUSED_PAD src0_sel:WORD_1 src1_sel:DWORD
	v_add3_u32 v6, v6, v8, s68
	v_add3_u32 v5, v7, v5, s68
	v_lshrrev_b32_e32 v6, 16, v6
	v_and_or_b32 v5, v5, s69, v6
	global_store_dwordx4 v[86:87], v[96:99], off offset:64
	global_store_dwordx4 v[86:87], v[40:43], off offset:96

.LBB0_638:
	s_waitcnt vmcnt(15)
	s_waitcnt vmcnt(13)
	v_mul_f32_e32 v40, v74, v46
	v_mul_f32_e32 v41, v75, v58
	s_waitcnt vmcnt(12)
	s_waitcnt vmcnt(11)
	s_waitcnt vmcnt(9)
	v_mul_f32_e32 v80, v98, v42
	v_mul_f32_e32 v81, v99, v50
	v_mul_f32_e32 v88, v78, v62
	v_mul_f32_e32 v89, v79, v70
	s_waitcnt vmcnt(8)
	v_bfe_u32 v62, v41, 16, 1
	v_mul_f32_e32 v108, v96, v54
	v_mul_f32_e32 v109, v97, v66
	v_bfe_u32 v50, v81, 16, 1
	v_bfe_u32 v66, v88, 16, 1
	v_bfe_u32 v70, v89, 16, 1
	v_add3_u32 v41, v41, v62, s68
	v_bfe_u32 v42, v109, 16, 1
	v_bfe_u32 v46, v108, 16, 1
	v_add3_u32 v50, v81, v50, s68
	v_bfe_u32 v58, v40, 16, 1
	v_add3_u32 v70, v89, v70, s68
	v_add3_u32 v66, v88, v66, s68
	v_lshrrev_b32_e32 v41, 16, v41
	v_bfe_u32 v54, v80, 16, 1
	v_add3_u32 v46, v108, v46, s68
	v_add3_u32 v42, v109, v42, s68
	v_add3_u32 v40, v40, v58, s68
	v_lshrrev_b32_e32 v58, 16, v66
	v_lshrrev_b32_e32 v62, 16, v70
	v_and_or_b32 v109, v50, s69, v41
	v_mov_b32_e32 v50, v43
	v_mov_b32_e32 v66, v55
	v_add3_u32 v54, v80, v54, s68
	v_lshrrev_b32_e32 v40, 16, v40
	v_and_or_b32 v111, v42, s69, v62
	v_and_or_b32 v110, v46, s69, v58
	v_mov_b32_e32 v58, v47
	v_pk_mul_f32 v[42:43], v[50:51], v[98:99]
	v_mov_b32_e32 v70, v63
	v_pk_mul_f32 v[50:51], v[66:67], v[96:97]
	v_and_or_b32 v108, v54, s69, v40
	v_pk_mul_f32 v[40:41], v[58:59], v[74:75]
	v_pk_mul_f32 v[46:47], v[70:71], v[78:79]
	v_bfe_u32 v54, v51, 16, 1
	v_bfe_u32 v55, v50, 16, 1
	v_bfe_u32 v58, v43, 16, 1
	v_bfe_u32 v59, v42, 16, 1
	v_add3_u32 v59, v42, v59, s68
	v_add3_u32 v58, v43, v58, s68
	v_add3_u32 v42, v50, v55, s68
	v_add3_u32 v43, v51, v54, s68
	v_bfe_u32 v50, v40, 16, 1
	v_bfe_u32 v51, v41, 16, 1
	v_bfe_u32 v54, v46, 16, 1
	v_bfe_u32 v55, v47, 16, 1
	v_add3_u32 v47, v47, v55, s68
	v_add3_u32 v46, v46, v54, s68
	v_add3_u32 v41, v41, v51, s68
	v_add3_u32 v40, v40, v50, s68
	v_lshrrev_b32_e32 v40, 16, v40
	v_lshrrev_b32_e32 v41, 16, v41
	v_lshrrev_b32_e32 v46, 16, v46
	v_lshrrev_b32_e32 v47, 16, v47
	v_and_or_b32 v43, v43, s69, v47
	v_and_or_b32 v42, v42, s69, v46
	v_and_or_b32 v41, v58, s69, v41
	v_and_or_b32 v40, v59, s69, v40
	global_store_dwordx4 v[86:87], v[40:43], off offset:2048
	s_nop 1
	v_mul_f32_e32 v42, v98, v44
	s_nop 1
	v_mul_f32_e32 v43, v99, v52
	v_mul_f32_e32 v50, v96, v56
	v_mul_f32_e32 v51, v97, v68
	v_mul_f32_e32 v40, v74, v48
	v_mul_f32_e32 v41, v75, v60
	v_mul_f32_e32 v46, v78, v64
	v_mul_f32_e32 v47, v79, v72
	v_bfe_u32 v44, v51, 16, 1
	v_bfe_u32 v48, v50, 16, 1
	v_bfe_u32 v52, v43, 16, 1
	v_bfe_u32 v54, v42, 16, 1
	v_add3_u32 v54, v42, v54, s68
	v_add3_u32 v52, v43, v52, s68
	v_add3_u32 v42, v50, v48, s68
	v_add3_u32 v43, v51, v44, s68
	v_bfe_u32 v44, v40, 16, 1
	v_bfe_u32 v48, v41, 16, 1
	v_bfe_u32 v50, v46, 16, 1
	v_bfe_u32 v51, v47, 16, 1
	v_add3_u32 v47, v47, v51, s68
	v_add3_u32 v46, v46, v50, s68
	v_add3_u32 v41, v41, v48, s68
	v_add3_u32 v40, v40, v44, s68
	v_lshrrev_b32_e32 v40, 16, v40
	v_lshrrev_b32_e32 v41, 16, v41
	v_lshrrev_b32_e32 v44, 16, v46
	v_lshrrev_b32_e32 v46, 16, v47
	v_add_co_u32_e32 v88, vcc, s61, v86
	v_and_or_b32 v43, v43, s69, v46
	v_and_or_b32 v42, v42, s69, v44
	v_and_or_b32 v41, v52, s69, v41
	v_and_or_b32 v40, v54, s69, v40
	v_addc_co_u32_e32 v89, vcc, 0, v87, vcc
	v_mov_b32_e32 v52, v45
	v_mov_b32_e32 v68, v57
	global_store_dwordx4 v[88:89], v[40:43], off
	v_mov_b32_e32 v60, v49
	v_mov_b32_e32 v72, v65
	v_pk_mul_f32 v[42:43], v[52:53], v[98:99]
	v_pk_mul_f32 v[46:47], v[68:69], v[96:97]
	v_pk_mul_f32 v[40:41], v[60:61], v[74:75]
	v_pk_mul_f32 v[44:45], v[72:73], v[78:79]
	v_bfe_u32 v48, v47, 16, 1
	v_bfe_u32 v49, v46, 16, 1
	v_bfe_u32 v50, v43, 16, 1
	v_bfe_u32 v51, v42, 16, 1
	v_add3_u32 v51, v42, v51, s68
	v_add3_u32 v50, v43, v50, s68
	v_add3_u32 v42, v46, v49, s68
	v_add3_u32 v43, v47, v48, s68
	v_bfe_u32 v46, v40, 16, 1
	v_bfe_u32 v47, v41, 16, 1
	v_bfe_u32 v48, v44, 16, 1
	v_bfe_u32 v49, v45, 16, 1
	v_add3_u32 v45, v45, v49, s68
	v_add3_u32 v44, v44, v48, s68
	v_add3_u32 v41, v41, v47, s68
	v_add3_u32 v40, v40, v46, s68
	v_lshrrev_b32_e32 v40, 16, v40
	v_lshrrev_b32_e32 v41, 16, v41
	v_lshrrev_b32_e32 v44, 16, v44
	v_lshrrev_b32_e32 v45, 16, v45
	v_and_or_b32 v43, v43, s69, v45
	v_and_or_b32 v42, v42, s69, v44
	v_and_or_b32 v41, v50, s69, v41
	v_and_or_b32 v40, v51, s69, v40
	global_store_dwordx4 v[88:89], v[40:43], off offset:2048
	s_waitcnt vmcnt(6)
	s_waitcnt vmcnt(4)
	v_mul_f32_e32 v40, v2, v10
	v_mul_f32_e32 v41, v3, v22
	v_mul_f32_e32 v44, v38, v26
	v_mul_f32_e32 v45, v39, v34
	s_waitcnt vmcnt(3)
	v_mul_f32_e32 v42, v76, v6
	v_mul_f32_e32 v43, v77, v14
	v_mul_f32_e32 v46, v4, v18
	v_mul_f32_e32 v47, v5, v30
	v_bfe_u32 v22, v40, 16, 1
	v_bfe_u32 v18, v42, 16, 1
	v_add3_u32 v22, v40, v22, s68
	v_add3_u32 v18, v42, v18, s68
	v_lshrrev_b32_e32 v22, 16, v22
	v_cvt_pk_bf16_f32 v42, v44, v46
	v_cvt_pk_bf16_f32 v41, v41, v43
	v_mov_b32_e32 v14, v7
	v_mov_b32_e32 v30, v19
	v_cvt_pk_bf16_f32 v43, v45, v47
	v_and_or_b32 v40, v18, s69, v22
	v_mov_b32_e32 v22, v11
	v_pk_mul_f32 v[6:7], v[14:15], v[76:77]
	v_mov_b32_e32 v34, v27
	v_pk_mul_f32 v[18:19], v[30:31], v[4:5]
	v_pk_mul_f32 v[10:11], v[22:23], v[2:3]
	v_pk_mul_f32 v[14:15], v[34:35], v[38:39]
	global_store_dwordx4 v[86:87], v[40:43], off offset:32
	global_store_dwordx4 v[86:87], v[108:111], off
	s_and_b64 vcc, exec, s[6:7]
	v_cvt_pk_bf16_f32 v43, v15, v19
	v_cvt_pk_bf16_f32 v42, v14, v18
	v_cvt_pk_bf16_f32 v41, v11, v7
	v_cvt_pk_bf16_f32 v40, v10, v6
	v_mul_f32_e32 v10, v76, v8
	v_mul_f32_e32 v11, v77, v16
	v_mul_f32_e32 v18, v4, v20
	v_mul_f32_e32 v19, v5, v32
	v_mul_f32_e32 v6, v2, v12
	v_mul_f32_e32 v7, v3, v24
	v_bfe_u32 v12, v18, 16, 1
	v_bfe_u32 v16, v11, 16, 1
	v_mul_f32_e32 v14, v38, v28
	v_mul_f32_e32 v15, v39, v36
	v_bfe_u32 v8, v19, 16, 1
	v_bfe_u32 v20, v10, 16, 1
	v_add3_u32 v11, v11, v16, s68
	v_add3_u32 v12, v18, v12, s68
	v_bfe_u32 v16, v6, 16, 1
	v_bfe_u32 v18, v7, 16, 1
	v_add3_u32 v10, v10, v20, s68
	v_add3_u32 v8, v19, v8, s68
	v_bfe_u32 v19, v14, 16, 1
	v_bfe_u32 v20, v15, 16, 1
	v_add3_u32 v7, v7, v18, s68
	v_add3_u32 v6, v6, v16, s68
	v_add3_u32 v15, v15, v20, s68
	v_add3_u32 v14, v14, v19, s68
	v_lshrrev_b32_e32 v6, 16, v6
	v_lshrrev_b32_e32 v7, 16, v7
	v_mov_b32_e32 v16, v9
	v_mov_b32_e32 v32, v21
	global_store_dwordx4 v[86:87], v[40:43], off offset:2080
	v_lshrrev_b32_e32 v14, 16, v14
	v_lshrrev_b32_e32 v15, 16, v15
	v_and_or_b32 v41, v11, s69, v7
	v_and_or_b32 v40, v10, s69, v6
	v_mov_b32_e32 v24, v13
	v_pk_mul_f32 v[6:7], v[16:17], v[76:77]
	v_mov_b32_e32 v36, v29
	v_pk_mul_f32 v[4:5], v[32:33], v[4:5]
	v_and_or_b32 v43, v8, s69, v15
	v_and_or_b32 v42, v12, s69, v14
	v_pk_mul_f32 v[2:3], v[24:25], v[2:3]
	v_pk_mul_f32 v[8:9], v[36:37], v[38:39]
	v_cvt_pk_bf16_f32 v5, v9, v5
	v_cvt_pk_bf16_f32 v4, v8, v4
	v_cvt_pk_bf16_f32 v3, v3, v7
	v_cvt_pk_bf16_f32 v2, v2, v6
	global_store_dwordx4 v[88:89], v[2:5], off offset:2080
	global_store_dwordx4 v[88:89], v[40:43], off offset:32
	v_mov_b32_e32 v74, 1.0
	v_or_b32_e32 v2, 32, v90
	v_mad_i64_i32 v[2:3], s[10:11], v2, s76, v[92:93]
	v_or_b32_e32 v4, 33, v90
	v_mad_i64_i32 v[4:5], s[10:11], v4, s76, v[92:93]
	global_load_dwordx4 v[46:49], v[2:3], off nt
	global_load_dwordx4 v[42:45], v[4:5], off nt
	v_or_b32_e32 v2, 34, v90
	v_mad_i64_i32 v[2:3], s[10:11], v2, s76, v[92:93]
	v_or_b32_e32 v4, 35, v90
	v_mad_i64_i32 v[4:5], s[10:11], v4, s76, v[92:93]
	global_load_dwordx4 v[58:61], v[2:3], off nt
	global_load_dwordx4 v[50:53], v[4:5], off nt
	v_or_b32_e32 v2, 36, v90
	v_mad_i64_i32 v[2:3], s[10:11], v2, s76, v[92:93]
	v_or_b32_e32 v4, 37, v90
	v_mad_i64_i32 v[4:5], s[10:11], v4, s76, v[92:93]
	global_load_dwordx4 v[62:65], v[2:3], off nt
	global_load_dwordx4 v[54:57], v[4:5], off nt
	v_or_b32_e32 v2, 38, v90
	v_mad_i64_i32 v[2:3], s[10:11], v2, s76, v[92:93]
	v_or_b32_e32 v4, 39, v90
	v_mad_i64_i32 v[4:5], s[10:11], v4, s76, v[92:93]
	global_load_dwordx4 v[70:73], v[2:3], off nt
	global_load_dwordx4 v[66:69], v[4:5], off nt
	v_mov_b32_e32 v2, 1.0
	v_mov_b32_e32 v98, 1.0
	v_mov_b32_e32 v75, 1.0
	v_mov_b32_e32 v99, 1.0
	v_mov_b32_e32 v78, 1.0
	v_mov_b32_e32 v96, 1.0
	v_mov_b32_e32 v79, 1.0
	v_mov_b32_e32 v97, 1.0
	s_cbranch_vccnz .LBB0_640
	global_load_dwordx4 v[74:77], v[94:95], off offset:128
	global_load_dwordx4 v[78:81], v[94:95], off offset:144
	s_waitcnt vmcnt(1)
	v_mov_b32_e32 v98, v75
	v_mov_b32_e32 v75, v76
	v_mov_b32_e32 v99, v77
	s_waitcnt vmcnt(0)
	v_mov_b32_e32 v96, v79
	v_mov_b32_e32 v79, v80
	v_mov_b32_e32 v97, v81

.LBB0_642:
	s_waitcnt vmcnt(14)
	s_waitcnt vmcnt(12)
	s_waitcnt vmcnt(11)
	s_waitcnt vmcnt(9)
	v_mul_f32_e32 v32, v98, v42
	v_mul_f32_e32 v33, v99, v50
	v_mul_f32_e32 v90, v78, v62
	v_mul_f32_e32 v91, v79, v70
	s_waitcnt vmcnt(8)
	v_mul_f32_e32 v4, v74, v46
	v_mul_f32_e32 v5, v75, v58
	v_mul_f32_e32 v92, v96, v54
	v_mul_f32_e32 v93, v97, v66
	v_bfe_u32 v50, v33, 16, 1
	v_bfe_u32 v54, v32, 16, 1
	v_add3_u32 v32, v32, v54, s68
	v_add3_u32 v33, v33, v50, s68
	v_bfe_u32 v50, v4, 16, 1
	v_bfe_u32 v54, v5, 16, 1
	v_bfe_u32 v62, v91, 16, 1
	v_add3_u32 v5, v5, v54, s68
	v_add3_u32 v4, v4, v50, s68
	v_bfe_u32 v42, v93, 16, 1
	v_add3_u32 v62, v91, v62, s68
	v_lshrrev_b32_e32 v4, 16, v4
	v_lshrrev_b32_e32 v5, 16, v5
	v_cvt_pk_bf16_f32 v92, v90, v92
	v_mov_b32_e32 v50, v43
	v_mov_b32_e32 v66, v55
	v_add3_u32 v42, v93, v42, s68
	v_lshrrev_b32_e32 v54, 16, v62
	v_and_or_b32 v91, v33, s69, v5
	v_and_or_b32 v90, v32, s69, v4
	v_mov_b32_e32 v58, v47
	v_pk_mul_f32 v[32:33], v[50:51], v[98:99]
	v_mov_b32_e32 v70, v63
	v_pk_mul_f32 v[46:47], v[66:67], v[96:97]
	v_and_or_b32 v93, v42, s69, v54
	v_pk_mul_f32 v[4:5], v[58:59], v[74:75]
	v_pk_mul_f32 v[42:43], v[70:71], v[78:79]
	global_store_dwordx4 v[86:87], v[90:93], off offset:64
	s_mov_b64 s[50:51], 0
	s_nop 0
	v_cvt_pk_bf16_f32 v93, v43, v47
	v_cvt_pk_bf16_f32 v92, v42, v46
	v_cvt_pk_bf16_f32 v91, v5, v33
	v_cvt_pk_bf16_f32 v90, v4, v32
	v_mul_f32_e32 v32, v98, v44
	v_mul_f32_e32 v33, v99, v52
	v_mul_f32_e32 v46, v96, v56
	v_mul_f32_e32 v47, v97, v68
	v_mul_f32_e32 v4, v74, v48
	v_mul_f32_e32 v5, v75, v60
	v_mul_f32_e32 v42, v78, v64
	v_mul_f32_e32 v43, v79, v72
	v_bfe_u32 v44, v47, 16, 1
	v_add3_u32 v44, v47, v44, s68
	v_bfe_u32 v51, v43, 16, 1
	v_add3_u32 v43, v43, v51, s68
	v_lshrrev_b32_e32 v43, 16, v43
	v_mov_b32_e32 v52, v45
	v_mov_b32_e32 v68, v57
	global_store_dwordx4 v[86:87], v[90:93], off offset:2112
	v_mov_b32_e32 v60, v49
	s_nop 1
	v_and_or_b32 v93, v44, s69, v43
	v_cvt_pk_bf16_f32 v91, v5, v33
	v_cvt_pk_bf16_f32 v90, v4, v32
	v_pk_mul_f32 v[32:33], v[52:53], v[98:99]
	v_mov_b32_e32 v72, v65
	v_pk_mul_f32 v[44:45], v[68:69], v[96:97]
	v_cvt_pk_bf16_f32 v92, v42, v46
	v_pk_mul_f32 v[4:5], v[60:61], v[74:75]
	v_pk_mul_f32 v[42:43], v[72:73], v[78:79]
	v_cvt_pk_bf16_f32 v45, v43, v45
	v_cvt_pk_bf16_f32 v44, v42, v44
	v_cvt_pk_bf16_f32 v43, v5, v33
	v_cvt_pk_bf16_f32 v42, v4, v32
	s_waitcnt vmcnt(8)
	s_waitcnt vmcnt(6)
	global_store_dwordx4 v[88:89], v[42:45], off offset:2112
	v_mul_f32_e32 v32, v80, v22
	v_mul_f32_e32 v33, v81, v34
	s_waitcnt vmcnt(6)
	s_waitcnt vmcnt(4)
	v_mul_f32_e32 v42, v30, v18
	v_mul_f32_e32 v43, v31, v10
	s_waitcnt vmcnt(3)
	v_mul_f32_e32 v4, v2, v26
	v_mul_f32_e32 v5, v3, v38
	v_mul_f32_e32 v44, v76, v14
	v_mul_f32_e32 v45, v77, v6
	v_bfe_u32 v18, v32, 16, 1
	v_add3_u32 v18, v32, v18, s68
	v_bfe_u32 v22, v4, 16, 1
	v_add3_u32 v4, v4, v22, s68
	v_cvt_pk_bf16_f32 v45, v43, v45
	v_mov_b32_e32 v34, v23
	v_lshrrev_b32_e32 v4, 16, v4
	v_cvt_pk_bf16_f32 v44, v42, v44
	v_mov_b32_e32 v38, v27
	v_pk_mul_f32 v[22:23], v[34:35], v[80:81]
	v_mul_f32_e32 v6, v76, v15
	v_mul_f32_e32 v7, v77, v7
	v_cvt_pk_bf16_f32 v43, v5, v33
	v_and_or_b32 v42, v18, s69, v4
	v_pk_mul_f32 v[4:5], v[38:39], v[2:3]
	v_mul_f32_e32 v10, v30, v19
	v_mul_f32_e32 v11, v31, v11
	v_cvt_pk_bf16_f32 v7, v11, v7
	v_cvt_pk_bf16_f32 v6, v10, v6
	v_cvt_pk_bf16_f32 v5, v5, v23
	v_cvt_pk_bf16_f32 v4, v4, v22
	global_store_dwordx4 v[86:87], v[4:7], off offset:2144
	s_nop 1
	v_mul_f32_e32 v6, v80, v24
	s_nop 1
	v_mul_f32_e32 v7, v81, v36
	v_mul_f32_e32 v14, v76, v16
	v_mul_f32_e32 v15, v77, v8
	v_mul_f32_e32 v4, v2, v28
	v_mul_f32_e32 v5, v3, v40
	v_mul_f32_e32 v10, v30, v20
	v_mul_f32_e32 v11, v31, v12
	v_bfe_u32 v8, v15, 16, 1
	v_bfe_u32 v12, v14, 16, 1
	v_bfe_u32 v16, v7, 16, 1
	v_bfe_u32 v18, v6, 16, 1
	v_add3_u32 v18, v6, v18, s68
	v_add3_u32 v16, v7, v16, s68
	v_add3_u32 v6, v14, v12, s68
	v_add3_u32 v7, v15, v8, s68
	v_bfe_u32 v8, v4, 16, 1
	v_bfe_u32 v12, v5, 16, 1
	v_bfe_u32 v14, v10, 16, 1
	v_bfe_u32 v15, v11, 16, 1
	v_add3_u32 v11, v11, v15, s68
	v_add3_u32 v10, v10, v14, s68
	v_add3_u32 v5, v5, v12, s68
	v_add3_u32 v4, v4, v8, s68
	v_lshrrev_b32_e32 v4, 16, v4
	v_lshrrev_b32_e32 v5, 16, v5
	v_lshrrev_b32_e32 v8, 16, v10
	v_lshrrev_b32_e32 v10, 16, v11
	v_mov_b32_e32 v40, v29
	v_and_or_b32 v7, v7, s69, v10
	v_and_or_b32 v6, v6, s69, v8
	v_and_or_b32 v5, v16, s69, v5
	v_and_or_b32 v4, v18, s69, v4
	v_pk_mul_f32 v[2:3], v[40:41], v[2:3]
	v_mov_b32_e32 v36, v25
	global_store_dwordx4 v[88:89], v[4:7], off offset:96
	v_mov_b32_e32 v16, v21
	v_mov_b32_e32 v8, v13
	v_pk_mul_f32 v[4:5], v[36:37], v[80:81]
	v_and_b32_sdwa v6, v3, v107 dst_sel:DWORD dst_unused:UNUSED_PAD src0_sel:WORD_1 src1_sel:DWORD
	v_and_b32_sdwa v7, v2, v107 dst_sel:DWORD dst_unused:UNUSED_PAD src0_sel:WORD_1 src1_sel:DWORD
	v_add3_u32 v2, v2, v7, s68
	v_add3_u32 v3, v3, v6, s68
	v_and_b32_sdwa v6, v5, v107 dst_sel:DWORD dst_unused:UNUSED_PAD src0_sel:WORD_1 src1_sel:DWORD
	v_and_b32_sdwa v7, v4, v107 dst_sel:DWORD dst_unused:UNUSED_PAD src0_sel:WORD_1 src1_sel:DWORD
	v_add3_u32 v5, v5, v6, s68
	v_add3_u32 v4, v4, v7, s68
	v_and_b32_e32 v5, 0xffff0000, v5
	v_and_b32_e32 v4, 0xffff0000, v4
	v_or_b32_sdwa v3, v5, v3 dst_sel:DWORD dst_unused:UNUSED_PAD src0_sel:DWORD src1_sel:WORD_1
	v_or_b32_sdwa v2, v4, v2 dst_sel:DWORD dst_unused:UNUSED_PAD src0_sel:DWORD src1_sel:WORD_1
	v_mov_b32_e32 v4, v30
	v_mov_b32_e32 v5, v76
	v_pk_mul_f32 v[4:5], v[16:17], v[4:5]
	v_mov_b32_e32 v76, v31
	v_and_b32_sdwa v6, v5, v107 dst_sel:DWORD dst_unused:UNUSED_PAD src0_sel:WORD_1 src1_sel:DWORD
	v_and_b32_sdwa v7, v4, v107 dst_sel:DWORD dst_unused:UNUSED_PAD src0_sel:WORD_1 src1_sel:DWORD
	v_add3_u32 v5, v5, v6, s68
	v_add3_u32 v4, v4, v7, s68
	v_pk_mul_f32 v[6:7], v[8:9], v[76:77]
	v_lshrrev_b32_e32 v4, 16, v4
	v_and_b32_sdwa v8, v6, v107 dst_sel:DWORD dst_unused:UNUSED_PAD src0_sel:WORD_1 src1_sel:DWORD
	v_and_or_b32 v4, v5, s69, v4
	v_and_b32_sdwa v5, v7, v107 dst_sel:DWORD dst_unused:UNUSED_PAD src0_sel:WORD_1 src1_sel:DWORD
	v_add3_u32 v6, v6, v8, s68
	v_add3_u32 v5, v7, v5, s68
	v_lshrrev_b32_e32 v6, 16, v6
	v_and_or_b32 v5, v5, s69, v6
	global_store_dwordx4 v[88:89], v[90:93], off offset:64
	global_store_dwordx4 v[86:87], v[42:45], off offset:96
